# scan chunk fully unrolled (16 steps): no loop/address-increment overhead, no prefetch after the last step
# speedup vs baseline: 1.0112x; 1.0112x over previous
; #define LAS __attribute__((address_space(3)))
; __device__ __forceinline__ float red4(float x) { x = DPP_ADD(x, 0xB1); x = DPP_ADD(x, 0x4E); return x; }
; __device__ __forceinline__ void phase_scan(const ScanArgs A, LAS unsigned char* lds) {
;     ...
;         for (int c = 0; c < NCH; ++c) {
;             if (consumer) {
;                 const LAS float* in = INc + (c & 1) * 6144;
;                 LAS float* yb = YBc + (c & 1) * 1024;
; #pragma unroll 2
;                 for (int t = 0; t < 16; ++t) {
;                     const LAS float* q = in + t * 64 + kq * 16;
;                     f32x4 Wv[4], KDv[4], Bv[4], ANv[4], Rv[4];
; #pragma unroll
;                     for (int j = 0; j < 4; ++j) { Wv[j] = *(const LAS f32x4*)(q + 4 * j); KDv[j] = *(const LAS f32x4*)(q + 1024 + 4 * j); Bv[j] = *(const LAS f32x4*)(q + 2048 + 4 * j);
;                                                   ANv[j] = *(const LAS f32x4*)(q + 3072 + 4 * j); Rv[j] = *(const LAS f32x4*)(q + 4096 + 4 * j); }
;                     const f32x2 v2 = *(const LAS f32x2*)(in + 5120 + t * 64 + half * 32 + rb * 2);
;     ...
;                     float sa[2], y[2];
; #pragma unroll
;                     for (int i = 0; i < 2; ++i) { f32x2 a0 = {0.f, 0.f}, a1 = {0.f, 0.f};
; #pragma unroll
;                         for (int p = 0; p < 8; p += 2) { a0 += S2[i][p] * PAIR(ANv, p); a1 += S2[i][p + 1] * PAIR(ANv, p + 1); }
;                         a0 += a1; sa[i] = red4(a0[0] + a0[1]); }
; #pragma unroll
;                     for (int i = 0; i < 2; ++i) { f32x2 y0 = {0.f, 0.f}, y1 = {0.f, 0.f}; const f32x2 sai = {sa[i], sa[i]}, vi = {v2[i], v2[i]};
; #pragma unroll
;                         for (int p = 0; p < 8; p += 2) {
;                             const f32x2 n0 = S2[i][p] * PAIR(Wv, p) + sai * PAIR(Bv, p) + vi * PAIR(KDv, p);
;                             const f32x2 n1 = S2[i][p + 1] * PAIR(Wv, p + 1) + sai * PAIR(Bv, p + 1) + vi * PAIR(KDv, p + 1);
;                             S2[i][p] = n0; S2[i][p + 1] = n1; y0 += n0 * PAIR(Rv, p); y1 += n1 * PAIR(Rv, p + 1); }
;                         y0 += y1; y[i] = red4(y0[0] + y0[1]); }
.LBB0_180:
	s_and_b64 vcc, exec, s[34:35]
	s_cbranch_vccz .LBB0_161
	v_cndmask_b32_e64 v48, 0, 1, s[94:95]
	v_lshl_add_u32 v75, v48, 12, v129
	v_mul_lo_u32 v48, v48, s83
	v_add_u32_e32 v75, 0x18000, v75
	v_add_u32_e32 v96, v130, v48
	v_add_u32_e32 v171, v131, v48
	s_mov_b32 s82, 0
	ds_read_b128 v[32:35], v171 offset:12288
	ds_read_b128 v[36:39], v171 offset:12304
	ds_read_b128 v[40:43], v171 offset:12320
	ds_read_b128 v[44:47], v171 offset:12336
	ds_read_b128 v[142:145], v171 offset:8192
	ds_read_b128 v[48:51], v171 offset:0
	ds_read_b128 v[172:175], v171 offset:4096
	ds_read_b128 v[146:149], v171 offset:8208
	ds_read_b128 v[52:55], v171 offset:16
	ds_read_b128 v[176:179], v171 offset:4112
	ds_read_b128 v[150:153], v171 offset:8224
	ds_read_b128 v[56:59], v171 offset:32
	ds_read_b128 v[180:183], v171 offset:4128
	ds_read_b128 v[154:157], v171 offset:8240
	ds_read_b128 v[60:63], v171 offset:48
	ds_read_b128 v[184:187], v171 offset:4144
	ds_read_b64 v[188:189], v96 offset:0
	ds_read_b128 v[200:203], v171 offset:16384
	ds_read_b128 v[204:207], v171 offset:16400
	ds_read_b128 v[208:211], v171 offset:16416
	ds_read_b128 v[212:215], v171 offset:16432
	s_waitcnt lgkmcnt(0)
	s_waitcnt lgkmcnt(15)
	v_pk_fma_f32 v[160:161], v[84:85], v[32:33], 0 op_sel_hi:[1,1,0]
	v_pk_fma_f32 v[162:163], v[88:89], v[34:35], 0 op_sel_hi:[1,1,0]
	v_pk_fma_f32 v[164:165], v[100:101], v[32:33], 0 op_sel_hi:[1,1,0]
	v_pk_fma_f32 v[166:167], v[104:105], v[34:35], 0 op_sel_hi:[1,1,0]
	v_pk_fma_f32 v[160:161], v[86:87], v[36:37], v[160:161]
	v_pk_fma_f32 v[162:163], v[92:93], v[38:39], v[162:163]
	v_pk_fma_f32 v[164:165], v[106:107], v[36:37], v[164:165]
	v_pk_fma_f32 v[166:167], v[108:109], v[38:39], v[166:167]
	v_pk_fma_f32 v[160:161], v[90:91], v[40:41], v[160:161]
	v_pk_fma_f32 v[162:163], v[98:99], v[42:43], v[162:163]
	v_pk_fma_f32 v[164:165], v[110:111], v[40:41], v[164:165]
	v_pk_fma_f32 v[166:167], v[112:113], v[42:43], v[166:167]
	v_pk_fma_f32 v[160:161], v[94:95], v[44:45], v[160:161]
	v_pk_fma_f32 v[162:163], v[102:103], v[46:47], v[162:163]
	v_pk_fma_f32 v[164:165], v[114:115], v[44:45], v[164:165]
	v_pk_fma_f32 v[166:167], v[116:117], v[46:47], v[166:167]
	ds_read_b128 v[32:35], v171 offset:12544
	ds_read_b128 v[36:39], v171 offset:12560
	ds_read_b128 v[40:43], v171 offset:12576
	ds_read_b128 v[44:47], v171 offset:12592
	v_pk_add_f32 v[160:161], v[162:163], v[160:161]
	v_pk_add_f32 v[164:165], v[166:167], v[164:165]
	v_add_f32_e32 v168, v160, v161
	v_add_f32_e32 v169, v164, v165
	s_nop 0
	v_add_f32_dpp v168, v168, v168 quad_perm:[1,0,3,2] row_mask:0xf bank_mask:0xf bound_ctrl:1
	v_add_f32_dpp v169, v169, v169 quad_perm:[1,0,3,2] row_mask:0xf bank_mask:0xf bound_ctrl:1
	s_nop 0
	v_add_f32_dpp v190, v168, v168 quad_perm:[2,3,0,1] row_mask:0xf bank_mask:0xf bound_ctrl:1
	v_add_f32_dpp v192, v169, v169 quad_perm:[2,3,0,1] row_mask:0xf bank_mask:0xf bound_ctrl:1
	s_waitcnt lgkmcnt(9)
	v_pk_mul_f32 v[216:217], v[142:143], v[190:191] op_sel_hi:[1,0]
	v_pk_mul_f32 v[218:219], v[144:145], v[190:191] op_sel_hi:[1,0]
	v_pk_mul_f32 v[232:233], v[142:143], v[192:193] op_sel_hi:[1,0]
	v_pk_mul_f32 v[234:235], v[144:145], v[192:193] op_sel_hi:[1,0]
	v_pk_fma_f32 v[216:217], v[84:85], v[48:49], v[216:217]
	v_pk_fma_f32 v[218:219], v[88:89], v[50:51], v[218:219]
	v_pk_fma_f32 v[232:233], v[100:101], v[48:49], v[232:233]
	v_pk_fma_f32 v[234:235], v[104:105], v[50:51], v[234:235]
	v_pk_fma_f32 v[84:85], v[172:173], v[188:189], v[216:217] op_sel_hi:[1,0,1]
	v_pk_fma_f32 v[88:89], v[174:175], v[188:189], v[218:219] op_sel_hi:[1,0,1]
	v_pk_fma_f32 v[100:101], v[172:173], v[188:189], v[232:233] op_sel:[0,1,0]
	v_pk_fma_f32 v[104:105], v[174:175], v[188:189], v[234:235] op_sel:[0,1,0]
	ds_read_b128 v[142:145], v171 offset:8448
	ds_read_b128 v[48:51], v171 offset:256
	ds_read_b128 v[172:175], v171 offset:4352
	v_pk_mul_f32 v[220:221], v[146:147], v[190:191] op_sel_hi:[1,0]
	v_pk_mul_f32 v[222:223], v[148:149], v[190:191] op_sel_hi:[1,0]
	v_pk_mul_f32 v[236:237], v[146:147], v[192:193] op_sel_hi:[1,0]
	v_pk_mul_f32 v[238:239], v[148:149], v[192:193] op_sel_hi:[1,0]
	v_pk_fma_f32 v[220:221], v[86:87], v[52:53], v[220:221]
	v_pk_fma_f32 v[222:223], v[92:93], v[54:55], v[222:223]
	v_pk_fma_f32 v[236:237], v[106:107], v[52:53], v[236:237]
	v_pk_fma_f32 v[238:239], v[108:109], v[54:55], v[238:239]
	v_pk_fma_f32 v[86:87], v[176:177], v[188:189], v[220:221] op_sel_hi:[1,0,1]
	v_pk_fma_f32 v[92:93], v[178:179], v[188:189], v[222:223] op_sel_hi:[1,0,1]
	v_pk_fma_f32 v[106:107], v[176:177], v[188:189], v[236:237] op_sel:[0,1,0]
	v_pk_fma_f32 v[108:109], v[178:179], v[188:189], v[238:239] op_sel:[0,1,0]
	ds_read_b128 v[146:149], v171 offset:8464
	ds_read_b128 v[52:55], v171 offset:272
	ds_read_b128 v[176:179], v171 offset:4368
	v_pk_mul_f32 v[224:225], v[150:151], v[190:191] op_sel_hi:[1,0]
	v_pk_mul_f32 v[226:227], v[152:153], v[190:191] op_sel_hi:[1,0]
	v_pk_mul_f32 v[240:241], v[150:151], v[192:193] op_sel_hi:[1,0]
	v_pk_mul_f32 v[242:243], v[152:153], v[192:193] op_sel_hi:[1,0]
	v_pk_fma_f32 v[224:225], v[90:91], v[56:57], v[224:225]
	v_pk_fma_f32 v[226:227], v[98:99], v[58:59], v[226:227]
	v_pk_fma_f32 v[240:241], v[110:111], v[56:57], v[240:241]
	v_pk_fma_f32 v[242:243], v[112:113], v[58:59], v[242:243]
	v_pk_fma_f32 v[90:91], v[180:181], v[188:189], v[224:225] op_sel_hi:[1,0,1]
	v_pk_fma_f32 v[98:99], v[182:183], v[188:189], v[226:227] op_sel_hi:[1,0,1]
	v_pk_fma_f32 v[110:111], v[180:181], v[188:189], v[240:241] op_sel:[0,1,0]
	v_pk_fma_f32 v[112:113], v[182:183], v[188:189], v[242:243] op_sel:[0,1,0]
	ds_read_b128 v[150:153], v171 offset:8480
	ds_read_b128 v[56:59], v171 offset:288
	ds_read_b128 v[180:183], v171 offset:4384
	v_pk_mul_f32 v[228:229], v[154:155], v[190:191] op_sel_hi:[1,0]
	v_pk_mul_f32 v[230:231], v[156:157], v[190:191] op_sel_hi:[1,0]
	v_pk_mul_f32 v[244:245], v[154:155], v[192:193] op_sel_hi:[1,0]
	v_pk_mul_f32 v[246:247], v[156:157], v[192:193] op_sel_hi:[1,0]
	v_pk_fma_f32 v[228:229], v[94:95], v[60:61], v[228:229]
	v_pk_fma_f32 v[230:231], v[102:103], v[62:63], v[230:231]
	v_pk_fma_f32 v[244:245], v[114:115], v[60:61], v[244:245]
	v_pk_fma_f32 v[246:247], v[116:117], v[62:63], v[246:247]
	v_pk_fma_f32 v[94:95], v[184:185], v[188:189], v[228:229] op_sel_hi:[1,0,1]
	v_pk_fma_f32 v[102:103], v[186:187], v[188:189], v[230:231] op_sel_hi:[1,0,1]
	v_pk_fma_f32 v[114:115], v[184:185], v[188:189], v[244:245] op_sel:[0,1,0]
	v_pk_fma_f32 v[116:117], v[186:187], v[188:189], v[246:247] op_sel:[0,1,0]
	ds_read_b128 v[154:157], v171 offset:8496
	ds_read_b128 v[60:63], v171 offset:304
	ds_read_b128 v[184:187], v171 offset:4400
	ds_read_b64 v[188:189], v96 offset:256
	s_waitcnt lgkmcnt(15)
; #define LAS __attribute__((address_space(3)))
; __device__ __forceinline__ float red4(float x) { x = DPP_ADD(x, 0xB1); x = DPP_ADD(x, 0x4E); return x; }
; __device__ __forceinline__ void phase_scan(const ScanArgs A, LAS unsigned char* lds) {
;     ...
;                 for (int t = 0; t < 16; ++t) {
;                     const LAS float* q = in + t * 64 + kq * 16;
;                     f32x4 Wv[4], KDv[4], Bv[4], ANv[4], Rv[4];
; #pragma unroll
;                     for (int j = 0; j < 4; ++j) { Wv[j] = *(const LAS f32x4*)(q + 4 * j); KDv[j] = *(const LAS f32x4*)(q + 1024 + 4 * j); Bv[j] = *(const LAS f32x4*)(q + 2048 + 4 * j);
;                                                   ANv[j] = *(const LAS f32x4*)(q + 3072 + 4 * j); Rv[j] = *(const LAS f32x4*)(q + 4096 + 4 * j); }
;                     const f32x2 v2 = *(const LAS f32x2*)(in + 5120 + t * 64 + half * 32 + rb * 2);
;     ...
;                     float sa[2], y[2];
; #pragma unroll
;                     for (int i = 0; i < 2; ++i) { f32x2 a0 = {0.f, 0.f}, a1 = {0.f, 0.f};
; #pragma unroll
;                         for (int p = 0; p < 8; p += 2) { a0 += S2[i][p] * PAIR(ANv, p); a1 += S2[i][p + 1] * PAIR(ANv, p + 1); }
;                         a0 += a1; sa[i] = red4(a0[0] + a0[1]); }
; #pragma unroll
;                     for (int i = 0; i < 2; ++i) { f32x2 y0 = {0.f, 0.f}, y1 = {0.f, 0.f}; const f32x2 sai = {sa[i], sa[i]}, vi = {v2[i], v2[i]};
; #pragma unroll
;                         for (int p = 0; p < 8; p += 2) {
;                             const f32x2 n0 = S2[i][p] * PAIR(Wv, p) + sai * PAIR(Bv, p) + vi * PAIR(KDv, p);
;                             const f32x2 n1 = S2[i][p + 1] * PAIR(Wv, p + 1) + sai * PAIR(Bv, p + 1) + vi * PAIR(KDv, p + 1);
;                             S2[i][p] = n0; S2[i][p + 1] = n1; y0 += n0 * PAIR(Rv, p); y1 += n1 * PAIR(Rv, p + 1); }
;                         y0 += y1; y[i] = red4(y0[0] + y0[1]); }
;     ...
;                     if (kq == 0) *(LAS f32x2*)(yb + t * 64 + half * 32 + rb * 2) = (f32x2){y[0], y[1]};
	v_pk_fma_f32 v[248:249], v[200:201], v[84:85], 0 op_sel_hi:[1,1,0]
	v_pk_fma_f32 v[250:251], v[202:203], v[88:89], 0 op_sel_hi:[1,1,0]
	v_pk_fma_f32 v[194:195], v[200:201], v[100:101], 0 op_sel_hi:[1,1,0]
	v_pk_fma_f32 v[158:159], v[202:203], v[104:105], 0 op_sel_hi:[1,1,0]
	v_pk_fma_f32 v[248:249], v[204:205], v[86:87], v[248:249]
	v_pk_fma_f32 v[250:251], v[206:207], v[92:93], v[250:251]
	v_pk_fma_f32 v[194:195], v[204:205], v[106:107], v[194:195]
	v_pk_fma_f32 v[158:159], v[206:207], v[108:109], v[158:159]
	v_pk_fma_f32 v[248:249], v[208:209], v[90:91], v[248:249]
	v_pk_fma_f32 v[250:251], v[210:211], v[98:99], v[250:251]
	v_pk_fma_f32 v[194:195], v[208:209], v[110:111], v[194:195]
	v_pk_fma_f32 v[158:159], v[210:211], v[112:113], v[158:159]
	v_pk_fma_f32 v[248:249], v[212:213], v[94:95], v[248:249]
	v_pk_fma_f32 v[250:251], v[214:215], v[102:103], v[250:251]
	v_pk_fma_f32 v[194:195], v[212:213], v[114:115], v[194:195]
	v_pk_fma_f32 v[158:159], v[214:215], v[116:117], v[158:159]
	ds_read_b128 v[200:203], v171 offset:16640
	ds_read_b128 v[204:207], v171 offset:16656
	ds_read_b128 v[208:211], v171 offset:16672
	ds_read_b128 v[212:215], v171 offset:16688
	v_pk_add_f32 v[248:249], v[250:251], v[248:249]
	v_pk_add_f32 v[194:195], v[158:159], v[194:195]
	v_add_f32_e32 v168, v248, v249
	v_add_f32_e32 v169, v194, v195
	s_nop 0
	v_add_f32_dpp v168, v168, v168 quad_perm:[1,0,3,2] row_mask:0xf bank_mask:0xf bound_ctrl:1
	v_add_f32_dpp v169, v169, v169 quad_perm:[1,0,3,2] row_mask:0xf bank_mask:0xf bound_ctrl:1
	s_nop 0
	v_add_f32_dpp v168, v168, v168 quad_perm:[2,3,0,1] row_mask:0xf bank_mask:0xf bound_ctrl:1
	v_add_f32_dpp v169, v169, v169 quad_perm:[2,3,0,1] row_mask:0xf bank_mask:0xf bound_ctrl:1
	s_and_saveexec_b64 s[34:35], s[8:9]
	ds_write_b64 v75, v[168:169] offset:0
	s_or_b64 exec, exec, s[34:35]
	s_waitcnt lgkmcnt(15)
	v_pk_fma_f32 v[160:161], v[84:85], v[32:33], 0 op_sel_hi:[1,1,0]
	v_pk_fma_f32 v[162:163], v[88:89], v[34:35], 0 op_sel_hi:[1,1,0]
	v_pk_fma_f32 v[164:165], v[100:101], v[32:33], 0 op_sel_hi:[1,1,0]
	v_pk_fma_f32 v[166:167], v[104:105], v[34:35], 0 op_sel_hi:[1,1,0]
	v_pk_fma_f32 v[160:161], v[86:87], v[36:37], v[160:161]
	v_pk_fma_f32 v[162:163], v[92:93], v[38:39], v[162:163]
	v_pk_fma_f32 v[164:165], v[106:107], v[36:37], v[164:165]
	v_pk_fma_f32 v[166:167], v[108:109], v[38:39], v[166:167]
	v_pk_fma_f32 v[160:161], v[90:91], v[40:41], v[160:161]
	v_pk_fma_f32 v[162:163], v[98:99], v[42:43], v[162:163]
	v_pk_fma_f32 v[164:165], v[110:111], v[40:41], v[164:165]
	v_pk_fma_f32 v[166:167], v[112:113], v[42:43], v[166:167]
	v_pk_fma_f32 v[160:161], v[94:95], v[44:45], v[160:161]
	v_pk_fma_f32 v[162:163], v[102:103], v[46:47], v[162:163]
	v_pk_fma_f32 v[164:165], v[114:115], v[44:45], v[164:165]
	v_pk_fma_f32 v[166:167], v[116:117], v[46:47], v[166:167]
	ds_read_b128 v[32:35], v171 offset:12800
	ds_read_b128 v[36:39], v171 offset:12816
	ds_read_b128 v[40:43], v171 offset:12832
	ds_read_b128 v[44:47], v171 offset:12848
	v_pk_add_f32 v[160:161], v[162:163], v[160:161]
	v_pk_add_f32 v[164:165], v[166:167], v[164:165]
	v_add_f32_e32 v168, v160, v161
	v_add_f32_e32 v169, v164, v165
	s_nop 0
	v_add_f32_dpp v168, v168, v168 quad_perm:[1,0,3,2] row_mask:0xf bank_mask:0xf bound_ctrl:1
	v_add_f32_dpp v169, v169, v169 quad_perm:[1,0,3,2] row_mask:0xf bank_mask:0xf bound_ctrl:1
	s_nop 0
	v_add_f32_dpp v190, v168, v168 quad_perm:[2,3,0,1] row_mask:0xf bank_mask:0xf bound_ctrl:1
	v_add_f32_dpp v192, v169, v169 quad_perm:[2,3,0,1] row_mask:0xf bank_mask:0xf bound_ctrl:1
	s_waitcnt lgkmcnt(9)
	v_pk_mul_f32 v[216:217], v[142:143], v[190:191] op_sel_hi:[1,0]
	v_pk_mul_f32 v[218:219], v[144:145], v[190:191] op_sel_hi:[1,0]
	v_pk_mul_f32 v[232:233], v[142:143], v[192:193] op_sel_hi:[1,0]
	v_pk_mul_f32 v[234:235], v[144:145], v[192:193] op_sel_hi:[1,0]
	v_pk_fma_f32 v[216:217], v[84:85], v[48:49], v[216:217]
	v_pk_fma_f32 v[218:219], v[88:89], v[50:51], v[218:219]
	v_pk_fma_f32 v[232:233], v[100:101], v[48:49], v[232:233]
	v_pk_fma_f32 v[234:235], v[104:105], v[50:51], v[234:235]
	v_pk_fma_f32 v[84:85], v[172:173], v[188:189], v[216:217] op_sel_hi:[1,0,1]
	v_pk_fma_f32 v[88:89], v[174:175], v[188:189], v[218:219] op_sel_hi:[1,0,1]
	v_pk_fma_f32 v[100:101], v[172:173], v[188:189], v[232:233] op_sel:[0,1,0]
	v_pk_fma_f32 v[104:105], v[174:175], v[188:189], v[234:235] op_sel:[0,1,0]
	ds_read_b128 v[142:145], v171 offset:8704
	ds_read_b128 v[48:51], v171 offset:512
	ds_read_b128 v[172:175], v171 offset:4608
	v_pk_mul_f32 v[220:221], v[146:147], v[190:191] op_sel_hi:[1,0]
	v_pk_mul_f32 v[222:223], v[148:149], v[190:191] op_sel_hi:[1,0]
	v_pk_mul_f32 v[236:237], v[146:147], v[192:193] op_sel_hi:[1,0]
	v_pk_mul_f32 v[238:239], v[148:149], v[192:193] op_sel_hi:[1,0]
	v_pk_fma_f32 v[220:221], v[86:87], v[52:53], v[220:221]
	v_pk_fma_f32 v[222:223], v[92:93], v[54:55], v[222:223]
	v_pk_fma_f32 v[236:237], v[106:107], v[52:53], v[236:237]
	v_pk_fma_f32 v[238:239], v[108:109], v[54:55], v[238:239]
	v_pk_fma_f32 v[86:87], v[176:177], v[188:189], v[220:221] op_sel_hi:[1,0,1]
	v_pk_fma_f32 v[92:93], v[178:179], v[188:189], v[222:223] op_sel_hi:[1,0,1]
	v_pk_fma_f32 v[106:107], v[176:177], v[188:189], v[236:237] op_sel:[0,1,0]
	v_pk_fma_f32 v[108:109], v[178:179], v[188:189], v[238:239] op_sel:[0,1,0]
	ds_read_b128 v[146:149], v171 offset:8720
	ds_read_b128 v[52:55], v171 offset:528
	ds_read_b128 v[176:179], v171 offset:4624
	v_pk_mul_f32 v[224:225], v[150:151], v[190:191] op_sel_hi:[1,0]
	v_pk_mul_f32 v[226:227], v[152:153], v[190:191] op_sel_hi:[1,0]
	v_pk_mul_f32 v[240:241], v[150:151], v[192:193] op_sel_hi:[1,0]
	v_pk_mul_f32 v[242:243], v[152:153], v[192:193] op_sel_hi:[1,0]
; #define LAS __attribute__((address_space(3)))
; __device__ __forceinline__ float red4(float x) { x = DPP_ADD(x, 0xB1); x = DPP_ADD(x, 0x4E); return x; }
; __device__ __forceinline__ void phase_scan(const ScanArgs A, LAS unsigned char* lds) {
;     ...
;                 for (int t = 0; t < 16; ++t) {
;                     const LAS float* q = in + t * 64 + kq * 16;
;                     f32x4 Wv[4], KDv[4], Bv[4], ANv[4], Rv[4];
; #pragma unroll
;                     for (int j = 0; j < 4; ++j) { Wv[j] = *(const LAS f32x4*)(q + 4 * j); KDv[j] = *(const LAS f32x4*)(q + 1024 + 4 * j); Bv[j] = *(const LAS f32x4*)(q + 2048 + 4 * j);
;                                                   ANv[j] = *(const LAS f32x4*)(q + 3072 + 4 * j); Rv[j] = *(const LAS f32x4*)(q + 4096 + 4 * j); }
;                     const f32x2 v2 = *(const LAS f32x2*)(in + 5120 + t * 64 + half * 32 + rb * 2);
;     ...
;                     float sa[2], y[2];
; #pragma unroll
;                     for (int i = 0; i < 2; ++i) { f32x2 a0 = {0.f, 0.f}, a1 = {0.f, 0.f};
; #pragma unroll
;                         for (int p = 0; p < 8; p += 2) { a0 += S2[i][p] * PAIR(ANv, p); a1 += S2[i][p + 1] * PAIR(ANv, p + 1); }
;                         a0 += a1; sa[i] = red4(a0[0] + a0[1]); }
;     ...
;                     for (int i = 0; i < 2; ++i) { f32x2 y0 = {0.f, 0.f}, y1 = {0.f, 0.f}; const f32x2 sai = {sa[i], sa[i]}, vi = {v2[i], v2[i]};
; #pragma unroll
;                         for (int p = 0; p < 8; p += 2) {
;                             const f32x2 n0 = S2[i][p] * PAIR(Wv, p) + sai * PAIR(Bv, p) + vi * PAIR(KDv, p);
;                             const f32x2 n1 = S2[i][p + 1] * PAIR(Wv, p + 1) + sai * PAIR(Bv, p + 1) + vi * PAIR(KDv, p + 1);
;                             S2[i][p] = n0; S2[i][p + 1] = n1; y0 += n0 * PAIR(Rv, p); y1 += n1 * PAIR(Rv, p + 1); }
;                         y0 += y1; y[i] = red4(y0[0] + y0[1]); }
;     ...
;                     if (kq == 0) *(LAS f32x2*)(yb + t * 64 + half * 32 + rb * 2) = (f32x2){y[0], y[1]};
	v_pk_fma_f32 v[224:225], v[90:91], v[56:57], v[224:225]
	v_pk_fma_f32 v[226:227], v[98:99], v[58:59], v[226:227]
	v_pk_fma_f32 v[240:241], v[110:111], v[56:57], v[240:241]
	v_pk_fma_f32 v[242:243], v[112:113], v[58:59], v[242:243]
	v_pk_fma_f32 v[90:91], v[180:181], v[188:189], v[224:225] op_sel_hi:[1,0,1]
	v_pk_fma_f32 v[98:99], v[182:183], v[188:189], v[226:227] op_sel_hi:[1,0,1]
	v_pk_fma_f32 v[110:111], v[180:181], v[188:189], v[240:241] op_sel:[0,1,0]
	v_pk_fma_f32 v[112:113], v[182:183], v[188:189], v[242:243] op_sel:[0,1,0]
	ds_read_b128 v[150:153], v171 offset:8736
	ds_read_b128 v[56:59], v171 offset:544
	ds_read_b128 v[180:183], v171 offset:4640
	v_pk_mul_f32 v[228:229], v[154:155], v[190:191] op_sel_hi:[1,0]
	v_pk_mul_f32 v[230:231], v[156:157], v[190:191] op_sel_hi:[1,0]
	v_pk_mul_f32 v[244:245], v[154:155], v[192:193] op_sel_hi:[1,0]
	v_pk_mul_f32 v[246:247], v[156:157], v[192:193] op_sel_hi:[1,0]
	v_pk_fma_f32 v[228:229], v[94:95], v[60:61], v[228:229]
	v_pk_fma_f32 v[230:231], v[102:103], v[62:63], v[230:231]
	v_pk_fma_f32 v[244:245], v[114:115], v[60:61], v[244:245]
	v_pk_fma_f32 v[246:247], v[116:117], v[62:63], v[246:247]
	v_pk_fma_f32 v[94:95], v[184:185], v[188:189], v[228:229] op_sel_hi:[1,0,1]
	v_pk_fma_f32 v[102:103], v[186:187], v[188:189], v[230:231] op_sel_hi:[1,0,1]
	v_pk_fma_f32 v[114:115], v[184:185], v[188:189], v[244:245] op_sel:[0,1,0]
	v_pk_fma_f32 v[116:117], v[186:187], v[188:189], v[246:247] op_sel:[0,1,0]
	ds_read_b128 v[154:157], v171 offset:8752
	ds_read_b128 v[60:63], v171 offset:560
	ds_read_b128 v[184:187], v171 offset:4656
	ds_read_b64 v[188:189], v96 offset:512
	s_waitcnt lgkmcnt(15)
	v_pk_fma_f32 v[248:249], v[200:201], v[84:85], 0 op_sel_hi:[1,1,0]
	v_pk_fma_f32 v[250:251], v[202:203], v[88:89], 0 op_sel_hi:[1,1,0]
	v_pk_fma_f32 v[194:195], v[200:201], v[100:101], 0 op_sel_hi:[1,1,0]
	v_pk_fma_f32 v[158:159], v[202:203], v[104:105], 0 op_sel_hi:[1,1,0]
	v_pk_fma_f32 v[248:249], v[204:205], v[86:87], v[248:249]
	v_pk_fma_f32 v[250:251], v[206:207], v[92:93], v[250:251]
	v_pk_fma_f32 v[194:195], v[204:205], v[106:107], v[194:195]
	v_pk_fma_f32 v[158:159], v[206:207], v[108:109], v[158:159]
	v_pk_fma_f32 v[248:249], v[208:209], v[90:91], v[248:249]
	v_pk_fma_f32 v[250:251], v[210:211], v[98:99], v[250:251]
	v_pk_fma_f32 v[194:195], v[208:209], v[110:111], v[194:195]
	v_pk_fma_f32 v[158:159], v[210:211], v[112:113], v[158:159]
	v_pk_fma_f32 v[248:249], v[212:213], v[94:95], v[248:249]
	v_pk_fma_f32 v[250:251], v[214:215], v[102:103], v[250:251]
	v_pk_fma_f32 v[194:195], v[212:213], v[114:115], v[194:195]
	v_pk_fma_f32 v[158:159], v[214:215], v[116:117], v[158:159]
	ds_read_b128 v[200:203], v171 offset:16896
	ds_read_b128 v[204:207], v171 offset:16912
	ds_read_b128 v[208:211], v171 offset:16928
	ds_read_b128 v[212:215], v171 offset:16944
	v_pk_add_f32 v[248:249], v[250:251], v[248:249]
	v_pk_add_f32 v[194:195], v[158:159], v[194:195]
	v_add_f32_e32 v168, v248, v249
	v_add_f32_e32 v169, v194, v195
	s_nop 0
	v_add_f32_dpp v168, v168, v168 quad_perm:[1,0,3,2] row_mask:0xf bank_mask:0xf bound_ctrl:1
	v_add_f32_dpp v169, v169, v169 quad_perm:[1,0,3,2] row_mask:0xf bank_mask:0xf bound_ctrl:1
	s_nop 0
	v_add_f32_dpp v168, v168, v168 quad_perm:[2,3,0,1] row_mask:0xf bank_mask:0xf bound_ctrl:1
	v_add_f32_dpp v169, v169, v169 quad_perm:[2,3,0,1] row_mask:0xf bank_mask:0xf bound_ctrl:1
	s_and_saveexec_b64 s[34:35], s[8:9]
	ds_write_b64 v75, v[168:169] offset:256
	s_or_b64 exec, exec, s[34:35]
	s_waitcnt lgkmcnt(15)
	v_pk_fma_f32 v[160:161], v[84:85], v[32:33], 0 op_sel_hi:[1,1,0]
	v_pk_fma_f32 v[162:163], v[88:89], v[34:35], 0 op_sel_hi:[1,1,0]
	v_pk_fma_f32 v[164:165], v[100:101], v[32:33], 0 op_sel_hi:[1,1,0]
	v_pk_fma_f32 v[166:167], v[104:105], v[34:35], 0 op_sel_hi:[1,1,0]
	v_pk_fma_f32 v[160:161], v[86:87], v[36:37], v[160:161]
	v_pk_fma_f32 v[162:163], v[92:93], v[38:39], v[162:163]
	v_pk_fma_f32 v[164:165], v[106:107], v[36:37], v[164:165]
	v_pk_fma_f32 v[166:167], v[108:109], v[38:39], v[166:167]
	v_pk_fma_f32 v[160:161], v[90:91], v[40:41], v[160:161]
	v_pk_fma_f32 v[162:163], v[98:99], v[42:43], v[162:163]
	v_pk_fma_f32 v[164:165], v[110:111], v[40:41], v[164:165]
	v_pk_fma_f32 v[166:167], v[112:113], v[42:43], v[166:167]
	v_pk_fma_f32 v[160:161], v[94:95], v[44:45], v[160:161]
	v_pk_fma_f32 v[162:163], v[102:103], v[46:47], v[162:163]
	v_pk_fma_f32 v[164:165], v[114:115], v[44:45], v[164:165]
	v_pk_fma_f32 v[166:167], v[116:117], v[46:47], v[166:167]
	ds_read_b128 v[32:35], v171 offset:13056
	ds_read_b128 v[36:39], v171 offset:13072
	ds_read_b128 v[40:43], v171 offset:13088
	ds_read_b128 v[44:47], v171 offset:13104
	v_pk_add_f32 v[160:161], v[162:163], v[160:161]
	v_pk_add_f32 v[164:165], v[166:167], v[164:165]
	v_add_f32_e32 v168, v160, v161
	v_add_f32_e32 v169, v164, v165
	s_nop 0
	v_add_f32_dpp v168, v168, v168 quad_perm:[1,0,3,2] row_mask:0xf bank_mask:0xf bound_ctrl:1
	v_add_f32_dpp v169, v169, v169 quad_perm:[1,0,3,2] row_mask:0xf bank_mask:0xf bound_ctrl:1
	s_nop 0
	v_add_f32_dpp v190, v168, v168 quad_perm:[2,3,0,1] row_mask:0xf bank_mask:0xf bound_ctrl:1
	v_add_f32_dpp v192, v169, v169 quad_perm:[2,3,0,1] row_mask:0xf bank_mask:0xf bound_ctrl:1
	s_waitcnt lgkmcnt(9)
; #define LAS __attribute__((address_space(3)))
; __device__ __forceinline__ float red4(float x) { x = DPP_ADD(x, 0xB1); x = DPP_ADD(x, 0x4E); return x; }
; __device__ __forceinline__ void phase_scan(const ScanArgs A, LAS unsigned char* lds) {
;     ...
;                     for (int i = 0; i < 2; ++i) { f32x2 y0 = {0.f, 0.f}, y1 = {0.f, 0.f}; const f32x2 sai = {sa[i], sa[i]}, vi = {v2[i], v2[i]};
; #pragma unroll
;                         for (int p = 0; p < 8; p += 2) {
;                             const f32x2 n0 = S2[i][p] * PAIR(Wv, p) + sai * PAIR(Bv, p) + vi * PAIR(KDv, p);
;                             const f32x2 n1 = S2[i][p + 1] * PAIR(Wv, p + 1) + sai * PAIR(Bv, p + 1) + vi * PAIR(KDv, p + 1);
;                             S2[i][p] = n0; S2[i][p + 1] = n1; y0 += n0 * PAIR(Rv, p); y1 += n1 * PAIR(Rv, p + 1); }
;                         y0 += y1; y[i] = red4(y0[0] + y0[1]); }
;     ...
;                     if (kq == 0) *(LAS f32x2*)(yb + t * 64 + half * 32 + rb * 2) = (f32x2){y[0], y[1]};
	v_pk_mul_f32 v[216:217], v[142:143], v[190:191] op_sel_hi:[1,0]
	v_pk_mul_f32 v[218:219], v[144:145], v[190:191] op_sel_hi:[1,0]
	v_pk_mul_f32 v[232:233], v[142:143], v[192:193] op_sel_hi:[1,0]
	v_pk_mul_f32 v[234:235], v[144:145], v[192:193] op_sel_hi:[1,0]
	v_pk_fma_f32 v[216:217], v[84:85], v[48:49], v[216:217]
	v_pk_fma_f32 v[218:219], v[88:89], v[50:51], v[218:219]
	v_pk_fma_f32 v[232:233], v[100:101], v[48:49], v[232:233]
	v_pk_fma_f32 v[234:235], v[104:105], v[50:51], v[234:235]
	v_pk_fma_f32 v[84:85], v[172:173], v[188:189], v[216:217] op_sel_hi:[1,0,1]
	v_pk_fma_f32 v[88:89], v[174:175], v[188:189], v[218:219] op_sel_hi:[1,0,1]
	v_pk_fma_f32 v[100:101], v[172:173], v[188:189], v[232:233] op_sel:[0,1,0]
	v_pk_fma_f32 v[104:105], v[174:175], v[188:189], v[234:235] op_sel:[0,1,0]
	ds_read_b128 v[142:145], v171 offset:8960
	ds_read_b128 v[48:51], v171 offset:768
	ds_read_b128 v[172:175], v171 offset:4864
	v_pk_mul_f32 v[220:221], v[146:147], v[190:191] op_sel_hi:[1,0]
	v_pk_mul_f32 v[222:223], v[148:149], v[190:191] op_sel_hi:[1,0]
	v_pk_mul_f32 v[236:237], v[146:147], v[192:193] op_sel_hi:[1,0]
	v_pk_mul_f32 v[238:239], v[148:149], v[192:193] op_sel_hi:[1,0]
	v_pk_fma_f32 v[220:221], v[86:87], v[52:53], v[220:221]
	v_pk_fma_f32 v[222:223], v[92:93], v[54:55], v[222:223]
	v_pk_fma_f32 v[236:237], v[106:107], v[52:53], v[236:237]
	v_pk_fma_f32 v[238:239], v[108:109], v[54:55], v[238:239]
	v_pk_fma_f32 v[86:87], v[176:177], v[188:189], v[220:221] op_sel_hi:[1,0,1]
	v_pk_fma_f32 v[92:93], v[178:179], v[188:189], v[222:223] op_sel_hi:[1,0,1]
	v_pk_fma_f32 v[106:107], v[176:177], v[188:189], v[236:237] op_sel:[0,1,0]
	v_pk_fma_f32 v[108:109], v[178:179], v[188:189], v[238:239] op_sel:[0,1,0]
	ds_read_b128 v[146:149], v171 offset:8976
	ds_read_b128 v[52:55], v171 offset:784
	ds_read_b128 v[176:179], v171 offset:4880
	v_pk_mul_f32 v[224:225], v[150:151], v[190:191] op_sel_hi:[1,0]
	v_pk_mul_f32 v[226:227], v[152:153], v[190:191] op_sel_hi:[1,0]
	v_pk_mul_f32 v[240:241], v[150:151], v[192:193] op_sel_hi:[1,0]
	v_pk_mul_f32 v[242:243], v[152:153], v[192:193] op_sel_hi:[1,0]
	v_pk_fma_f32 v[224:225], v[90:91], v[56:57], v[224:225]
	v_pk_fma_f32 v[226:227], v[98:99], v[58:59], v[226:227]
	v_pk_fma_f32 v[240:241], v[110:111], v[56:57], v[240:241]
	v_pk_fma_f32 v[242:243], v[112:113], v[58:59], v[242:243]
	v_pk_fma_f32 v[90:91], v[180:181], v[188:189], v[224:225] op_sel_hi:[1,0,1]
	v_pk_fma_f32 v[98:99], v[182:183], v[188:189], v[226:227] op_sel_hi:[1,0,1]
	v_pk_fma_f32 v[110:111], v[180:181], v[188:189], v[240:241] op_sel:[0,1,0]
	v_pk_fma_f32 v[112:113], v[182:183], v[188:189], v[242:243] op_sel:[0,1,0]
	ds_read_b128 v[150:153], v171 offset:8992
	ds_read_b128 v[56:59], v171 offset:800
	ds_read_b128 v[180:183], v171 offset:4896
	v_pk_mul_f32 v[228:229], v[154:155], v[190:191] op_sel_hi:[1,0]
	v_pk_mul_f32 v[230:231], v[156:157], v[190:191] op_sel_hi:[1,0]
	v_pk_mul_f32 v[244:245], v[154:155], v[192:193] op_sel_hi:[1,0]
	v_pk_mul_f32 v[246:247], v[156:157], v[192:193] op_sel_hi:[1,0]
	v_pk_fma_f32 v[228:229], v[94:95], v[60:61], v[228:229]
	v_pk_fma_f32 v[230:231], v[102:103], v[62:63], v[230:231]
	v_pk_fma_f32 v[244:245], v[114:115], v[60:61], v[244:245]
	v_pk_fma_f32 v[246:247], v[116:117], v[62:63], v[246:247]
	v_pk_fma_f32 v[94:95], v[184:185], v[188:189], v[228:229] op_sel_hi:[1,0,1]
	v_pk_fma_f32 v[102:103], v[186:187], v[188:189], v[230:231] op_sel_hi:[1,0,1]
	v_pk_fma_f32 v[114:115], v[184:185], v[188:189], v[244:245] op_sel:[0,1,0]
	v_pk_fma_f32 v[116:117], v[186:187], v[188:189], v[246:247] op_sel:[0,1,0]
	ds_read_b128 v[154:157], v171 offset:9008
	ds_read_b128 v[60:63], v171 offset:816
	ds_read_b128 v[184:187], v171 offset:4912
	ds_read_b64 v[188:189], v96 offset:768
	s_waitcnt lgkmcnt(15)
	v_pk_fma_f32 v[248:249], v[200:201], v[84:85], 0 op_sel_hi:[1,1,0]
	v_pk_fma_f32 v[250:251], v[202:203], v[88:89], 0 op_sel_hi:[1,1,0]
	v_pk_fma_f32 v[194:195], v[200:201], v[100:101], 0 op_sel_hi:[1,1,0]
	v_pk_fma_f32 v[158:159], v[202:203], v[104:105], 0 op_sel_hi:[1,1,0]
	v_pk_fma_f32 v[248:249], v[204:205], v[86:87], v[248:249]
	v_pk_fma_f32 v[250:251], v[206:207], v[92:93], v[250:251]
	v_pk_fma_f32 v[194:195], v[204:205], v[106:107], v[194:195]
	v_pk_fma_f32 v[158:159], v[206:207], v[108:109], v[158:159]
	v_pk_fma_f32 v[248:249], v[208:209], v[90:91], v[248:249]
	v_pk_fma_f32 v[250:251], v[210:211], v[98:99], v[250:251]
	v_pk_fma_f32 v[194:195], v[208:209], v[110:111], v[194:195]
	v_pk_fma_f32 v[158:159], v[210:211], v[112:113], v[158:159]
	v_pk_fma_f32 v[248:249], v[212:213], v[94:95], v[248:249]
	v_pk_fma_f32 v[250:251], v[214:215], v[102:103], v[250:251]
	v_pk_fma_f32 v[194:195], v[212:213], v[114:115], v[194:195]
	v_pk_fma_f32 v[158:159], v[214:215], v[116:117], v[158:159]
	ds_read_b128 v[200:203], v171 offset:17152
	ds_read_b128 v[204:207], v171 offset:17168
	ds_read_b128 v[208:211], v171 offset:17184
	ds_read_b128 v[212:215], v171 offset:17200
	v_pk_add_f32 v[248:249], v[250:251], v[248:249]
	v_pk_add_f32 v[194:195], v[158:159], v[194:195]
	v_add_f32_e32 v168, v248, v249
	v_add_f32_e32 v169, v194, v195
	s_nop 0
	v_add_f32_dpp v168, v168, v168 quad_perm:[1,0,3,2] row_mask:0xf bank_mask:0xf bound_ctrl:1
	v_add_f32_dpp v169, v169, v169 quad_perm:[1,0,3,2] row_mask:0xf bank_mask:0xf bound_ctrl:1
	s_nop 0
	v_add_f32_dpp v168, v168, v168 quad_perm:[2,3,0,1] row_mask:0xf bank_mask:0xf bound_ctrl:1
	v_add_f32_dpp v169, v169, v169 quad_perm:[2,3,0,1] row_mask:0xf bank_mask:0xf bound_ctrl:1
	s_and_saveexec_b64 s[34:35], s[8:9]
	ds_write_b64 v75, v[168:169] offset:512
	s_or_b64 exec, exec, s[34:35]
	s_waitcnt lgkmcnt(15)
; #define LAS __attribute__((address_space(3)))
; __device__ __forceinline__ float red4(float x) { x = DPP_ADD(x, 0xB1); x = DPP_ADD(x, 0x4E); return x; }
; __device__ __forceinline__ void phase_scan(const ScanArgs A, LAS unsigned char* lds) {
;     ...
;                 for (int t = 0; t < 16; ++t) {
;                     const LAS float* q = in + t * 64 + kq * 16;
;                     f32x4 Wv[4], KDv[4], Bv[4], ANv[4], Rv[4];
; #pragma unroll
;                     for (int j = 0; j < 4; ++j) { Wv[j] = *(const LAS f32x4*)(q + 4 * j); KDv[j] = *(const LAS f32x4*)(q + 1024 + 4 * j); Bv[j] = *(const LAS f32x4*)(q + 2048 + 4 * j);
;                                                   ANv[j] = *(const LAS f32x4*)(q + 3072 + 4 * j); Rv[j] = *(const LAS f32x4*)(q + 4096 + 4 * j); }
;                     const f32x2 v2 = *(const LAS f32x2*)(in + 5120 + t * 64 + half * 32 + rb * 2);
;     ...
;                     float sa[2], y[2];
; #pragma unroll
;                     for (int i = 0; i < 2; ++i) { f32x2 a0 = {0.f, 0.f}, a1 = {0.f, 0.f};
; #pragma unroll
;                         for (int p = 0; p < 8; p += 2) { a0 += S2[i][p] * PAIR(ANv, p); a1 += S2[i][p + 1] * PAIR(ANv, p + 1); }
;                         a0 += a1; sa[i] = red4(a0[0] + a0[1]); }
; #pragma unroll
;                     for (int i = 0; i < 2; ++i) { f32x2 y0 = {0.f, 0.f}, y1 = {0.f, 0.f}; const f32x2 sai = {sa[i], sa[i]}, vi = {v2[i], v2[i]};
; #pragma unroll
;                         for (int p = 0; p < 8; p += 2) {
;                             const f32x2 n0 = S2[i][p] * PAIR(Wv, p) + sai * PAIR(Bv, p) + vi * PAIR(KDv, p);
;                             const f32x2 n1 = S2[i][p + 1] * PAIR(Wv, p + 1) + sai * PAIR(Bv, p + 1) + vi * PAIR(KDv, p + 1);
;                             S2[i][p] = n0; S2[i][p + 1] = n1; y0 += n0 * PAIR(Rv, p); y1 += n1 * PAIR(Rv, p + 1); }
;                         y0 += y1; y[i] = red4(y0[0] + y0[1]); }
	v_pk_fma_f32 v[160:161], v[84:85], v[32:33], 0 op_sel_hi:[1,1,0]
	v_pk_fma_f32 v[162:163], v[88:89], v[34:35], 0 op_sel_hi:[1,1,0]
	v_pk_fma_f32 v[164:165], v[100:101], v[32:33], 0 op_sel_hi:[1,1,0]
	v_pk_fma_f32 v[166:167], v[104:105], v[34:35], 0 op_sel_hi:[1,1,0]
	v_pk_fma_f32 v[160:161], v[86:87], v[36:37], v[160:161]
	v_pk_fma_f32 v[162:163], v[92:93], v[38:39], v[162:163]
	v_pk_fma_f32 v[164:165], v[106:107], v[36:37], v[164:165]
	v_pk_fma_f32 v[166:167], v[108:109], v[38:39], v[166:167]
	v_pk_fma_f32 v[160:161], v[90:91], v[40:41], v[160:161]
	v_pk_fma_f32 v[162:163], v[98:99], v[42:43], v[162:163]
	v_pk_fma_f32 v[164:165], v[110:111], v[40:41], v[164:165]
	v_pk_fma_f32 v[166:167], v[112:113], v[42:43], v[166:167]
	v_pk_fma_f32 v[160:161], v[94:95], v[44:45], v[160:161]
	v_pk_fma_f32 v[162:163], v[102:103], v[46:47], v[162:163]
	v_pk_fma_f32 v[164:165], v[114:115], v[44:45], v[164:165]
	v_pk_fma_f32 v[166:167], v[116:117], v[46:47], v[166:167]
	ds_read_b128 v[32:35], v171 offset:13312
	ds_read_b128 v[36:39], v171 offset:13328
	ds_read_b128 v[40:43], v171 offset:13344
	ds_read_b128 v[44:47], v171 offset:13360
	v_pk_add_f32 v[160:161], v[162:163], v[160:161]
	v_pk_add_f32 v[164:165], v[166:167], v[164:165]
	v_add_f32_e32 v168, v160, v161
	v_add_f32_e32 v169, v164, v165
	s_nop 0
	v_add_f32_dpp v168, v168, v168 quad_perm:[1,0,3,2] row_mask:0xf bank_mask:0xf bound_ctrl:1
	v_add_f32_dpp v169, v169, v169 quad_perm:[1,0,3,2] row_mask:0xf bank_mask:0xf bound_ctrl:1
	s_nop 0
	v_add_f32_dpp v190, v168, v168 quad_perm:[2,3,0,1] row_mask:0xf bank_mask:0xf bound_ctrl:1
	v_add_f32_dpp v192, v169, v169 quad_perm:[2,3,0,1] row_mask:0xf bank_mask:0xf bound_ctrl:1
	s_waitcnt lgkmcnt(9)
	v_pk_mul_f32 v[216:217], v[142:143], v[190:191] op_sel_hi:[1,0]
	v_pk_mul_f32 v[218:219], v[144:145], v[190:191] op_sel_hi:[1,0]
	v_pk_mul_f32 v[232:233], v[142:143], v[192:193] op_sel_hi:[1,0]
	v_pk_mul_f32 v[234:235], v[144:145], v[192:193] op_sel_hi:[1,0]
	v_pk_fma_f32 v[216:217], v[84:85], v[48:49], v[216:217]
	v_pk_fma_f32 v[218:219], v[88:89], v[50:51], v[218:219]
	v_pk_fma_f32 v[232:233], v[100:101], v[48:49], v[232:233]
	v_pk_fma_f32 v[234:235], v[104:105], v[50:51], v[234:235]
	v_pk_fma_f32 v[84:85], v[172:173], v[188:189], v[216:217] op_sel_hi:[1,0,1]
	v_pk_fma_f32 v[88:89], v[174:175], v[188:189], v[218:219] op_sel_hi:[1,0,1]
	v_pk_fma_f32 v[100:101], v[172:173], v[188:189], v[232:233] op_sel:[0,1,0]
	v_pk_fma_f32 v[104:105], v[174:175], v[188:189], v[234:235] op_sel:[0,1,0]
	ds_read_b128 v[142:145], v171 offset:9216
	ds_read_b128 v[48:51], v171 offset:1024
	ds_read_b128 v[172:175], v171 offset:5120
	v_pk_mul_f32 v[220:221], v[146:147], v[190:191] op_sel_hi:[1,0]
	v_pk_mul_f32 v[222:223], v[148:149], v[190:191] op_sel_hi:[1,0]
	v_pk_mul_f32 v[236:237], v[146:147], v[192:193] op_sel_hi:[1,0]
	v_pk_mul_f32 v[238:239], v[148:149], v[192:193] op_sel_hi:[1,0]
	v_pk_fma_f32 v[220:221], v[86:87], v[52:53], v[220:221]
	v_pk_fma_f32 v[222:223], v[92:93], v[54:55], v[222:223]
	v_pk_fma_f32 v[236:237], v[106:107], v[52:53], v[236:237]
	v_pk_fma_f32 v[238:239], v[108:109], v[54:55], v[238:239]
	v_pk_fma_f32 v[86:87], v[176:177], v[188:189], v[220:221] op_sel_hi:[1,0,1]
	v_pk_fma_f32 v[92:93], v[178:179], v[188:189], v[222:223] op_sel_hi:[1,0,1]
	v_pk_fma_f32 v[106:107], v[176:177], v[188:189], v[236:237] op_sel:[0,1,0]
	v_pk_fma_f32 v[108:109], v[178:179], v[188:189], v[238:239] op_sel:[0,1,0]
	ds_read_b128 v[146:149], v171 offset:9232
	ds_read_b128 v[52:55], v171 offset:1040
	ds_read_b128 v[176:179], v171 offset:5136
	v_pk_mul_f32 v[224:225], v[150:151], v[190:191] op_sel_hi:[1,0]
	v_pk_mul_f32 v[226:227], v[152:153], v[190:191] op_sel_hi:[1,0]
	v_pk_mul_f32 v[240:241], v[150:151], v[192:193] op_sel_hi:[1,0]
	v_pk_mul_f32 v[242:243], v[152:153], v[192:193] op_sel_hi:[1,0]
	v_pk_fma_f32 v[224:225], v[90:91], v[56:57], v[224:225]
	v_pk_fma_f32 v[226:227], v[98:99], v[58:59], v[226:227]
	v_pk_fma_f32 v[240:241], v[110:111], v[56:57], v[240:241]
	v_pk_fma_f32 v[242:243], v[112:113], v[58:59], v[242:243]
	v_pk_fma_f32 v[90:91], v[180:181], v[188:189], v[224:225] op_sel_hi:[1,0,1]
	v_pk_fma_f32 v[98:99], v[182:183], v[188:189], v[226:227] op_sel_hi:[1,0,1]
	v_pk_fma_f32 v[110:111], v[180:181], v[188:189], v[240:241] op_sel:[0,1,0]
	v_pk_fma_f32 v[112:113], v[182:183], v[188:189], v[242:243] op_sel:[0,1,0]
	ds_read_b128 v[150:153], v171 offset:9248
	ds_read_b128 v[56:59], v171 offset:1056
	ds_read_b128 v[180:183], v171 offset:5152
	v_pk_mul_f32 v[228:229], v[154:155], v[190:191] op_sel_hi:[1,0]
	v_pk_mul_f32 v[230:231], v[156:157], v[190:191] op_sel_hi:[1,0]
	v_pk_mul_f32 v[244:245], v[154:155], v[192:193] op_sel_hi:[1,0]
	v_pk_mul_f32 v[246:247], v[156:157], v[192:193] op_sel_hi:[1,0]
	v_pk_fma_f32 v[228:229], v[94:95], v[60:61], v[228:229]
	v_pk_fma_f32 v[230:231], v[102:103], v[62:63], v[230:231]
	v_pk_fma_f32 v[244:245], v[114:115], v[60:61], v[244:245]
	v_pk_fma_f32 v[246:247], v[116:117], v[62:63], v[246:247]
	v_pk_fma_f32 v[94:95], v[184:185], v[188:189], v[228:229] op_sel_hi:[1,0,1]
	v_pk_fma_f32 v[102:103], v[186:187], v[188:189], v[230:231] op_sel_hi:[1,0,1]
	v_pk_fma_f32 v[114:115], v[184:185], v[188:189], v[244:245] op_sel:[0,1,0]
	v_pk_fma_f32 v[116:117], v[186:187], v[188:189], v[246:247] op_sel:[0,1,0]
	ds_read_b128 v[154:157], v171 offset:9264
	ds_read_b128 v[60:63], v171 offset:1072
	ds_read_b128 v[184:187], v171 offset:5168
	ds_read_b64 v[188:189], v96 offset:1024
	s_waitcnt lgkmcnt(15)
; #define LAS __attribute__((address_space(3)))
; __device__ __forceinline__ float red4(float x) { x = DPP_ADD(x, 0xB1); x = DPP_ADD(x, 0x4E); return x; }
; __device__ __forceinline__ void phase_scan(const ScanArgs A, LAS unsigned char* lds) {
;     ...
;                 for (int t = 0; t < 16; ++t) {
;                     const LAS float* q = in + t * 64 + kq * 16;
;                     f32x4 Wv[4], KDv[4], Bv[4], ANv[4], Rv[4];
; #pragma unroll
;                     for (int j = 0; j < 4; ++j) { Wv[j] = *(const LAS f32x4*)(q + 4 * j); KDv[j] = *(const LAS f32x4*)(q + 1024 + 4 * j); Bv[j] = *(const LAS f32x4*)(q + 2048 + 4 * j);
;                                                   ANv[j] = *(const LAS f32x4*)(q + 3072 + 4 * j); Rv[j] = *(const LAS f32x4*)(q + 4096 + 4 * j); }
;                     const f32x2 v2 = *(const LAS f32x2*)(in + 5120 + t * 64 + half * 32 + rb * 2);
;     ...
;                     float sa[2], y[2];
; #pragma unroll
;                     for (int i = 0; i < 2; ++i) { f32x2 a0 = {0.f, 0.f}, a1 = {0.f, 0.f};
; #pragma unroll
;                         for (int p = 0; p < 8; p += 2) { a0 += S2[i][p] * PAIR(ANv, p); a1 += S2[i][p + 1] * PAIR(ANv, p + 1); }
;                         a0 += a1; sa[i] = red4(a0[0] + a0[1]); }
;     ...
;                     for (int i = 0; i < 2; ++i) { f32x2 y0 = {0.f, 0.f}, y1 = {0.f, 0.f}; const f32x2 sai = {sa[i], sa[i]}, vi = {v2[i], v2[i]};
; #pragma unroll
;                         for (int p = 0; p < 8; p += 2) {
;                             const f32x2 n0 = S2[i][p] * PAIR(Wv, p) + sai * PAIR(Bv, p) + vi * PAIR(KDv, p);
;                             const f32x2 n1 = S2[i][p + 1] * PAIR(Wv, p + 1) + sai * PAIR(Bv, p + 1) + vi * PAIR(KDv, p + 1);
;                             S2[i][p] = n0; S2[i][p + 1] = n1; y0 += n0 * PAIR(Rv, p); y1 += n1 * PAIR(Rv, p + 1); }
;                         y0 += y1; y[i] = red4(y0[0] + y0[1]); }
;     ...
;                     if (kq == 0) *(LAS f32x2*)(yb + t * 64 + half * 32 + rb * 2) = (f32x2){y[0], y[1]};
	v_pk_fma_f32 v[248:249], v[200:201], v[84:85], 0 op_sel_hi:[1,1,0]
	v_pk_fma_f32 v[250:251], v[202:203], v[88:89], 0 op_sel_hi:[1,1,0]
	v_pk_fma_f32 v[194:195], v[200:201], v[100:101], 0 op_sel_hi:[1,1,0]
	v_pk_fma_f32 v[158:159], v[202:203], v[104:105], 0 op_sel_hi:[1,1,0]
	v_pk_fma_f32 v[248:249], v[204:205], v[86:87], v[248:249]
	v_pk_fma_f32 v[250:251], v[206:207], v[92:93], v[250:251]
	v_pk_fma_f32 v[194:195], v[204:205], v[106:107], v[194:195]
	v_pk_fma_f32 v[158:159], v[206:207], v[108:109], v[158:159]
	v_pk_fma_f32 v[248:249], v[208:209], v[90:91], v[248:249]
	v_pk_fma_f32 v[250:251], v[210:211], v[98:99], v[250:251]
	v_pk_fma_f32 v[194:195], v[208:209], v[110:111], v[194:195]
	v_pk_fma_f32 v[158:159], v[210:211], v[112:113], v[158:159]
	v_pk_fma_f32 v[248:249], v[212:213], v[94:95], v[248:249]
	v_pk_fma_f32 v[250:251], v[214:215], v[102:103], v[250:251]
	v_pk_fma_f32 v[194:195], v[212:213], v[114:115], v[194:195]
	v_pk_fma_f32 v[158:159], v[214:215], v[116:117], v[158:159]
	ds_read_b128 v[200:203], v171 offset:17408
	ds_read_b128 v[204:207], v171 offset:17424
	ds_read_b128 v[208:211], v171 offset:17440
	ds_read_b128 v[212:215], v171 offset:17456
	v_pk_add_f32 v[248:249], v[250:251], v[248:249]
	v_pk_add_f32 v[194:195], v[158:159], v[194:195]
	v_add_f32_e32 v168, v248, v249
	v_add_f32_e32 v169, v194, v195
	s_nop 0
	v_add_f32_dpp v168, v168, v168 quad_perm:[1,0,3,2] row_mask:0xf bank_mask:0xf bound_ctrl:1
	v_add_f32_dpp v169, v169, v169 quad_perm:[1,0,3,2] row_mask:0xf bank_mask:0xf bound_ctrl:1
	s_nop 0
	v_add_f32_dpp v168, v168, v168 quad_perm:[2,3,0,1] row_mask:0xf bank_mask:0xf bound_ctrl:1
	v_add_f32_dpp v169, v169, v169 quad_perm:[2,3,0,1] row_mask:0xf bank_mask:0xf bound_ctrl:1
	s_and_saveexec_b64 s[34:35], s[8:9]
	ds_write_b64 v75, v[168:169] offset:768
	s_or_b64 exec, exec, s[34:35]
	s_waitcnt lgkmcnt(15)
	v_pk_fma_f32 v[160:161], v[84:85], v[32:33], 0 op_sel_hi:[1,1,0]
	v_pk_fma_f32 v[162:163], v[88:89], v[34:35], 0 op_sel_hi:[1,1,0]
	v_pk_fma_f32 v[164:165], v[100:101], v[32:33], 0 op_sel_hi:[1,1,0]
	v_pk_fma_f32 v[166:167], v[104:105], v[34:35], 0 op_sel_hi:[1,1,0]
	v_pk_fma_f32 v[160:161], v[86:87], v[36:37], v[160:161]
	v_pk_fma_f32 v[162:163], v[92:93], v[38:39], v[162:163]
	v_pk_fma_f32 v[164:165], v[106:107], v[36:37], v[164:165]
	v_pk_fma_f32 v[166:167], v[108:109], v[38:39], v[166:167]
	v_pk_fma_f32 v[160:161], v[90:91], v[40:41], v[160:161]
	v_pk_fma_f32 v[162:163], v[98:99], v[42:43], v[162:163]
	v_pk_fma_f32 v[164:165], v[110:111], v[40:41], v[164:165]
	v_pk_fma_f32 v[166:167], v[112:113], v[42:43], v[166:167]
	v_pk_fma_f32 v[160:161], v[94:95], v[44:45], v[160:161]
	v_pk_fma_f32 v[162:163], v[102:103], v[46:47], v[162:163]
	v_pk_fma_f32 v[164:165], v[114:115], v[44:45], v[164:165]
	v_pk_fma_f32 v[166:167], v[116:117], v[46:47], v[166:167]
	ds_read_b128 v[32:35], v171 offset:13568
	ds_read_b128 v[36:39], v171 offset:13584
	ds_read_b128 v[40:43], v171 offset:13600
	ds_read_b128 v[44:47], v171 offset:13616
	v_pk_add_f32 v[160:161], v[162:163], v[160:161]
	v_pk_add_f32 v[164:165], v[166:167], v[164:165]
	v_add_f32_e32 v168, v160, v161
	v_add_f32_e32 v169, v164, v165
	s_nop 0
	v_add_f32_dpp v168, v168, v168 quad_perm:[1,0,3,2] row_mask:0xf bank_mask:0xf bound_ctrl:1
	v_add_f32_dpp v169, v169, v169 quad_perm:[1,0,3,2] row_mask:0xf bank_mask:0xf bound_ctrl:1
	s_nop 0
	v_add_f32_dpp v190, v168, v168 quad_perm:[2,3,0,1] row_mask:0xf bank_mask:0xf bound_ctrl:1
	v_add_f32_dpp v192, v169, v169 quad_perm:[2,3,0,1] row_mask:0xf bank_mask:0xf bound_ctrl:1
	s_waitcnt lgkmcnt(9)
	v_pk_mul_f32 v[216:217], v[142:143], v[190:191] op_sel_hi:[1,0]
	v_pk_mul_f32 v[218:219], v[144:145], v[190:191] op_sel_hi:[1,0]
	v_pk_mul_f32 v[232:233], v[142:143], v[192:193] op_sel_hi:[1,0]
	v_pk_mul_f32 v[234:235], v[144:145], v[192:193] op_sel_hi:[1,0]
	v_pk_fma_f32 v[216:217], v[84:85], v[48:49], v[216:217]
	v_pk_fma_f32 v[218:219], v[88:89], v[50:51], v[218:219]
	v_pk_fma_f32 v[232:233], v[100:101], v[48:49], v[232:233]
	v_pk_fma_f32 v[234:235], v[104:105], v[50:51], v[234:235]
	v_pk_fma_f32 v[84:85], v[172:173], v[188:189], v[216:217] op_sel_hi:[1,0,1]
	v_pk_fma_f32 v[88:89], v[174:175], v[188:189], v[218:219] op_sel_hi:[1,0,1]
	v_pk_fma_f32 v[100:101], v[172:173], v[188:189], v[232:233] op_sel:[0,1,0]
	v_pk_fma_f32 v[104:105], v[174:175], v[188:189], v[234:235] op_sel:[0,1,0]
	ds_read_b128 v[142:145], v171 offset:9472
	ds_read_b128 v[48:51], v171 offset:1280
	ds_read_b128 v[172:175], v171 offset:5376
	v_pk_mul_f32 v[220:221], v[146:147], v[190:191] op_sel_hi:[1,0]
	v_pk_mul_f32 v[222:223], v[148:149], v[190:191] op_sel_hi:[1,0]
	v_pk_mul_f32 v[236:237], v[146:147], v[192:193] op_sel_hi:[1,0]
	v_pk_mul_f32 v[238:239], v[148:149], v[192:193] op_sel_hi:[1,0]
	v_pk_fma_f32 v[220:221], v[86:87], v[52:53], v[220:221]
	v_pk_fma_f32 v[222:223], v[92:93], v[54:55], v[222:223]
	v_pk_fma_f32 v[236:237], v[106:107], v[52:53], v[236:237]
	v_pk_fma_f32 v[238:239], v[108:109], v[54:55], v[238:239]
	v_pk_fma_f32 v[86:87], v[176:177], v[188:189], v[220:221] op_sel_hi:[1,0,1]
	v_pk_fma_f32 v[92:93], v[178:179], v[188:189], v[222:223] op_sel_hi:[1,0,1]
	v_pk_fma_f32 v[106:107], v[176:177], v[188:189], v[236:237] op_sel:[0,1,0]
	v_pk_fma_f32 v[108:109], v[178:179], v[188:189], v[238:239] op_sel:[0,1,0]
	ds_read_b128 v[146:149], v171 offset:9488
	ds_read_b128 v[52:55], v171 offset:1296
	ds_read_b128 v[176:179], v171 offset:5392
	v_pk_mul_f32 v[224:225], v[150:151], v[190:191] op_sel_hi:[1,0]
	v_pk_mul_f32 v[226:227], v[152:153], v[190:191] op_sel_hi:[1,0]
	v_pk_mul_f32 v[240:241], v[150:151], v[192:193] op_sel_hi:[1,0]
	v_pk_mul_f32 v[242:243], v[152:153], v[192:193] op_sel_hi:[1,0]
; #define LAS __attribute__((address_space(3)))
; __device__ __forceinline__ float red4(float x) { x = DPP_ADD(x, 0xB1); x = DPP_ADD(x, 0x4E); return x; }
; __device__ __forceinline__ void phase_scan(const ScanArgs A, LAS unsigned char* lds) {
;     ...
;                 for (int t = 0; t < 16; ++t) {
;                     const LAS float* q = in + t * 64 + kq * 16;
;                     f32x4 Wv[4], KDv[4], Bv[4], ANv[4], Rv[4];
; #pragma unroll
;                     for (int j = 0; j < 4; ++j) { Wv[j] = *(const LAS f32x4*)(q + 4 * j); KDv[j] = *(const LAS f32x4*)(q + 1024 + 4 * j); Bv[j] = *(const LAS f32x4*)(q + 2048 + 4 * j);
;                                                   ANv[j] = *(const LAS f32x4*)(q + 3072 + 4 * j); Rv[j] = *(const LAS f32x4*)(q + 4096 + 4 * j); }
;                     const f32x2 v2 = *(const LAS f32x2*)(in + 5120 + t * 64 + half * 32 + rb * 2);
;     ...
;                     float sa[2], y[2];
; #pragma unroll
;                     for (int i = 0; i < 2; ++i) { f32x2 a0 = {0.f, 0.f}, a1 = {0.f, 0.f};
; #pragma unroll
;                         for (int p = 0; p < 8; p += 2) { a0 += S2[i][p] * PAIR(ANv, p); a1 += S2[i][p + 1] * PAIR(ANv, p + 1); }
;                         a0 += a1; sa[i] = red4(a0[0] + a0[1]); }
;     ...
;                     for (int i = 0; i < 2; ++i) { f32x2 y0 = {0.f, 0.f}, y1 = {0.f, 0.f}; const f32x2 sai = {sa[i], sa[i]}, vi = {v2[i], v2[i]};
; #pragma unroll
;                         for (int p = 0; p < 8; p += 2) {
;                             const f32x2 n0 = S2[i][p] * PAIR(Wv, p) + sai * PAIR(Bv, p) + vi * PAIR(KDv, p);
;                             const f32x2 n1 = S2[i][p + 1] * PAIR(Wv, p + 1) + sai * PAIR(Bv, p + 1) + vi * PAIR(KDv, p + 1);
;                             S2[i][p] = n0; S2[i][p + 1] = n1; y0 += n0 * PAIR(Rv, p); y1 += n1 * PAIR(Rv, p + 1); }
;                         y0 += y1; y[i] = red4(y0[0] + y0[1]); }
;     ...
;                     if (kq == 0) *(LAS f32x2*)(yb + t * 64 + half * 32 + rb * 2) = (f32x2){y[0], y[1]};
	v_pk_fma_f32 v[224:225], v[90:91], v[56:57], v[224:225]
	v_pk_fma_f32 v[226:227], v[98:99], v[58:59], v[226:227]
	v_pk_fma_f32 v[240:241], v[110:111], v[56:57], v[240:241]
	v_pk_fma_f32 v[242:243], v[112:113], v[58:59], v[242:243]
	v_pk_fma_f32 v[90:91], v[180:181], v[188:189], v[224:225] op_sel_hi:[1,0,1]
	v_pk_fma_f32 v[98:99], v[182:183], v[188:189], v[226:227] op_sel_hi:[1,0,1]
	v_pk_fma_f32 v[110:111], v[180:181], v[188:189], v[240:241] op_sel:[0,1,0]
	v_pk_fma_f32 v[112:113], v[182:183], v[188:189], v[242:243] op_sel:[0,1,0]
	ds_read_b128 v[150:153], v171 offset:9504
	ds_read_b128 v[56:59], v171 offset:1312
	ds_read_b128 v[180:183], v171 offset:5408
	v_pk_mul_f32 v[228:229], v[154:155], v[190:191] op_sel_hi:[1,0]
	v_pk_mul_f32 v[230:231], v[156:157], v[190:191] op_sel_hi:[1,0]
	v_pk_mul_f32 v[244:245], v[154:155], v[192:193] op_sel_hi:[1,0]
	v_pk_mul_f32 v[246:247], v[156:157], v[192:193] op_sel_hi:[1,0]
	v_pk_fma_f32 v[228:229], v[94:95], v[60:61], v[228:229]
	v_pk_fma_f32 v[230:231], v[102:103], v[62:63], v[230:231]
	v_pk_fma_f32 v[244:245], v[114:115], v[60:61], v[244:245]
	v_pk_fma_f32 v[246:247], v[116:117], v[62:63], v[246:247]
	v_pk_fma_f32 v[94:95], v[184:185], v[188:189], v[228:229] op_sel_hi:[1,0,1]
	v_pk_fma_f32 v[102:103], v[186:187], v[188:189], v[230:231] op_sel_hi:[1,0,1]
	v_pk_fma_f32 v[114:115], v[184:185], v[188:189], v[244:245] op_sel:[0,1,0]
	v_pk_fma_f32 v[116:117], v[186:187], v[188:189], v[246:247] op_sel:[0,1,0]
	ds_read_b128 v[154:157], v171 offset:9520
	ds_read_b128 v[60:63], v171 offset:1328
	ds_read_b128 v[184:187], v171 offset:5424
	ds_read_b64 v[188:189], v96 offset:1280
	s_waitcnt lgkmcnt(15)
	v_pk_fma_f32 v[248:249], v[200:201], v[84:85], 0 op_sel_hi:[1,1,0]
	v_pk_fma_f32 v[250:251], v[202:203], v[88:89], 0 op_sel_hi:[1,1,0]
	v_pk_fma_f32 v[194:195], v[200:201], v[100:101], 0 op_sel_hi:[1,1,0]
	v_pk_fma_f32 v[158:159], v[202:203], v[104:105], 0 op_sel_hi:[1,1,0]
	v_pk_fma_f32 v[248:249], v[204:205], v[86:87], v[248:249]
	v_pk_fma_f32 v[250:251], v[206:207], v[92:93], v[250:251]
	v_pk_fma_f32 v[194:195], v[204:205], v[106:107], v[194:195]
	v_pk_fma_f32 v[158:159], v[206:207], v[108:109], v[158:159]
	v_pk_fma_f32 v[248:249], v[208:209], v[90:91], v[248:249]
	v_pk_fma_f32 v[250:251], v[210:211], v[98:99], v[250:251]
	v_pk_fma_f32 v[194:195], v[208:209], v[110:111], v[194:195]
	v_pk_fma_f32 v[158:159], v[210:211], v[112:113], v[158:159]
	v_pk_fma_f32 v[248:249], v[212:213], v[94:95], v[248:249]
	v_pk_fma_f32 v[250:251], v[214:215], v[102:103], v[250:251]
	v_pk_fma_f32 v[194:195], v[212:213], v[114:115], v[194:195]
	v_pk_fma_f32 v[158:159], v[214:215], v[116:117], v[158:159]
	ds_read_b128 v[200:203], v171 offset:17664
	ds_read_b128 v[204:207], v171 offset:17680
	ds_read_b128 v[208:211], v171 offset:17696
	ds_read_b128 v[212:215], v171 offset:17712
	v_pk_add_f32 v[248:249], v[250:251], v[248:249]
	v_pk_add_f32 v[194:195], v[158:159], v[194:195]
	v_add_f32_e32 v168, v248, v249
	v_add_f32_e32 v169, v194, v195
	s_nop 0
	v_add_f32_dpp v168, v168, v168 quad_perm:[1,0,3,2] row_mask:0xf bank_mask:0xf bound_ctrl:1
	v_add_f32_dpp v169, v169, v169 quad_perm:[1,0,3,2] row_mask:0xf bank_mask:0xf bound_ctrl:1
	s_nop 0
	v_add_f32_dpp v168, v168, v168 quad_perm:[2,3,0,1] row_mask:0xf bank_mask:0xf bound_ctrl:1
	v_add_f32_dpp v169, v169, v169 quad_perm:[2,3,0,1] row_mask:0xf bank_mask:0xf bound_ctrl:1
	s_and_saveexec_b64 s[34:35], s[8:9]
	ds_write_b64 v75, v[168:169] offset:1024
	s_or_b64 exec, exec, s[34:35]
	s_waitcnt lgkmcnt(15)
	v_pk_fma_f32 v[160:161], v[84:85], v[32:33], 0 op_sel_hi:[1,1,0]
	v_pk_fma_f32 v[162:163], v[88:89], v[34:35], 0 op_sel_hi:[1,1,0]
	v_pk_fma_f32 v[164:165], v[100:101], v[32:33], 0 op_sel_hi:[1,1,0]
	v_pk_fma_f32 v[166:167], v[104:105], v[34:35], 0 op_sel_hi:[1,1,0]
	v_pk_fma_f32 v[160:161], v[86:87], v[36:37], v[160:161]
	v_pk_fma_f32 v[162:163], v[92:93], v[38:39], v[162:163]
	v_pk_fma_f32 v[164:165], v[106:107], v[36:37], v[164:165]
	v_pk_fma_f32 v[166:167], v[108:109], v[38:39], v[166:167]
	v_pk_fma_f32 v[160:161], v[90:91], v[40:41], v[160:161]
	v_pk_fma_f32 v[162:163], v[98:99], v[42:43], v[162:163]
	v_pk_fma_f32 v[164:165], v[110:111], v[40:41], v[164:165]
	v_pk_fma_f32 v[166:167], v[112:113], v[42:43], v[166:167]
	v_pk_fma_f32 v[160:161], v[94:95], v[44:45], v[160:161]
	v_pk_fma_f32 v[162:163], v[102:103], v[46:47], v[162:163]
	v_pk_fma_f32 v[164:165], v[114:115], v[44:45], v[164:165]
	v_pk_fma_f32 v[166:167], v[116:117], v[46:47], v[166:167]
	ds_read_b128 v[32:35], v171 offset:13824
	ds_read_b128 v[36:39], v171 offset:13840
	ds_read_b128 v[40:43], v171 offset:13856
	ds_read_b128 v[44:47], v171 offset:13872
	v_pk_add_f32 v[160:161], v[162:163], v[160:161]
	v_pk_add_f32 v[164:165], v[166:167], v[164:165]
	v_add_f32_e32 v168, v160, v161
	v_add_f32_e32 v169, v164, v165
	s_nop 0
	v_add_f32_dpp v168, v168, v168 quad_perm:[1,0,3,2] row_mask:0xf bank_mask:0xf bound_ctrl:1
	v_add_f32_dpp v169, v169, v169 quad_perm:[1,0,3,2] row_mask:0xf bank_mask:0xf bound_ctrl:1
	s_nop 0
	v_add_f32_dpp v190, v168, v168 quad_perm:[2,3,0,1] row_mask:0xf bank_mask:0xf bound_ctrl:1
	v_add_f32_dpp v192, v169, v169 quad_perm:[2,3,0,1] row_mask:0xf bank_mask:0xf bound_ctrl:1
	s_waitcnt lgkmcnt(9)
; #define LAS __attribute__((address_space(3)))
; __device__ __forceinline__ float red4(float x) { x = DPP_ADD(x, 0xB1); x = DPP_ADD(x, 0x4E); return x; }
; __device__ __forceinline__ void phase_scan(const ScanArgs A, LAS unsigned char* lds) {
;     ...
;                     for (int i = 0; i < 2; ++i) { f32x2 y0 = {0.f, 0.f}, y1 = {0.f, 0.f}; const f32x2 sai = {sa[i], sa[i]}, vi = {v2[i], v2[i]};
; #pragma unroll
;                         for (int p = 0; p < 8; p += 2) {
;                             const f32x2 n0 = S2[i][p] * PAIR(Wv, p) + sai * PAIR(Bv, p) + vi * PAIR(KDv, p);
;                             const f32x2 n1 = S2[i][p + 1] * PAIR(Wv, p + 1) + sai * PAIR(Bv, p + 1) + vi * PAIR(KDv, p + 1);
;                             S2[i][p] = n0; S2[i][p + 1] = n1; y0 += n0 * PAIR(Rv, p); y1 += n1 * PAIR(Rv, p + 1); }
;                         y0 += y1; y[i] = red4(y0[0] + y0[1]); }
;     ...
;                     if (kq == 0) *(LAS f32x2*)(yb + t * 64 + half * 32 + rb * 2) = (f32x2){y[0], y[1]};
	v_pk_mul_f32 v[216:217], v[142:143], v[190:191] op_sel_hi:[1,0]
	v_pk_mul_f32 v[218:219], v[144:145], v[190:191] op_sel_hi:[1,0]
	v_pk_mul_f32 v[232:233], v[142:143], v[192:193] op_sel_hi:[1,0]
	v_pk_mul_f32 v[234:235], v[144:145], v[192:193] op_sel_hi:[1,0]
	v_pk_fma_f32 v[216:217], v[84:85], v[48:49], v[216:217]
	v_pk_fma_f32 v[218:219], v[88:89], v[50:51], v[218:219]
	v_pk_fma_f32 v[232:233], v[100:101], v[48:49], v[232:233]
	v_pk_fma_f32 v[234:235], v[104:105], v[50:51], v[234:235]
	v_pk_fma_f32 v[84:85], v[172:173], v[188:189], v[216:217] op_sel_hi:[1,0,1]
	v_pk_fma_f32 v[88:89], v[174:175], v[188:189], v[218:219] op_sel_hi:[1,0,1]
	v_pk_fma_f32 v[100:101], v[172:173], v[188:189], v[232:233] op_sel:[0,1,0]
	v_pk_fma_f32 v[104:105], v[174:175], v[188:189], v[234:235] op_sel:[0,1,0]
	ds_read_b128 v[142:145], v171 offset:9728
	ds_read_b128 v[48:51], v171 offset:1536
	ds_read_b128 v[172:175], v171 offset:5632
	v_pk_mul_f32 v[220:221], v[146:147], v[190:191] op_sel_hi:[1,0]
	v_pk_mul_f32 v[222:223], v[148:149], v[190:191] op_sel_hi:[1,0]
	v_pk_mul_f32 v[236:237], v[146:147], v[192:193] op_sel_hi:[1,0]
	v_pk_mul_f32 v[238:239], v[148:149], v[192:193] op_sel_hi:[1,0]
	v_pk_fma_f32 v[220:221], v[86:87], v[52:53], v[220:221]
	v_pk_fma_f32 v[222:223], v[92:93], v[54:55], v[222:223]
	v_pk_fma_f32 v[236:237], v[106:107], v[52:53], v[236:237]
	v_pk_fma_f32 v[238:239], v[108:109], v[54:55], v[238:239]
	v_pk_fma_f32 v[86:87], v[176:177], v[188:189], v[220:221] op_sel_hi:[1,0,1]
	v_pk_fma_f32 v[92:93], v[178:179], v[188:189], v[222:223] op_sel_hi:[1,0,1]
	v_pk_fma_f32 v[106:107], v[176:177], v[188:189], v[236:237] op_sel:[0,1,0]
	v_pk_fma_f32 v[108:109], v[178:179], v[188:189], v[238:239] op_sel:[0,1,0]
	ds_read_b128 v[146:149], v171 offset:9744
	ds_read_b128 v[52:55], v171 offset:1552
	ds_read_b128 v[176:179], v171 offset:5648
	v_pk_mul_f32 v[224:225], v[150:151], v[190:191] op_sel_hi:[1,0]
	v_pk_mul_f32 v[226:227], v[152:153], v[190:191] op_sel_hi:[1,0]
	v_pk_mul_f32 v[240:241], v[150:151], v[192:193] op_sel_hi:[1,0]
	v_pk_mul_f32 v[242:243], v[152:153], v[192:193] op_sel_hi:[1,0]
	v_pk_fma_f32 v[224:225], v[90:91], v[56:57], v[224:225]
	v_pk_fma_f32 v[226:227], v[98:99], v[58:59], v[226:227]
	v_pk_fma_f32 v[240:241], v[110:111], v[56:57], v[240:241]
	v_pk_fma_f32 v[242:243], v[112:113], v[58:59], v[242:243]
	v_pk_fma_f32 v[90:91], v[180:181], v[188:189], v[224:225] op_sel_hi:[1,0,1]
	v_pk_fma_f32 v[98:99], v[182:183], v[188:189], v[226:227] op_sel_hi:[1,0,1]
	v_pk_fma_f32 v[110:111], v[180:181], v[188:189], v[240:241] op_sel:[0,1,0]
	v_pk_fma_f32 v[112:113], v[182:183], v[188:189], v[242:243] op_sel:[0,1,0]
	ds_read_b128 v[150:153], v171 offset:9760
	ds_read_b128 v[56:59], v171 offset:1568
	ds_read_b128 v[180:183], v171 offset:5664
	v_pk_mul_f32 v[228:229], v[154:155], v[190:191] op_sel_hi:[1,0]
	v_pk_mul_f32 v[230:231], v[156:157], v[190:191] op_sel_hi:[1,0]
	v_pk_mul_f32 v[244:245], v[154:155], v[192:193] op_sel_hi:[1,0]
	v_pk_mul_f32 v[246:247], v[156:157], v[192:193] op_sel_hi:[1,0]
	v_pk_fma_f32 v[228:229], v[94:95], v[60:61], v[228:229]
	v_pk_fma_f32 v[230:231], v[102:103], v[62:63], v[230:231]
	v_pk_fma_f32 v[244:245], v[114:115], v[60:61], v[244:245]
	v_pk_fma_f32 v[246:247], v[116:117], v[62:63], v[246:247]
	v_pk_fma_f32 v[94:95], v[184:185], v[188:189], v[228:229] op_sel_hi:[1,0,1]
	v_pk_fma_f32 v[102:103], v[186:187], v[188:189], v[230:231] op_sel_hi:[1,0,1]
	v_pk_fma_f32 v[114:115], v[184:185], v[188:189], v[244:245] op_sel:[0,1,0]
	v_pk_fma_f32 v[116:117], v[186:187], v[188:189], v[246:247] op_sel:[0,1,0]
	ds_read_b128 v[154:157], v171 offset:9776
	ds_read_b128 v[60:63], v171 offset:1584
	ds_read_b128 v[184:187], v171 offset:5680
	ds_read_b64 v[188:189], v96 offset:1536
	s_waitcnt lgkmcnt(15)
	v_pk_fma_f32 v[248:249], v[200:201], v[84:85], 0 op_sel_hi:[1,1,0]
	v_pk_fma_f32 v[250:251], v[202:203], v[88:89], 0 op_sel_hi:[1,1,0]
	v_pk_fma_f32 v[194:195], v[200:201], v[100:101], 0 op_sel_hi:[1,1,0]
	v_pk_fma_f32 v[158:159], v[202:203], v[104:105], 0 op_sel_hi:[1,1,0]
	v_pk_fma_f32 v[248:249], v[204:205], v[86:87], v[248:249]
	v_pk_fma_f32 v[250:251], v[206:207], v[92:93], v[250:251]
	v_pk_fma_f32 v[194:195], v[204:205], v[106:107], v[194:195]
	v_pk_fma_f32 v[158:159], v[206:207], v[108:109], v[158:159]
	v_pk_fma_f32 v[248:249], v[208:209], v[90:91], v[248:249]
	v_pk_fma_f32 v[250:251], v[210:211], v[98:99], v[250:251]
	v_pk_fma_f32 v[194:195], v[208:209], v[110:111], v[194:195]
	v_pk_fma_f32 v[158:159], v[210:211], v[112:113], v[158:159]
	v_pk_fma_f32 v[248:249], v[212:213], v[94:95], v[248:249]
	v_pk_fma_f32 v[250:251], v[214:215], v[102:103], v[250:251]
	v_pk_fma_f32 v[194:195], v[212:213], v[114:115], v[194:195]
	v_pk_fma_f32 v[158:159], v[214:215], v[116:117], v[158:159]
	ds_read_b128 v[200:203], v171 offset:17920
	ds_read_b128 v[204:207], v171 offset:17936
	ds_read_b128 v[208:211], v171 offset:17952
	ds_read_b128 v[212:215], v171 offset:17968
	v_pk_add_f32 v[248:249], v[250:251], v[248:249]
	v_pk_add_f32 v[194:195], v[158:159], v[194:195]
	v_add_f32_e32 v168, v248, v249
	v_add_f32_e32 v169, v194, v195
	s_nop 0
	v_add_f32_dpp v168, v168, v168 quad_perm:[1,0,3,2] row_mask:0xf bank_mask:0xf bound_ctrl:1
	v_add_f32_dpp v169, v169, v169 quad_perm:[1,0,3,2] row_mask:0xf bank_mask:0xf bound_ctrl:1
	s_nop 0
	v_add_f32_dpp v168, v168, v168 quad_perm:[2,3,0,1] row_mask:0xf bank_mask:0xf bound_ctrl:1
	v_add_f32_dpp v169, v169, v169 quad_perm:[2,3,0,1] row_mask:0xf bank_mask:0xf bound_ctrl:1
	s_and_saveexec_b64 s[34:35], s[8:9]
	ds_write_b64 v75, v[168:169] offset:1280
	s_or_b64 exec, exec, s[34:35]
	s_waitcnt lgkmcnt(15)
; #define LAS __attribute__((address_space(3)))
; __device__ __forceinline__ float red4(float x) { x = DPP_ADD(x, 0xB1); x = DPP_ADD(x, 0x4E); return x; }
; __device__ __forceinline__ void phase_scan(const ScanArgs A, LAS unsigned char* lds) {
;     ...
;                 for (int t = 0; t < 16; ++t) {
;                     const LAS float* q = in + t * 64 + kq * 16;
;                     f32x4 Wv[4], KDv[4], Bv[4], ANv[4], Rv[4];
; #pragma unroll
;                     for (int j = 0; j < 4; ++j) { Wv[j] = *(const LAS f32x4*)(q + 4 * j); KDv[j] = *(const LAS f32x4*)(q + 1024 + 4 * j); Bv[j] = *(const LAS f32x4*)(q + 2048 + 4 * j);
;                                                   ANv[j] = *(const LAS f32x4*)(q + 3072 + 4 * j); Rv[j] = *(const LAS f32x4*)(q + 4096 + 4 * j); }
;                     const f32x2 v2 = *(const LAS f32x2*)(in + 5120 + t * 64 + half * 32 + rb * 2);
;     ...
;                     float sa[2], y[2];
; #pragma unroll
;                     for (int i = 0; i < 2; ++i) { f32x2 a0 = {0.f, 0.f}, a1 = {0.f, 0.f};
; #pragma unroll
;                         for (int p = 0; p < 8; p += 2) { a0 += S2[i][p] * PAIR(ANv, p); a1 += S2[i][p + 1] * PAIR(ANv, p + 1); }
;                         a0 += a1; sa[i] = red4(a0[0] + a0[1]); }
; #pragma unroll
;                     for (int i = 0; i < 2; ++i) { f32x2 y0 = {0.f, 0.f}, y1 = {0.f, 0.f}; const f32x2 sai = {sa[i], sa[i]}, vi = {v2[i], v2[i]};
; #pragma unroll
;                         for (int p = 0; p < 8; p += 2) {
;                             const f32x2 n0 = S2[i][p] * PAIR(Wv, p) + sai * PAIR(Bv, p) + vi * PAIR(KDv, p);
;                             const f32x2 n1 = S2[i][p + 1] * PAIR(Wv, p + 1) + sai * PAIR(Bv, p + 1) + vi * PAIR(KDv, p + 1);
;                             S2[i][p] = n0; S2[i][p + 1] = n1; y0 += n0 * PAIR(Rv, p); y1 += n1 * PAIR(Rv, p + 1); }
;                         y0 += y1; y[i] = red4(y0[0] + y0[1]); }
	v_pk_fma_f32 v[160:161], v[84:85], v[32:33], 0 op_sel_hi:[1,1,0]
	v_pk_fma_f32 v[162:163], v[88:89], v[34:35], 0 op_sel_hi:[1,1,0]
	v_pk_fma_f32 v[164:165], v[100:101], v[32:33], 0 op_sel_hi:[1,1,0]
	v_pk_fma_f32 v[166:167], v[104:105], v[34:35], 0 op_sel_hi:[1,1,0]
	v_pk_fma_f32 v[160:161], v[86:87], v[36:37], v[160:161]
	v_pk_fma_f32 v[162:163], v[92:93], v[38:39], v[162:163]
	v_pk_fma_f32 v[164:165], v[106:107], v[36:37], v[164:165]
	v_pk_fma_f32 v[166:167], v[108:109], v[38:39], v[166:167]
	v_pk_fma_f32 v[160:161], v[90:91], v[40:41], v[160:161]
	v_pk_fma_f32 v[162:163], v[98:99], v[42:43], v[162:163]
	v_pk_fma_f32 v[164:165], v[110:111], v[40:41], v[164:165]
	v_pk_fma_f32 v[166:167], v[112:113], v[42:43], v[166:167]
	v_pk_fma_f32 v[160:161], v[94:95], v[44:45], v[160:161]
	v_pk_fma_f32 v[162:163], v[102:103], v[46:47], v[162:163]
	v_pk_fma_f32 v[164:165], v[114:115], v[44:45], v[164:165]
	v_pk_fma_f32 v[166:167], v[116:117], v[46:47], v[166:167]
	ds_read_b128 v[32:35], v171 offset:14080
	ds_read_b128 v[36:39], v171 offset:14096
	ds_read_b128 v[40:43], v171 offset:14112
	ds_read_b128 v[44:47], v171 offset:14128
	v_pk_add_f32 v[160:161], v[162:163], v[160:161]
	v_pk_add_f32 v[164:165], v[166:167], v[164:165]
	v_add_f32_e32 v168, v160, v161
	v_add_f32_e32 v169, v164, v165
	s_nop 0
	v_add_f32_dpp v168, v168, v168 quad_perm:[1,0,3,2] row_mask:0xf bank_mask:0xf bound_ctrl:1
	v_add_f32_dpp v169, v169, v169 quad_perm:[1,0,3,2] row_mask:0xf bank_mask:0xf bound_ctrl:1
	s_nop 0
	v_add_f32_dpp v190, v168, v168 quad_perm:[2,3,0,1] row_mask:0xf bank_mask:0xf bound_ctrl:1
	v_add_f32_dpp v192, v169, v169 quad_perm:[2,3,0,1] row_mask:0xf bank_mask:0xf bound_ctrl:1
	s_waitcnt lgkmcnt(9)
	v_pk_mul_f32 v[216:217], v[142:143], v[190:191] op_sel_hi:[1,0]
	v_pk_mul_f32 v[218:219], v[144:145], v[190:191] op_sel_hi:[1,0]
	v_pk_mul_f32 v[232:233], v[142:143], v[192:193] op_sel_hi:[1,0]
	v_pk_mul_f32 v[234:235], v[144:145], v[192:193] op_sel_hi:[1,0]
	v_pk_fma_f32 v[216:217], v[84:85], v[48:49], v[216:217]
	v_pk_fma_f32 v[218:219], v[88:89], v[50:51], v[218:219]
	v_pk_fma_f32 v[232:233], v[100:101], v[48:49], v[232:233]
	v_pk_fma_f32 v[234:235], v[104:105], v[50:51], v[234:235]
	v_pk_fma_f32 v[84:85], v[172:173], v[188:189], v[216:217] op_sel_hi:[1,0,1]
	v_pk_fma_f32 v[88:89], v[174:175], v[188:189], v[218:219] op_sel_hi:[1,0,1]
	v_pk_fma_f32 v[100:101], v[172:173], v[188:189], v[232:233] op_sel:[0,1,0]
	v_pk_fma_f32 v[104:105], v[174:175], v[188:189], v[234:235] op_sel:[0,1,0]
	ds_read_b128 v[142:145], v171 offset:9984
	ds_read_b128 v[48:51], v171 offset:1792
	ds_read_b128 v[172:175], v171 offset:5888
	v_pk_mul_f32 v[220:221], v[146:147], v[190:191] op_sel_hi:[1,0]
	v_pk_mul_f32 v[222:223], v[148:149], v[190:191] op_sel_hi:[1,0]
	v_pk_mul_f32 v[236:237], v[146:147], v[192:193] op_sel_hi:[1,0]
	v_pk_mul_f32 v[238:239], v[148:149], v[192:193] op_sel_hi:[1,0]
	v_pk_fma_f32 v[220:221], v[86:87], v[52:53], v[220:221]
	v_pk_fma_f32 v[222:223], v[92:93], v[54:55], v[222:223]
	v_pk_fma_f32 v[236:237], v[106:107], v[52:53], v[236:237]
	v_pk_fma_f32 v[238:239], v[108:109], v[54:55], v[238:239]
	v_pk_fma_f32 v[86:87], v[176:177], v[188:189], v[220:221] op_sel_hi:[1,0,1]
	v_pk_fma_f32 v[92:93], v[178:179], v[188:189], v[222:223] op_sel_hi:[1,0,1]
	v_pk_fma_f32 v[106:107], v[176:177], v[188:189], v[236:237] op_sel:[0,1,0]
	v_pk_fma_f32 v[108:109], v[178:179], v[188:189], v[238:239] op_sel:[0,1,0]
	ds_read_b128 v[146:149], v171 offset:10000
	ds_read_b128 v[52:55], v171 offset:1808
	ds_read_b128 v[176:179], v171 offset:5904
	v_pk_mul_f32 v[224:225], v[150:151], v[190:191] op_sel_hi:[1,0]
	v_pk_mul_f32 v[226:227], v[152:153], v[190:191] op_sel_hi:[1,0]
	v_pk_mul_f32 v[240:241], v[150:151], v[192:193] op_sel_hi:[1,0]
	v_pk_mul_f32 v[242:243], v[152:153], v[192:193] op_sel_hi:[1,0]
	v_pk_fma_f32 v[224:225], v[90:91], v[56:57], v[224:225]
	v_pk_fma_f32 v[226:227], v[98:99], v[58:59], v[226:227]
	v_pk_fma_f32 v[240:241], v[110:111], v[56:57], v[240:241]
	v_pk_fma_f32 v[242:243], v[112:113], v[58:59], v[242:243]
	v_pk_fma_f32 v[90:91], v[180:181], v[188:189], v[224:225] op_sel_hi:[1,0,1]
	v_pk_fma_f32 v[98:99], v[182:183], v[188:189], v[226:227] op_sel_hi:[1,0,1]
	v_pk_fma_f32 v[110:111], v[180:181], v[188:189], v[240:241] op_sel:[0,1,0]
	v_pk_fma_f32 v[112:113], v[182:183], v[188:189], v[242:243] op_sel:[0,1,0]
	ds_read_b128 v[150:153], v171 offset:10016
	ds_read_b128 v[56:59], v171 offset:1824
	ds_read_b128 v[180:183], v171 offset:5920
	v_pk_mul_f32 v[228:229], v[154:155], v[190:191] op_sel_hi:[1,0]
	v_pk_mul_f32 v[230:231], v[156:157], v[190:191] op_sel_hi:[1,0]
	v_pk_mul_f32 v[244:245], v[154:155], v[192:193] op_sel_hi:[1,0]
	v_pk_mul_f32 v[246:247], v[156:157], v[192:193] op_sel_hi:[1,0]
	v_pk_fma_f32 v[228:229], v[94:95], v[60:61], v[228:229]
	v_pk_fma_f32 v[230:231], v[102:103], v[62:63], v[230:231]
	v_pk_fma_f32 v[244:245], v[114:115], v[60:61], v[244:245]
	v_pk_fma_f32 v[246:247], v[116:117], v[62:63], v[246:247]
	v_pk_fma_f32 v[94:95], v[184:185], v[188:189], v[228:229] op_sel_hi:[1,0,1]
	v_pk_fma_f32 v[102:103], v[186:187], v[188:189], v[230:231] op_sel_hi:[1,0,1]
	v_pk_fma_f32 v[114:115], v[184:185], v[188:189], v[244:245] op_sel:[0,1,0]
	v_pk_fma_f32 v[116:117], v[186:187], v[188:189], v[246:247] op_sel:[0,1,0]
	ds_read_b128 v[154:157], v171 offset:10032
	ds_read_b128 v[60:63], v171 offset:1840
	ds_read_b128 v[184:187], v171 offset:5936
	ds_read_b64 v[188:189], v96 offset:1792
	s_waitcnt lgkmcnt(15)
; #define LAS __attribute__((address_space(3)))
; __device__ __forceinline__ float red4(float x) { x = DPP_ADD(x, 0xB1); x = DPP_ADD(x, 0x4E); return x; }
; __device__ __forceinline__ void phase_scan(const ScanArgs A, LAS unsigned char* lds) {
;     ...
;                 for (int t = 0; t < 16; ++t) {
;                     const LAS float* q = in + t * 64 + kq * 16;
;                     f32x4 Wv[4], KDv[4], Bv[4], ANv[4], Rv[4];
; #pragma unroll
;                     for (int j = 0; j < 4; ++j) { Wv[j] = *(const LAS f32x4*)(q + 4 * j); KDv[j] = *(const LAS f32x4*)(q + 1024 + 4 * j); Bv[j] = *(const LAS f32x4*)(q + 2048 + 4 * j);
;                                                   ANv[j] = *(const LAS f32x4*)(q + 3072 + 4 * j); Rv[j] = *(const LAS f32x4*)(q + 4096 + 4 * j); }
;                     const f32x2 v2 = *(const LAS f32x2*)(in + 5120 + t * 64 + half * 32 + rb * 2);
;     ...
;                     float sa[2], y[2];
; #pragma unroll
;                     for (int i = 0; i < 2; ++i) { f32x2 a0 = {0.f, 0.f}, a1 = {0.f, 0.f};
; #pragma unroll
;                         for (int p = 0; p < 8; p += 2) { a0 += S2[i][p] * PAIR(ANv, p); a1 += S2[i][p + 1] * PAIR(ANv, p + 1); }
;                         a0 += a1; sa[i] = red4(a0[0] + a0[1]); }
;     ...
;                     for (int i = 0; i < 2; ++i) { f32x2 y0 = {0.f, 0.f}, y1 = {0.f, 0.f}; const f32x2 sai = {sa[i], sa[i]}, vi = {v2[i], v2[i]};
; #pragma unroll
;                         for (int p = 0; p < 8; p += 2) {
;                             const f32x2 n0 = S2[i][p] * PAIR(Wv, p) + sai * PAIR(Bv, p) + vi * PAIR(KDv, p);
;                             const f32x2 n1 = S2[i][p + 1] * PAIR(Wv, p + 1) + sai * PAIR(Bv, p + 1) + vi * PAIR(KDv, p + 1);
;                             S2[i][p] = n0; S2[i][p + 1] = n1; y0 += n0 * PAIR(Rv, p); y1 += n1 * PAIR(Rv, p + 1); }
;                         y0 += y1; y[i] = red4(y0[0] + y0[1]); }
;     ...
;                     if (kq == 0) *(LAS f32x2*)(yb + t * 64 + half * 32 + rb * 2) = (f32x2){y[0], y[1]};
	v_pk_fma_f32 v[248:249], v[200:201], v[84:85], 0 op_sel_hi:[1,1,0]
	v_pk_fma_f32 v[250:251], v[202:203], v[88:89], 0 op_sel_hi:[1,1,0]
	v_pk_fma_f32 v[194:195], v[200:201], v[100:101], 0 op_sel_hi:[1,1,0]
	v_pk_fma_f32 v[158:159], v[202:203], v[104:105], 0 op_sel_hi:[1,1,0]
	v_pk_fma_f32 v[248:249], v[204:205], v[86:87], v[248:249]
	v_pk_fma_f32 v[250:251], v[206:207], v[92:93], v[250:251]
	v_pk_fma_f32 v[194:195], v[204:205], v[106:107], v[194:195]
	v_pk_fma_f32 v[158:159], v[206:207], v[108:109], v[158:159]
	v_pk_fma_f32 v[248:249], v[208:209], v[90:91], v[248:249]
	v_pk_fma_f32 v[250:251], v[210:211], v[98:99], v[250:251]
	v_pk_fma_f32 v[194:195], v[208:209], v[110:111], v[194:195]
	v_pk_fma_f32 v[158:159], v[210:211], v[112:113], v[158:159]
	v_pk_fma_f32 v[248:249], v[212:213], v[94:95], v[248:249]
	v_pk_fma_f32 v[250:251], v[214:215], v[102:103], v[250:251]
	v_pk_fma_f32 v[194:195], v[212:213], v[114:115], v[194:195]
	v_pk_fma_f32 v[158:159], v[214:215], v[116:117], v[158:159]
	ds_read_b128 v[200:203], v171 offset:18176
	ds_read_b128 v[204:207], v171 offset:18192
	ds_read_b128 v[208:211], v171 offset:18208
	ds_read_b128 v[212:215], v171 offset:18224
	v_pk_add_f32 v[248:249], v[250:251], v[248:249]
	v_pk_add_f32 v[194:195], v[158:159], v[194:195]
	v_add_f32_e32 v168, v248, v249
	v_add_f32_e32 v169, v194, v195
	s_nop 0
	v_add_f32_dpp v168, v168, v168 quad_perm:[1,0,3,2] row_mask:0xf bank_mask:0xf bound_ctrl:1
	v_add_f32_dpp v169, v169, v169 quad_perm:[1,0,3,2] row_mask:0xf bank_mask:0xf bound_ctrl:1
	s_nop 0
	v_add_f32_dpp v168, v168, v168 quad_perm:[2,3,0,1] row_mask:0xf bank_mask:0xf bound_ctrl:1
	v_add_f32_dpp v169, v169, v169 quad_perm:[2,3,0,1] row_mask:0xf bank_mask:0xf bound_ctrl:1
	s_and_saveexec_b64 s[34:35], s[8:9]
	ds_write_b64 v75, v[168:169] offset:1536
	s_or_b64 exec, exec, s[34:35]
	s_waitcnt lgkmcnt(15)
	v_pk_fma_f32 v[160:161], v[84:85], v[32:33], 0 op_sel_hi:[1,1,0]
	v_pk_fma_f32 v[162:163], v[88:89], v[34:35], 0 op_sel_hi:[1,1,0]
	v_pk_fma_f32 v[164:165], v[100:101], v[32:33], 0 op_sel_hi:[1,1,0]
	v_pk_fma_f32 v[166:167], v[104:105], v[34:35], 0 op_sel_hi:[1,1,0]
	v_pk_fma_f32 v[160:161], v[86:87], v[36:37], v[160:161]
	v_pk_fma_f32 v[162:163], v[92:93], v[38:39], v[162:163]
	v_pk_fma_f32 v[164:165], v[106:107], v[36:37], v[164:165]
	v_pk_fma_f32 v[166:167], v[108:109], v[38:39], v[166:167]
	v_pk_fma_f32 v[160:161], v[90:91], v[40:41], v[160:161]
	v_pk_fma_f32 v[162:163], v[98:99], v[42:43], v[162:163]
	v_pk_fma_f32 v[164:165], v[110:111], v[40:41], v[164:165]
	v_pk_fma_f32 v[166:167], v[112:113], v[42:43], v[166:167]
	v_pk_fma_f32 v[160:161], v[94:95], v[44:45], v[160:161]
	v_pk_fma_f32 v[162:163], v[102:103], v[46:47], v[162:163]
	v_pk_fma_f32 v[164:165], v[114:115], v[44:45], v[164:165]
	v_pk_fma_f32 v[166:167], v[116:117], v[46:47], v[166:167]
	ds_read_b128 v[32:35], v171 offset:14336
	ds_read_b128 v[36:39], v171 offset:14352
	ds_read_b128 v[40:43], v171 offset:14368
	ds_read_b128 v[44:47], v171 offset:14384
	v_pk_add_f32 v[160:161], v[162:163], v[160:161]
	v_pk_add_f32 v[164:165], v[166:167], v[164:165]
	v_add_f32_e32 v168, v160, v161
	v_add_f32_e32 v169, v164, v165
	s_nop 0
	v_add_f32_dpp v168, v168, v168 quad_perm:[1,0,3,2] row_mask:0xf bank_mask:0xf bound_ctrl:1
	v_add_f32_dpp v169, v169, v169 quad_perm:[1,0,3,2] row_mask:0xf bank_mask:0xf bound_ctrl:1
	s_nop 0
	v_add_f32_dpp v190, v168, v168 quad_perm:[2,3,0,1] row_mask:0xf bank_mask:0xf bound_ctrl:1
	v_add_f32_dpp v192, v169, v169 quad_perm:[2,3,0,1] row_mask:0xf bank_mask:0xf bound_ctrl:1
	s_waitcnt lgkmcnt(9)
	v_pk_mul_f32 v[216:217], v[142:143], v[190:191] op_sel_hi:[1,0]
	v_pk_mul_f32 v[218:219], v[144:145], v[190:191] op_sel_hi:[1,0]
	v_pk_mul_f32 v[232:233], v[142:143], v[192:193] op_sel_hi:[1,0]
	v_pk_mul_f32 v[234:235], v[144:145], v[192:193] op_sel_hi:[1,0]
	v_pk_fma_f32 v[216:217], v[84:85], v[48:49], v[216:217]
	v_pk_fma_f32 v[218:219], v[88:89], v[50:51], v[218:219]
	v_pk_fma_f32 v[232:233], v[100:101], v[48:49], v[232:233]
	v_pk_fma_f32 v[234:235], v[104:105], v[50:51], v[234:235]
	v_pk_fma_f32 v[84:85], v[172:173], v[188:189], v[216:217] op_sel_hi:[1,0,1]
	v_pk_fma_f32 v[88:89], v[174:175], v[188:189], v[218:219] op_sel_hi:[1,0,1]
	v_pk_fma_f32 v[100:101], v[172:173], v[188:189], v[232:233] op_sel:[0,1,0]
	v_pk_fma_f32 v[104:105], v[174:175], v[188:189], v[234:235] op_sel:[0,1,0]
	ds_read_b128 v[142:145], v171 offset:10240
	ds_read_b128 v[48:51], v171 offset:2048
	ds_read_b128 v[172:175], v171 offset:6144
	v_pk_mul_f32 v[220:221], v[146:147], v[190:191] op_sel_hi:[1,0]
	v_pk_mul_f32 v[222:223], v[148:149], v[190:191] op_sel_hi:[1,0]
	v_pk_mul_f32 v[236:237], v[146:147], v[192:193] op_sel_hi:[1,0]
	v_pk_mul_f32 v[238:239], v[148:149], v[192:193] op_sel_hi:[1,0]
	v_pk_fma_f32 v[220:221], v[86:87], v[52:53], v[220:221]
	v_pk_fma_f32 v[222:223], v[92:93], v[54:55], v[222:223]
	v_pk_fma_f32 v[236:237], v[106:107], v[52:53], v[236:237]
	v_pk_fma_f32 v[238:239], v[108:109], v[54:55], v[238:239]
	v_pk_fma_f32 v[86:87], v[176:177], v[188:189], v[220:221] op_sel_hi:[1,0,1]
	v_pk_fma_f32 v[92:93], v[178:179], v[188:189], v[222:223] op_sel_hi:[1,0,1]
	v_pk_fma_f32 v[106:107], v[176:177], v[188:189], v[236:237] op_sel:[0,1,0]
	v_pk_fma_f32 v[108:109], v[178:179], v[188:189], v[238:239] op_sel:[0,1,0]
	ds_read_b128 v[146:149], v171 offset:10256
	ds_read_b128 v[52:55], v171 offset:2064
	ds_read_b128 v[176:179], v171 offset:6160
	v_pk_mul_f32 v[224:225], v[150:151], v[190:191] op_sel_hi:[1,0]
	v_pk_mul_f32 v[226:227], v[152:153], v[190:191] op_sel_hi:[1,0]
	v_pk_mul_f32 v[240:241], v[150:151], v[192:193] op_sel_hi:[1,0]
	v_pk_mul_f32 v[242:243], v[152:153], v[192:193] op_sel_hi:[1,0]
; #define LAS __attribute__((address_space(3)))
; __device__ __forceinline__ float red4(float x) { x = DPP_ADD(x, 0xB1); x = DPP_ADD(x, 0x4E); return x; }
; __device__ __forceinline__ void phase_scan(const ScanArgs A, LAS unsigned char* lds) {
;     ...
;                 for (int t = 0; t < 16; ++t) {
;                     const LAS float* q = in + t * 64 + kq * 16;
;                     f32x4 Wv[4], KDv[4], Bv[4], ANv[4], Rv[4];
; #pragma unroll
;                     for (int j = 0; j < 4; ++j) { Wv[j] = *(const LAS f32x4*)(q + 4 * j); KDv[j] = *(const LAS f32x4*)(q + 1024 + 4 * j); Bv[j] = *(const LAS f32x4*)(q + 2048 + 4 * j);
;                                                   ANv[j] = *(const LAS f32x4*)(q + 3072 + 4 * j); Rv[j] = *(const LAS f32x4*)(q + 4096 + 4 * j); }
;                     const f32x2 v2 = *(const LAS f32x2*)(in + 5120 + t * 64 + half * 32 + rb * 2);
;     ...
;                     float sa[2], y[2];
; #pragma unroll
;                     for (int i = 0; i < 2; ++i) { f32x2 a0 = {0.f, 0.f}, a1 = {0.f, 0.f};
; #pragma unroll
;                         for (int p = 0; p < 8; p += 2) { a0 += S2[i][p] * PAIR(ANv, p); a1 += S2[i][p + 1] * PAIR(ANv, p + 1); }
;                         a0 += a1; sa[i] = red4(a0[0] + a0[1]); }
;     ...
;                     for (int i = 0; i < 2; ++i) { f32x2 y0 = {0.f, 0.f}, y1 = {0.f, 0.f}; const f32x2 sai = {sa[i], sa[i]}, vi = {v2[i], v2[i]};
; #pragma unroll
;                         for (int p = 0; p < 8; p += 2) {
;                             const f32x2 n0 = S2[i][p] * PAIR(Wv, p) + sai * PAIR(Bv, p) + vi * PAIR(KDv, p);
;                             const f32x2 n1 = S2[i][p + 1] * PAIR(Wv, p + 1) + sai * PAIR(Bv, p + 1) + vi * PAIR(KDv, p + 1);
;                             S2[i][p] = n0; S2[i][p + 1] = n1; y0 += n0 * PAIR(Rv, p); y1 += n1 * PAIR(Rv, p + 1); }
;                         y0 += y1; y[i] = red4(y0[0] + y0[1]); }
;     ...
;                     if (kq == 0) *(LAS f32x2*)(yb + t * 64 + half * 32 + rb * 2) = (f32x2){y[0], y[1]};
	v_pk_fma_f32 v[224:225], v[90:91], v[56:57], v[224:225]
	v_pk_fma_f32 v[226:227], v[98:99], v[58:59], v[226:227]
	v_pk_fma_f32 v[240:241], v[110:111], v[56:57], v[240:241]
	v_pk_fma_f32 v[242:243], v[112:113], v[58:59], v[242:243]
	v_pk_fma_f32 v[90:91], v[180:181], v[188:189], v[224:225] op_sel_hi:[1,0,1]
	v_pk_fma_f32 v[98:99], v[182:183], v[188:189], v[226:227] op_sel_hi:[1,0,1]
	v_pk_fma_f32 v[110:111], v[180:181], v[188:189], v[240:241] op_sel:[0,1,0]
	v_pk_fma_f32 v[112:113], v[182:183], v[188:189], v[242:243] op_sel:[0,1,0]
	ds_read_b128 v[150:153], v171 offset:10272
	ds_read_b128 v[56:59], v171 offset:2080
	ds_read_b128 v[180:183], v171 offset:6176
	v_pk_mul_f32 v[228:229], v[154:155], v[190:191] op_sel_hi:[1,0]
	v_pk_mul_f32 v[230:231], v[156:157], v[190:191] op_sel_hi:[1,0]
	v_pk_mul_f32 v[244:245], v[154:155], v[192:193] op_sel_hi:[1,0]
	v_pk_mul_f32 v[246:247], v[156:157], v[192:193] op_sel_hi:[1,0]
	v_pk_fma_f32 v[228:229], v[94:95], v[60:61], v[228:229]
	v_pk_fma_f32 v[230:231], v[102:103], v[62:63], v[230:231]
	v_pk_fma_f32 v[244:245], v[114:115], v[60:61], v[244:245]
	v_pk_fma_f32 v[246:247], v[116:117], v[62:63], v[246:247]
	v_pk_fma_f32 v[94:95], v[184:185], v[188:189], v[228:229] op_sel_hi:[1,0,1]
	v_pk_fma_f32 v[102:103], v[186:187], v[188:189], v[230:231] op_sel_hi:[1,0,1]
	v_pk_fma_f32 v[114:115], v[184:185], v[188:189], v[244:245] op_sel:[0,1,0]
	v_pk_fma_f32 v[116:117], v[186:187], v[188:189], v[246:247] op_sel:[0,1,0]
	ds_read_b128 v[154:157], v171 offset:10288
	ds_read_b128 v[60:63], v171 offset:2096
	ds_read_b128 v[184:187], v171 offset:6192
	ds_read_b64 v[188:189], v96 offset:2048
	s_waitcnt lgkmcnt(15)
	v_pk_fma_f32 v[248:249], v[200:201], v[84:85], 0 op_sel_hi:[1,1,0]
	v_pk_fma_f32 v[250:251], v[202:203], v[88:89], 0 op_sel_hi:[1,1,0]
	v_pk_fma_f32 v[194:195], v[200:201], v[100:101], 0 op_sel_hi:[1,1,0]
	v_pk_fma_f32 v[158:159], v[202:203], v[104:105], 0 op_sel_hi:[1,1,0]
	v_pk_fma_f32 v[248:249], v[204:205], v[86:87], v[248:249]
	v_pk_fma_f32 v[250:251], v[206:207], v[92:93], v[250:251]
	v_pk_fma_f32 v[194:195], v[204:205], v[106:107], v[194:195]
	v_pk_fma_f32 v[158:159], v[206:207], v[108:109], v[158:159]
	v_pk_fma_f32 v[248:249], v[208:209], v[90:91], v[248:249]
	v_pk_fma_f32 v[250:251], v[210:211], v[98:99], v[250:251]
	v_pk_fma_f32 v[194:195], v[208:209], v[110:111], v[194:195]
	v_pk_fma_f32 v[158:159], v[210:211], v[112:113], v[158:159]
	v_pk_fma_f32 v[248:249], v[212:213], v[94:95], v[248:249]
	v_pk_fma_f32 v[250:251], v[214:215], v[102:103], v[250:251]
	v_pk_fma_f32 v[194:195], v[212:213], v[114:115], v[194:195]
	v_pk_fma_f32 v[158:159], v[214:215], v[116:117], v[158:159]
	ds_read_b128 v[200:203], v171 offset:18432
	ds_read_b128 v[204:207], v171 offset:18448
	ds_read_b128 v[208:211], v171 offset:18464
	ds_read_b128 v[212:215], v171 offset:18480
	v_pk_add_f32 v[248:249], v[250:251], v[248:249]
	v_pk_add_f32 v[194:195], v[158:159], v[194:195]
	v_add_f32_e32 v168, v248, v249
	v_add_f32_e32 v169, v194, v195
	s_nop 0
	v_add_f32_dpp v168, v168, v168 quad_perm:[1,0,3,2] row_mask:0xf bank_mask:0xf bound_ctrl:1
	v_add_f32_dpp v169, v169, v169 quad_perm:[1,0,3,2] row_mask:0xf bank_mask:0xf bound_ctrl:1
	s_nop 0
	v_add_f32_dpp v168, v168, v168 quad_perm:[2,3,0,1] row_mask:0xf bank_mask:0xf bound_ctrl:1
	v_add_f32_dpp v169, v169, v169 quad_perm:[2,3,0,1] row_mask:0xf bank_mask:0xf bound_ctrl:1
	s_and_saveexec_b64 s[34:35], s[8:9]
	ds_write_b64 v75, v[168:169] offset:1792
	s_or_b64 exec, exec, s[34:35]
	s_waitcnt lgkmcnt(15)
	v_pk_fma_f32 v[160:161], v[84:85], v[32:33], 0 op_sel_hi:[1,1,0]
	v_pk_fma_f32 v[162:163], v[88:89], v[34:35], 0 op_sel_hi:[1,1,0]
	v_pk_fma_f32 v[164:165], v[100:101], v[32:33], 0 op_sel_hi:[1,1,0]
	v_pk_fma_f32 v[166:167], v[104:105], v[34:35], 0 op_sel_hi:[1,1,0]
	v_pk_fma_f32 v[160:161], v[86:87], v[36:37], v[160:161]
	v_pk_fma_f32 v[162:163], v[92:93], v[38:39], v[162:163]
	v_pk_fma_f32 v[164:165], v[106:107], v[36:37], v[164:165]
	v_pk_fma_f32 v[166:167], v[108:109], v[38:39], v[166:167]
	v_pk_fma_f32 v[160:161], v[90:91], v[40:41], v[160:161]
	v_pk_fma_f32 v[162:163], v[98:99], v[42:43], v[162:163]
	v_pk_fma_f32 v[164:165], v[110:111], v[40:41], v[164:165]
	v_pk_fma_f32 v[166:167], v[112:113], v[42:43], v[166:167]
	v_pk_fma_f32 v[160:161], v[94:95], v[44:45], v[160:161]
	v_pk_fma_f32 v[162:163], v[102:103], v[46:47], v[162:163]
	v_pk_fma_f32 v[164:165], v[114:115], v[44:45], v[164:165]
	v_pk_fma_f32 v[166:167], v[116:117], v[46:47], v[166:167]
	ds_read_b128 v[32:35], v171 offset:14592
	ds_read_b128 v[36:39], v171 offset:14608
	ds_read_b128 v[40:43], v171 offset:14624
	ds_read_b128 v[44:47], v171 offset:14640
	v_pk_add_f32 v[160:161], v[162:163], v[160:161]
	v_pk_add_f32 v[164:165], v[166:167], v[164:165]
	v_add_f32_e32 v168, v160, v161
	v_add_f32_e32 v169, v164, v165
	s_nop 0
	v_add_f32_dpp v168, v168, v168 quad_perm:[1,0,3,2] row_mask:0xf bank_mask:0xf bound_ctrl:1
	v_add_f32_dpp v169, v169, v169 quad_perm:[1,0,3,2] row_mask:0xf bank_mask:0xf bound_ctrl:1
	s_nop 0
	v_add_f32_dpp v190, v168, v168 quad_perm:[2,3,0,1] row_mask:0xf bank_mask:0xf bound_ctrl:1
	v_add_f32_dpp v192, v169, v169 quad_perm:[2,3,0,1] row_mask:0xf bank_mask:0xf bound_ctrl:1
	s_waitcnt lgkmcnt(9)
; #define LAS __attribute__((address_space(3)))
; __device__ __forceinline__ float red4(float x) { x = DPP_ADD(x, 0xB1); x = DPP_ADD(x, 0x4E); return x; }
; __device__ __forceinline__ void phase_scan(const ScanArgs A, LAS unsigned char* lds) {
;     ...
;                     for (int i = 0; i < 2; ++i) { f32x2 y0 = {0.f, 0.f}, y1 = {0.f, 0.f}; const f32x2 sai = {sa[i], sa[i]}, vi = {v2[i], v2[i]};
; #pragma unroll
;                         for (int p = 0; p < 8; p += 2) {
;                             const f32x2 n0 = S2[i][p] * PAIR(Wv, p) + sai * PAIR(Bv, p) + vi * PAIR(KDv, p);
;                             const f32x2 n1 = S2[i][p + 1] * PAIR(Wv, p + 1) + sai * PAIR(Bv, p + 1) + vi * PAIR(KDv, p + 1);
;                             S2[i][p] = n0; S2[i][p + 1] = n1; y0 += n0 * PAIR(Rv, p); y1 += n1 * PAIR(Rv, p + 1); }
;                         y0 += y1; y[i] = red4(y0[0] + y0[1]); }
;     ...
;                     if (kq == 0) *(LAS f32x2*)(yb + t * 64 + half * 32 + rb * 2) = (f32x2){y[0], y[1]};
	v_pk_mul_f32 v[216:217], v[142:143], v[190:191] op_sel_hi:[1,0]
	v_pk_mul_f32 v[218:219], v[144:145], v[190:191] op_sel_hi:[1,0]
	v_pk_mul_f32 v[232:233], v[142:143], v[192:193] op_sel_hi:[1,0]
	v_pk_mul_f32 v[234:235], v[144:145], v[192:193] op_sel_hi:[1,0]
	v_pk_fma_f32 v[216:217], v[84:85], v[48:49], v[216:217]
	v_pk_fma_f32 v[218:219], v[88:89], v[50:51], v[218:219]
	v_pk_fma_f32 v[232:233], v[100:101], v[48:49], v[232:233]
	v_pk_fma_f32 v[234:235], v[104:105], v[50:51], v[234:235]
	v_pk_fma_f32 v[84:85], v[172:173], v[188:189], v[216:217] op_sel_hi:[1,0,1]
	v_pk_fma_f32 v[88:89], v[174:175], v[188:189], v[218:219] op_sel_hi:[1,0,1]
	v_pk_fma_f32 v[100:101], v[172:173], v[188:189], v[232:233] op_sel:[0,1,0]
	v_pk_fma_f32 v[104:105], v[174:175], v[188:189], v[234:235] op_sel:[0,1,0]
	ds_read_b128 v[142:145], v171 offset:10496
	ds_read_b128 v[48:51], v171 offset:2304
	ds_read_b128 v[172:175], v171 offset:6400
	v_pk_mul_f32 v[220:221], v[146:147], v[190:191] op_sel_hi:[1,0]
	v_pk_mul_f32 v[222:223], v[148:149], v[190:191] op_sel_hi:[1,0]
	v_pk_mul_f32 v[236:237], v[146:147], v[192:193] op_sel_hi:[1,0]
	v_pk_mul_f32 v[238:239], v[148:149], v[192:193] op_sel_hi:[1,0]
	v_pk_fma_f32 v[220:221], v[86:87], v[52:53], v[220:221]
	v_pk_fma_f32 v[222:223], v[92:93], v[54:55], v[222:223]
	v_pk_fma_f32 v[236:237], v[106:107], v[52:53], v[236:237]
	v_pk_fma_f32 v[238:239], v[108:109], v[54:55], v[238:239]
	v_pk_fma_f32 v[86:87], v[176:177], v[188:189], v[220:221] op_sel_hi:[1,0,1]
	v_pk_fma_f32 v[92:93], v[178:179], v[188:189], v[222:223] op_sel_hi:[1,0,1]
	v_pk_fma_f32 v[106:107], v[176:177], v[188:189], v[236:237] op_sel:[0,1,0]
	v_pk_fma_f32 v[108:109], v[178:179], v[188:189], v[238:239] op_sel:[0,1,0]
	ds_read_b128 v[146:149], v171 offset:10512
	ds_read_b128 v[52:55], v171 offset:2320
	ds_read_b128 v[176:179], v171 offset:6416
	v_pk_mul_f32 v[224:225], v[150:151], v[190:191] op_sel_hi:[1,0]
	v_pk_mul_f32 v[226:227], v[152:153], v[190:191] op_sel_hi:[1,0]
	v_pk_mul_f32 v[240:241], v[150:151], v[192:193] op_sel_hi:[1,0]
	v_pk_mul_f32 v[242:243], v[152:153], v[192:193] op_sel_hi:[1,0]
	v_pk_fma_f32 v[224:225], v[90:91], v[56:57], v[224:225]
	v_pk_fma_f32 v[226:227], v[98:99], v[58:59], v[226:227]
	v_pk_fma_f32 v[240:241], v[110:111], v[56:57], v[240:241]
	v_pk_fma_f32 v[242:243], v[112:113], v[58:59], v[242:243]
	v_pk_fma_f32 v[90:91], v[180:181], v[188:189], v[224:225] op_sel_hi:[1,0,1]
	v_pk_fma_f32 v[98:99], v[182:183], v[188:189], v[226:227] op_sel_hi:[1,0,1]
	v_pk_fma_f32 v[110:111], v[180:181], v[188:189], v[240:241] op_sel:[0,1,0]
	v_pk_fma_f32 v[112:113], v[182:183], v[188:189], v[242:243] op_sel:[0,1,0]
	ds_read_b128 v[150:153], v171 offset:10528
	ds_read_b128 v[56:59], v171 offset:2336
	ds_read_b128 v[180:183], v171 offset:6432
	v_pk_mul_f32 v[228:229], v[154:155], v[190:191] op_sel_hi:[1,0]
	v_pk_mul_f32 v[230:231], v[156:157], v[190:191] op_sel_hi:[1,0]
	v_pk_mul_f32 v[244:245], v[154:155], v[192:193] op_sel_hi:[1,0]
	v_pk_mul_f32 v[246:247], v[156:157], v[192:193] op_sel_hi:[1,0]
	v_pk_fma_f32 v[228:229], v[94:95], v[60:61], v[228:229]
	v_pk_fma_f32 v[230:231], v[102:103], v[62:63], v[230:231]
	v_pk_fma_f32 v[244:245], v[114:115], v[60:61], v[244:245]
	v_pk_fma_f32 v[246:247], v[116:117], v[62:63], v[246:247]
	v_pk_fma_f32 v[94:95], v[184:185], v[188:189], v[228:229] op_sel_hi:[1,0,1]
	v_pk_fma_f32 v[102:103], v[186:187], v[188:189], v[230:231] op_sel_hi:[1,0,1]
	v_pk_fma_f32 v[114:115], v[184:185], v[188:189], v[244:245] op_sel:[0,1,0]
	v_pk_fma_f32 v[116:117], v[186:187], v[188:189], v[246:247] op_sel:[0,1,0]
	ds_read_b128 v[154:157], v171 offset:10544
	ds_read_b128 v[60:63], v171 offset:2352
	ds_read_b128 v[184:187], v171 offset:6448
	ds_read_b64 v[188:189], v96 offset:2304
	s_waitcnt lgkmcnt(15)
	v_pk_fma_f32 v[248:249], v[200:201], v[84:85], 0 op_sel_hi:[1,1,0]
	v_pk_fma_f32 v[250:251], v[202:203], v[88:89], 0 op_sel_hi:[1,1,0]
	v_pk_fma_f32 v[194:195], v[200:201], v[100:101], 0 op_sel_hi:[1,1,0]
	v_pk_fma_f32 v[158:159], v[202:203], v[104:105], 0 op_sel_hi:[1,1,0]
	v_pk_fma_f32 v[248:249], v[204:205], v[86:87], v[248:249]
	v_pk_fma_f32 v[250:251], v[206:207], v[92:93], v[250:251]
	v_pk_fma_f32 v[194:195], v[204:205], v[106:107], v[194:195]
	v_pk_fma_f32 v[158:159], v[206:207], v[108:109], v[158:159]
	v_pk_fma_f32 v[248:249], v[208:209], v[90:91], v[248:249]
	v_pk_fma_f32 v[250:251], v[210:211], v[98:99], v[250:251]
	v_pk_fma_f32 v[194:195], v[208:209], v[110:111], v[194:195]
	v_pk_fma_f32 v[158:159], v[210:211], v[112:113], v[158:159]
	v_pk_fma_f32 v[248:249], v[212:213], v[94:95], v[248:249]
	v_pk_fma_f32 v[250:251], v[214:215], v[102:103], v[250:251]
	v_pk_fma_f32 v[194:195], v[212:213], v[114:115], v[194:195]
	v_pk_fma_f32 v[158:159], v[214:215], v[116:117], v[158:159]
	ds_read_b128 v[200:203], v171 offset:18688
	ds_read_b128 v[204:207], v171 offset:18704
	ds_read_b128 v[208:211], v171 offset:18720
	ds_read_b128 v[212:215], v171 offset:18736
	v_pk_add_f32 v[248:249], v[250:251], v[248:249]
	v_pk_add_f32 v[194:195], v[158:159], v[194:195]
	v_add_f32_e32 v168, v248, v249
	v_add_f32_e32 v169, v194, v195
	s_nop 0
	v_add_f32_dpp v168, v168, v168 quad_perm:[1,0,3,2] row_mask:0xf bank_mask:0xf bound_ctrl:1
	v_add_f32_dpp v169, v169, v169 quad_perm:[1,0,3,2] row_mask:0xf bank_mask:0xf bound_ctrl:1
	s_nop 0
	v_add_f32_dpp v168, v168, v168 quad_perm:[2,3,0,1] row_mask:0xf bank_mask:0xf bound_ctrl:1
	v_add_f32_dpp v169, v169, v169 quad_perm:[2,3,0,1] row_mask:0xf bank_mask:0xf bound_ctrl:1
	s_and_saveexec_b64 s[34:35], s[8:9]
	ds_write_b64 v75, v[168:169] offset:2048
	s_or_b64 exec, exec, s[34:35]
	s_waitcnt lgkmcnt(15)
; #define LAS __attribute__((address_space(3)))
; __device__ __forceinline__ float red4(float x) { x = DPP_ADD(x, 0xB1); x = DPP_ADD(x, 0x4E); return x; }
; __device__ __forceinline__ void phase_scan(const ScanArgs A, LAS unsigned char* lds) {
;     ...
;                 for (int t = 0; t < 16; ++t) {
;                     const LAS float* q = in + t * 64 + kq * 16;
;                     f32x4 Wv[4], KDv[4], Bv[4], ANv[4], Rv[4];
; #pragma unroll
;                     for (int j = 0; j < 4; ++j) { Wv[j] = *(const LAS f32x4*)(q + 4 * j); KDv[j] = *(const LAS f32x4*)(q + 1024 + 4 * j); Bv[j] = *(const LAS f32x4*)(q + 2048 + 4 * j);
;                                                   ANv[j] = *(const LAS f32x4*)(q + 3072 + 4 * j); Rv[j] = *(const LAS f32x4*)(q + 4096 + 4 * j); }
;                     const f32x2 v2 = *(const LAS f32x2*)(in + 5120 + t * 64 + half * 32 + rb * 2);
;     ...
;                     float sa[2], y[2];
; #pragma unroll
;                     for (int i = 0; i < 2; ++i) { f32x2 a0 = {0.f, 0.f}, a1 = {0.f, 0.f};
; #pragma unroll
;                         for (int p = 0; p < 8; p += 2) { a0 += S2[i][p] * PAIR(ANv, p); a1 += S2[i][p + 1] * PAIR(ANv, p + 1); }
;                         a0 += a1; sa[i] = red4(a0[0] + a0[1]); }
; #pragma unroll
;                     for (int i = 0; i < 2; ++i) { f32x2 y0 = {0.f, 0.f}, y1 = {0.f, 0.f}; const f32x2 sai = {sa[i], sa[i]}, vi = {v2[i], v2[i]};
; #pragma unroll
;                         for (int p = 0; p < 8; p += 2) {
;                             const f32x2 n0 = S2[i][p] * PAIR(Wv, p) + sai * PAIR(Bv, p) + vi * PAIR(KDv, p);
;                             const f32x2 n1 = S2[i][p + 1] * PAIR(Wv, p + 1) + sai * PAIR(Bv, p + 1) + vi * PAIR(KDv, p + 1);
;                             S2[i][p] = n0; S2[i][p + 1] = n1; y0 += n0 * PAIR(Rv, p); y1 += n1 * PAIR(Rv, p + 1); }
;                         y0 += y1; y[i] = red4(y0[0] + y0[1]); }
	v_pk_fma_f32 v[160:161], v[84:85], v[32:33], 0 op_sel_hi:[1,1,0]
	v_pk_fma_f32 v[162:163], v[88:89], v[34:35], 0 op_sel_hi:[1,1,0]
	v_pk_fma_f32 v[164:165], v[100:101], v[32:33], 0 op_sel_hi:[1,1,0]
	v_pk_fma_f32 v[166:167], v[104:105], v[34:35], 0 op_sel_hi:[1,1,0]
	v_pk_fma_f32 v[160:161], v[86:87], v[36:37], v[160:161]
	v_pk_fma_f32 v[162:163], v[92:93], v[38:39], v[162:163]
	v_pk_fma_f32 v[164:165], v[106:107], v[36:37], v[164:165]
	v_pk_fma_f32 v[166:167], v[108:109], v[38:39], v[166:167]
	v_pk_fma_f32 v[160:161], v[90:91], v[40:41], v[160:161]
	v_pk_fma_f32 v[162:163], v[98:99], v[42:43], v[162:163]
	v_pk_fma_f32 v[164:165], v[110:111], v[40:41], v[164:165]
	v_pk_fma_f32 v[166:167], v[112:113], v[42:43], v[166:167]
	v_pk_fma_f32 v[160:161], v[94:95], v[44:45], v[160:161]
	v_pk_fma_f32 v[162:163], v[102:103], v[46:47], v[162:163]
	v_pk_fma_f32 v[164:165], v[114:115], v[44:45], v[164:165]
	v_pk_fma_f32 v[166:167], v[116:117], v[46:47], v[166:167]
	ds_read_b128 v[32:35], v171 offset:14848
	ds_read_b128 v[36:39], v171 offset:14864
	ds_read_b128 v[40:43], v171 offset:14880
	ds_read_b128 v[44:47], v171 offset:14896
	v_pk_add_f32 v[160:161], v[162:163], v[160:161]
	v_pk_add_f32 v[164:165], v[166:167], v[164:165]
	v_add_f32_e32 v168, v160, v161
	v_add_f32_e32 v169, v164, v165
	s_nop 0
	v_add_f32_dpp v168, v168, v168 quad_perm:[1,0,3,2] row_mask:0xf bank_mask:0xf bound_ctrl:1
	v_add_f32_dpp v169, v169, v169 quad_perm:[1,0,3,2] row_mask:0xf bank_mask:0xf bound_ctrl:1
	s_nop 0
	v_add_f32_dpp v190, v168, v168 quad_perm:[2,3,0,1] row_mask:0xf bank_mask:0xf bound_ctrl:1
	v_add_f32_dpp v192, v169, v169 quad_perm:[2,3,0,1] row_mask:0xf bank_mask:0xf bound_ctrl:1
	s_waitcnt lgkmcnt(9)
	v_pk_mul_f32 v[216:217], v[142:143], v[190:191] op_sel_hi:[1,0]
	v_pk_mul_f32 v[218:219], v[144:145], v[190:191] op_sel_hi:[1,0]
	v_pk_mul_f32 v[232:233], v[142:143], v[192:193] op_sel_hi:[1,0]
	v_pk_mul_f32 v[234:235], v[144:145], v[192:193] op_sel_hi:[1,0]
	v_pk_fma_f32 v[216:217], v[84:85], v[48:49], v[216:217]
	v_pk_fma_f32 v[218:219], v[88:89], v[50:51], v[218:219]
	v_pk_fma_f32 v[232:233], v[100:101], v[48:49], v[232:233]
	v_pk_fma_f32 v[234:235], v[104:105], v[50:51], v[234:235]
	v_pk_fma_f32 v[84:85], v[172:173], v[188:189], v[216:217] op_sel_hi:[1,0,1]
	v_pk_fma_f32 v[88:89], v[174:175], v[188:189], v[218:219] op_sel_hi:[1,0,1]
	v_pk_fma_f32 v[100:101], v[172:173], v[188:189], v[232:233] op_sel:[0,1,0]
	v_pk_fma_f32 v[104:105], v[174:175], v[188:189], v[234:235] op_sel:[0,1,0]
	ds_read_b128 v[142:145], v171 offset:10752
	ds_read_b128 v[48:51], v171 offset:2560
	ds_read_b128 v[172:175], v171 offset:6656
	v_pk_mul_f32 v[220:221], v[146:147], v[190:191] op_sel_hi:[1,0]
	v_pk_mul_f32 v[222:223], v[148:149], v[190:191] op_sel_hi:[1,0]
	v_pk_mul_f32 v[236:237], v[146:147], v[192:193] op_sel_hi:[1,0]
	v_pk_mul_f32 v[238:239], v[148:149], v[192:193] op_sel_hi:[1,0]
	v_pk_fma_f32 v[220:221], v[86:87], v[52:53], v[220:221]
	v_pk_fma_f32 v[222:223], v[92:93], v[54:55], v[222:223]
	v_pk_fma_f32 v[236:237], v[106:107], v[52:53], v[236:237]
	v_pk_fma_f32 v[238:239], v[108:109], v[54:55], v[238:239]
	v_pk_fma_f32 v[86:87], v[176:177], v[188:189], v[220:221] op_sel_hi:[1,0,1]
	v_pk_fma_f32 v[92:93], v[178:179], v[188:189], v[222:223] op_sel_hi:[1,0,1]
	v_pk_fma_f32 v[106:107], v[176:177], v[188:189], v[236:237] op_sel:[0,1,0]
	v_pk_fma_f32 v[108:109], v[178:179], v[188:189], v[238:239] op_sel:[0,1,0]
	ds_read_b128 v[146:149], v171 offset:10768
	ds_read_b128 v[52:55], v171 offset:2576
	ds_read_b128 v[176:179], v171 offset:6672
	v_pk_mul_f32 v[224:225], v[150:151], v[190:191] op_sel_hi:[1,0]
	v_pk_mul_f32 v[226:227], v[152:153], v[190:191] op_sel_hi:[1,0]
	v_pk_mul_f32 v[240:241], v[150:151], v[192:193] op_sel_hi:[1,0]
	v_pk_mul_f32 v[242:243], v[152:153], v[192:193] op_sel_hi:[1,0]
	v_pk_fma_f32 v[224:225], v[90:91], v[56:57], v[224:225]
	v_pk_fma_f32 v[226:227], v[98:99], v[58:59], v[226:227]
	v_pk_fma_f32 v[240:241], v[110:111], v[56:57], v[240:241]
	v_pk_fma_f32 v[242:243], v[112:113], v[58:59], v[242:243]
	v_pk_fma_f32 v[90:91], v[180:181], v[188:189], v[224:225] op_sel_hi:[1,0,1]
	v_pk_fma_f32 v[98:99], v[182:183], v[188:189], v[226:227] op_sel_hi:[1,0,1]
	v_pk_fma_f32 v[110:111], v[180:181], v[188:189], v[240:241] op_sel:[0,1,0]
	v_pk_fma_f32 v[112:113], v[182:183], v[188:189], v[242:243] op_sel:[0,1,0]
	ds_read_b128 v[150:153], v171 offset:10784
	ds_read_b128 v[56:59], v171 offset:2592
	ds_read_b128 v[180:183], v171 offset:6688
	v_pk_mul_f32 v[228:229], v[154:155], v[190:191] op_sel_hi:[1,0]
	v_pk_mul_f32 v[230:231], v[156:157], v[190:191] op_sel_hi:[1,0]
	v_pk_mul_f32 v[244:245], v[154:155], v[192:193] op_sel_hi:[1,0]
	v_pk_mul_f32 v[246:247], v[156:157], v[192:193] op_sel_hi:[1,0]
	v_pk_fma_f32 v[228:229], v[94:95], v[60:61], v[228:229]
	v_pk_fma_f32 v[230:231], v[102:103], v[62:63], v[230:231]
	v_pk_fma_f32 v[244:245], v[114:115], v[60:61], v[244:245]
	v_pk_fma_f32 v[246:247], v[116:117], v[62:63], v[246:247]
	v_pk_fma_f32 v[94:95], v[184:185], v[188:189], v[228:229] op_sel_hi:[1,0,1]
	v_pk_fma_f32 v[102:103], v[186:187], v[188:189], v[230:231] op_sel_hi:[1,0,1]
	v_pk_fma_f32 v[114:115], v[184:185], v[188:189], v[244:245] op_sel:[0,1,0]
	v_pk_fma_f32 v[116:117], v[186:187], v[188:189], v[246:247] op_sel:[0,1,0]
	ds_read_b128 v[154:157], v171 offset:10800
	ds_read_b128 v[60:63], v171 offset:2608
	ds_read_b128 v[184:187], v171 offset:6704
	ds_read_b64 v[188:189], v96 offset:2560
	s_waitcnt lgkmcnt(15)
; #define LAS __attribute__((address_space(3)))
; __device__ __forceinline__ float red4(float x) { x = DPP_ADD(x, 0xB1); x = DPP_ADD(x, 0x4E); return x; }
; __device__ __forceinline__ void phase_scan(const ScanArgs A, LAS unsigned char* lds) {
;     ...
;                 for (int t = 0; t < 16; ++t) {
;                     const LAS float* q = in + t * 64 + kq * 16;
;                     f32x4 Wv[4], KDv[4], Bv[4], ANv[4], Rv[4];
; #pragma unroll
;                     for (int j = 0; j < 4; ++j) { Wv[j] = *(const LAS f32x4*)(q + 4 * j); KDv[j] = *(const LAS f32x4*)(q + 1024 + 4 * j); Bv[j] = *(const LAS f32x4*)(q + 2048 + 4 * j);
;                                                   ANv[j] = *(const LAS f32x4*)(q + 3072 + 4 * j); Rv[j] = *(const LAS f32x4*)(q + 4096 + 4 * j); }
;                     const f32x2 v2 = *(const LAS f32x2*)(in + 5120 + t * 64 + half * 32 + rb * 2);
;     ...
;                     float sa[2], y[2];
; #pragma unroll
;                     for (int i = 0; i < 2; ++i) { f32x2 a0 = {0.f, 0.f}, a1 = {0.f, 0.f};
; #pragma unroll
;                         for (int p = 0; p < 8; p += 2) { a0 += S2[i][p] * PAIR(ANv, p); a1 += S2[i][p + 1] * PAIR(ANv, p + 1); }
;                         a0 += a1; sa[i] = red4(a0[0] + a0[1]); }
;     ...
;                     for (int i = 0; i < 2; ++i) { f32x2 y0 = {0.f, 0.f}, y1 = {0.f, 0.f}; const f32x2 sai = {sa[i], sa[i]}, vi = {v2[i], v2[i]};
; #pragma unroll
;                         for (int p = 0; p < 8; p += 2) {
;                             const f32x2 n0 = S2[i][p] * PAIR(Wv, p) + sai * PAIR(Bv, p) + vi * PAIR(KDv, p);
;                             const f32x2 n1 = S2[i][p + 1] * PAIR(Wv, p + 1) + sai * PAIR(Bv, p + 1) + vi * PAIR(KDv, p + 1);
;                             S2[i][p] = n0; S2[i][p + 1] = n1; y0 += n0 * PAIR(Rv, p); y1 += n1 * PAIR(Rv, p + 1); }
;                         y0 += y1; y[i] = red4(y0[0] + y0[1]); }
;     ...
;                     if (kq == 0) *(LAS f32x2*)(yb + t * 64 + half * 32 + rb * 2) = (f32x2){y[0], y[1]};
	v_pk_fma_f32 v[248:249], v[200:201], v[84:85], 0 op_sel_hi:[1,1,0]
	v_pk_fma_f32 v[250:251], v[202:203], v[88:89], 0 op_sel_hi:[1,1,0]
	v_pk_fma_f32 v[194:195], v[200:201], v[100:101], 0 op_sel_hi:[1,1,0]
	v_pk_fma_f32 v[158:159], v[202:203], v[104:105], 0 op_sel_hi:[1,1,0]
	v_pk_fma_f32 v[248:249], v[204:205], v[86:87], v[248:249]
	v_pk_fma_f32 v[250:251], v[206:207], v[92:93], v[250:251]
	v_pk_fma_f32 v[194:195], v[204:205], v[106:107], v[194:195]
	v_pk_fma_f32 v[158:159], v[206:207], v[108:109], v[158:159]
	v_pk_fma_f32 v[248:249], v[208:209], v[90:91], v[248:249]
	v_pk_fma_f32 v[250:251], v[210:211], v[98:99], v[250:251]
	v_pk_fma_f32 v[194:195], v[208:209], v[110:111], v[194:195]
	v_pk_fma_f32 v[158:159], v[210:211], v[112:113], v[158:159]
	v_pk_fma_f32 v[248:249], v[212:213], v[94:95], v[248:249]
	v_pk_fma_f32 v[250:251], v[214:215], v[102:103], v[250:251]
	v_pk_fma_f32 v[194:195], v[212:213], v[114:115], v[194:195]
	v_pk_fma_f32 v[158:159], v[214:215], v[116:117], v[158:159]
	ds_read_b128 v[200:203], v171 offset:18944
	ds_read_b128 v[204:207], v171 offset:18960
	ds_read_b128 v[208:211], v171 offset:18976
	ds_read_b128 v[212:215], v171 offset:18992
	v_pk_add_f32 v[248:249], v[250:251], v[248:249]
	v_pk_add_f32 v[194:195], v[158:159], v[194:195]
	v_add_f32_e32 v168, v248, v249
	v_add_f32_e32 v169, v194, v195
	s_nop 0
	v_add_f32_dpp v168, v168, v168 quad_perm:[1,0,3,2] row_mask:0xf bank_mask:0xf bound_ctrl:1
	v_add_f32_dpp v169, v169, v169 quad_perm:[1,0,3,2] row_mask:0xf bank_mask:0xf bound_ctrl:1
	s_nop 0
	v_add_f32_dpp v168, v168, v168 quad_perm:[2,3,0,1] row_mask:0xf bank_mask:0xf bound_ctrl:1
	v_add_f32_dpp v169, v169, v169 quad_perm:[2,3,0,1] row_mask:0xf bank_mask:0xf bound_ctrl:1
	s_and_saveexec_b64 s[34:35], s[8:9]
	ds_write_b64 v75, v[168:169] offset:2304
	s_or_b64 exec, exec, s[34:35]
	s_waitcnt lgkmcnt(15)
	v_pk_fma_f32 v[160:161], v[84:85], v[32:33], 0 op_sel_hi:[1,1,0]
	v_pk_fma_f32 v[162:163], v[88:89], v[34:35], 0 op_sel_hi:[1,1,0]
	v_pk_fma_f32 v[164:165], v[100:101], v[32:33], 0 op_sel_hi:[1,1,0]
	v_pk_fma_f32 v[166:167], v[104:105], v[34:35], 0 op_sel_hi:[1,1,0]
	v_pk_fma_f32 v[160:161], v[86:87], v[36:37], v[160:161]
	v_pk_fma_f32 v[162:163], v[92:93], v[38:39], v[162:163]
	v_pk_fma_f32 v[164:165], v[106:107], v[36:37], v[164:165]
	v_pk_fma_f32 v[166:167], v[108:109], v[38:39], v[166:167]
	v_pk_fma_f32 v[160:161], v[90:91], v[40:41], v[160:161]
	v_pk_fma_f32 v[162:163], v[98:99], v[42:43], v[162:163]
	v_pk_fma_f32 v[164:165], v[110:111], v[40:41], v[164:165]
	v_pk_fma_f32 v[166:167], v[112:113], v[42:43], v[166:167]
	v_pk_fma_f32 v[160:161], v[94:95], v[44:45], v[160:161]
	v_pk_fma_f32 v[162:163], v[102:103], v[46:47], v[162:163]
	v_pk_fma_f32 v[164:165], v[114:115], v[44:45], v[164:165]
	v_pk_fma_f32 v[166:167], v[116:117], v[46:47], v[166:167]
	ds_read_b128 v[32:35], v171 offset:15104
	ds_read_b128 v[36:39], v171 offset:15120
	ds_read_b128 v[40:43], v171 offset:15136
	ds_read_b128 v[44:47], v171 offset:15152
	v_pk_add_f32 v[160:161], v[162:163], v[160:161]
	v_pk_add_f32 v[164:165], v[166:167], v[164:165]
	v_add_f32_e32 v168, v160, v161
	v_add_f32_e32 v169, v164, v165
	s_nop 0
	v_add_f32_dpp v168, v168, v168 quad_perm:[1,0,3,2] row_mask:0xf bank_mask:0xf bound_ctrl:1
	v_add_f32_dpp v169, v169, v169 quad_perm:[1,0,3,2] row_mask:0xf bank_mask:0xf bound_ctrl:1
	s_nop 0
	v_add_f32_dpp v190, v168, v168 quad_perm:[2,3,0,1] row_mask:0xf bank_mask:0xf bound_ctrl:1
	v_add_f32_dpp v192, v169, v169 quad_perm:[2,3,0,1] row_mask:0xf bank_mask:0xf bound_ctrl:1
	s_waitcnt lgkmcnt(9)
	v_pk_mul_f32 v[216:217], v[142:143], v[190:191] op_sel_hi:[1,0]
	v_pk_mul_f32 v[218:219], v[144:145], v[190:191] op_sel_hi:[1,0]
	v_pk_mul_f32 v[232:233], v[142:143], v[192:193] op_sel_hi:[1,0]
	v_pk_mul_f32 v[234:235], v[144:145], v[192:193] op_sel_hi:[1,0]
	v_pk_fma_f32 v[216:217], v[84:85], v[48:49], v[216:217]
	v_pk_fma_f32 v[218:219], v[88:89], v[50:51], v[218:219]
	v_pk_fma_f32 v[232:233], v[100:101], v[48:49], v[232:233]
	v_pk_fma_f32 v[234:235], v[104:105], v[50:51], v[234:235]
	v_pk_fma_f32 v[84:85], v[172:173], v[188:189], v[216:217] op_sel_hi:[1,0,1]
	v_pk_fma_f32 v[88:89], v[174:175], v[188:189], v[218:219] op_sel_hi:[1,0,1]
	v_pk_fma_f32 v[100:101], v[172:173], v[188:189], v[232:233] op_sel:[0,1,0]
	v_pk_fma_f32 v[104:105], v[174:175], v[188:189], v[234:235] op_sel:[0,1,0]
	ds_read_b128 v[142:145], v171 offset:11008
	ds_read_b128 v[48:51], v171 offset:2816
	ds_read_b128 v[172:175], v171 offset:6912
	v_pk_mul_f32 v[220:221], v[146:147], v[190:191] op_sel_hi:[1,0]
	v_pk_mul_f32 v[222:223], v[148:149], v[190:191] op_sel_hi:[1,0]
	v_pk_mul_f32 v[236:237], v[146:147], v[192:193] op_sel_hi:[1,0]
	v_pk_mul_f32 v[238:239], v[148:149], v[192:193] op_sel_hi:[1,0]
	v_pk_fma_f32 v[220:221], v[86:87], v[52:53], v[220:221]
	v_pk_fma_f32 v[222:223], v[92:93], v[54:55], v[222:223]
	v_pk_fma_f32 v[236:237], v[106:107], v[52:53], v[236:237]
	v_pk_fma_f32 v[238:239], v[108:109], v[54:55], v[238:239]
	v_pk_fma_f32 v[86:87], v[176:177], v[188:189], v[220:221] op_sel_hi:[1,0,1]
	v_pk_fma_f32 v[92:93], v[178:179], v[188:189], v[222:223] op_sel_hi:[1,0,1]
	v_pk_fma_f32 v[106:107], v[176:177], v[188:189], v[236:237] op_sel:[0,1,0]
	v_pk_fma_f32 v[108:109], v[178:179], v[188:189], v[238:239] op_sel:[0,1,0]
	ds_read_b128 v[146:149], v171 offset:11024
	ds_read_b128 v[52:55], v171 offset:2832
	ds_read_b128 v[176:179], v171 offset:6928
	v_pk_mul_f32 v[224:225], v[150:151], v[190:191] op_sel_hi:[1,0]
	v_pk_mul_f32 v[226:227], v[152:153], v[190:191] op_sel_hi:[1,0]
	v_pk_mul_f32 v[240:241], v[150:151], v[192:193] op_sel_hi:[1,0]
	v_pk_mul_f32 v[242:243], v[152:153], v[192:193] op_sel_hi:[1,0]
; #define LAS __attribute__((address_space(3)))
; __device__ __forceinline__ float red4(float x) { x = DPP_ADD(x, 0xB1); x = DPP_ADD(x, 0x4E); return x; }
; __device__ __forceinline__ void phase_scan(const ScanArgs A, LAS unsigned char* lds) {
;     ...
;                 for (int t = 0; t < 16; ++t) {
;                     const LAS float* q = in + t * 64 + kq * 16;
;                     f32x4 Wv[4], KDv[4], Bv[4], ANv[4], Rv[4];
; #pragma unroll
;                     for (int j = 0; j < 4; ++j) { Wv[j] = *(const LAS f32x4*)(q + 4 * j); KDv[j] = *(const LAS f32x4*)(q + 1024 + 4 * j); Bv[j] = *(const LAS f32x4*)(q + 2048 + 4 * j);
;                                                   ANv[j] = *(const LAS f32x4*)(q + 3072 + 4 * j); Rv[j] = *(const LAS f32x4*)(q + 4096 + 4 * j); }
;                     const f32x2 v2 = *(const LAS f32x2*)(in + 5120 + t * 64 + half * 32 + rb * 2);
;     ...
;                     float sa[2], y[2];
; #pragma unroll
;                     for (int i = 0; i < 2; ++i) { f32x2 a0 = {0.f, 0.f}, a1 = {0.f, 0.f};
; #pragma unroll
;                         for (int p = 0; p < 8; p += 2) { a0 += S2[i][p] * PAIR(ANv, p); a1 += S2[i][p + 1] * PAIR(ANv, p + 1); }
;                         a0 += a1; sa[i] = red4(a0[0] + a0[1]); }
;     ...
;                     for (int i = 0; i < 2; ++i) { f32x2 y0 = {0.f, 0.f}, y1 = {0.f, 0.f}; const f32x2 sai = {sa[i], sa[i]}, vi = {v2[i], v2[i]};
; #pragma unroll
;                         for (int p = 0; p < 8; p += 2) {
;                             const f32x2 n0 = S2[i][p] * PAIR(Wv, p) + sai * PAIR(Bv, p) + vi * PAIR(KDv, p);
;                             const f32x2 n1 = S2[i][p + 1] * PAIR(Wv, p + 1) + sai * PAIR(Bv, p + 1) + vi * PAIR(KDv, p + 1);
;                             S2[i][p] = n0; S2[i][p + 1] = n1; y0 += n0 * PAIR(Rv, p); y1 += n1 * PAIR(Rv, p + 1); }
;                         y0 += y1; y[i] = red4(y0[0] + y0[1]); }
;     ...
;                     if (kq == 0) *(LAS f32x2*)(yb + t * 64 + half * 32 + rb * 2) = (f32x2){y[0], y[1]};
	v_pk_fma_f32 v[224:225], v[90:91], v[56:57], v[224:225]
	v_pk_fma_f32 v[226:227], v[98:99], v[58:59], v[226:227]
	v_pk_fma_f32 v[240:241], v[110:111], v[56:57], v[240:241]
	v_pk_fma_f32 v[242:243], v[112:113], v[58:59], v[242:243]
	v_pk_fma_f32 v[90:91], v[180:181], v[188:189], v[224:225] op_sel_hi:[1,0,1]
	v_pk_fma_f32 v[98:99], v[182:183], v[188:189], v[226:227] op_sel_hi:[1,0,1]
	v_pk_fma_f32 v[110:111], v[180:181], v[188:189], v[240:241] op_sel:[0,1,0]
	v_pk_fma_f32 v[112:113], v[182:183], v[188:189], v[242:243] op_sel:[0,1,0]
	ds_read_b128 v[150:153], v171 offset:11040
	ds_read_b128 v[56:59], v171 offset:2848
	ds_read_b128 v[180:183], v171 offset:6944
	v_pk_mul_f32 v[228:229], v[154:155], v[190:191] op_sel_hi:[1,0]
	v_pk_mul_f32 v[230:231], v[156:157], v[190:191] op_sel_hi:[1,0]
	v_pk_mul_f32 v[244:245], v[154:155], v[192:193] op_sel_hi:[1,0]
	v_pk_mul_f32 v[246:247], v[156:157], v[192:193] op_sel_hi:[1,0]
	v_pk_fma_f32 v[228:229], v[94:95], v[60:61], v[228:229]
	v_pk_fma_f32 v[230:231], v[102:103], v[62:63], v[230:231]
	v_pk_fma_f32 v[244:245], v[114:115], v[60:61], v[244:245]
	v_pk_fma_f32 v[246:247], v[116:117], v[62:63], v[246:247]
	v_pk_fma_f32 v[94:95], v[184:185], v[188:189], v[228:229] op_sel_hi:[1,0,1]
	v_pk_fma_f32 v[102:103], v[186:187], v[188:189], v[230:231] op_sel_hi:[1,0,1]
	v_pk_fma_f32 v[114:115], v[184:185], v[188:189], v[244:245] op_sel:[0,1,0]
	v_pk_fma_f32 v[116:117], v[186:187], v[188:189], v[246:247] op_sel:[0,1,0]
	ds_read_b128 v[154:157], v171 offset:11056
	ds_read_b128 v[60:63], v171 offset:2864
	ds_read_b128 v[184:187], v171 offset:6960
	ds_read_b64 v[188:189], v96 offset:2816
	s_waitcnt lgkmcnt(15)
	v_pk_fma_f32 v[248:249], v[200:201], v[84:85], 0 op_sel_hi:[1,1,0]
	v_pk_fma_f32 v[250:251], v[202:203], v[88:89], 0 op_sel_hi:[1,1,0]
	v_pk_fma_f32 v[194:195], v[200:201], v[100:101], 0 op_sel_hi:[1,1,0]
	v_pk_fma_f32 v[158:159], v[202:203], v[104:105], 0 op_sel_hi:[1,1,0]
	v_pk_fma_f32 v[248:249], v[204:205], v[86:87], v[248:249]
	v_pk_fma_f32 v[250:251], v[206:207], v[92:93], v[250:251]
	v_pk_fma_f32 v[194:195], v[204:205], v[106:107], v[194:195]
	v_pk_fma_f32 v[158:159], v[206:207], v[108:109], v[158:159]
	v_pk_fma_f32 v[248:249], v[208:209], v[90:91], v[248:249]
	v_pk_fma_f32 v[250:251], v[210:211], v[98:99], v[250:251]
	v_pk_fma_f32 v[194:195], v[208:209], v[110:111], v[194:195]
	v_pk_fma_f32 v[158:159], v[210:211], v[112:113], v[158:159]
	v_pk_fma_f32 v[248:249], v[212:213], v[94:95], v[248:249]
	v_pk_fma_f32 v[250:251], v[214:215], v[102:103], v[250:251]
	v_pk_fma_f32 v[194:195], v[212:213], v[114:115], v[194:195]
	v_pk_fma_f32 v[158:159], v[214:215], v[116:117], v[158:159]
	ds_read_b128 v[200:203], v171 offset:19200
	ds_read_b128 v[204:207], v171 offset:19216
	ds_read_b128 v[208:211], v171 offset:19232
	ds_read_b128 v[212:215], v171 offset:19248
	v_pk_add_f32 v[248:249], v[250:251], v[248:249]
	v_pk_add_f32 v[194:195], v[158:159], v[194:195]
	v_add_f32_e32 v168, v248, v249
	v_add_f32_e32 v169, v194, v195
	s_nop 0
	v_add_f32_dpp v168, v168, v168 quad_perm:[1,0,3,2] row_mask:0xf bank_mask:0xf bound_ctrl:1
	v_add_f32_dpp v169, v169, v169 quad_perm:[1,0,3,2] row_mask:0xf bank_mask:0xf bound_ctrl:1
	s_nop 0
	v_add_f32_dpp v168, v168, v168 quad_perm:[2,3,0,1] row_mask:0xf bank_mask:0xf bound_ctrl:1
	v_add_f32_dpp v169, v169, v169 quad_perm:[2,3,0,1] row_mask:0xf bank_mask:0xf bound_ctrl:1
	s_and_saveexec_b64 s[34:35], s[8:9]
	ds_write_b64 v75, v[168:169] offset:2560
	s_or_b64 exec, exec, s[34:35]
	s_waitcnt lgkmcnt(15)
	v_pk_fma_f32 v[160:161], v[84:85], v[32:33], 0 op_sel_hi:[1,1,0]
	v_pk_fma_f32 v[162:163], v[88:89], v[34:35], 0 op_sel_hi:[1,1,0]
	v_pk_fma_f32 v[164:165], v[100:101], v[32:33], 0 op_sel_hi:[1,1,0]
	v_pk_fma_f32 v[166:167], v[104:105], v[34:35], 0 op_sel_hi:[1,1,0]
	v_pk_fma_f32 v[160:161], v[86:87], v[36:37], v[160:161]
	v_pk_fma_f32 v[162:163], v[92:93], v[38:39], v[162:163]
	v_pk_fma_f32 v[164:165], v[106:107], v[36:37], v[164:165]
	v_pk_fma_f32 v[166:167], v[108:109], v[38:39], v[166:167]
	v_pk_fma_f32 v[160:161], v[90:91], v[40:41], v[160:161]
	v_pk_fma_f32 v[162:163], v[98:99], v[42:43], v[162:163]
	v_pk_fma_f32 v[164:165], v[110:111], v[40:41], v[164:165]
	v_pk_fma_f32 v[166:167], v[112:113], v[42:43], v[166:167]
	v_pk_fma_f32 v[160:161], v[94:95], v[44:45], v[160:161]
	v_pk_fma_f32 v[162:163], v[102:103], v[46:47], v[162:163]
	v_pk_fma_f32 v[164:165], v[114:115], v[44:45], v[164:165]
	v_pk_fma_f32 v[166:167], v[116:117], v[46:47], v[166:167]
	ds_read_b128 v[32:35], v171 offset:15360
	ds_read_b128 v[36:39], v171 offset:15376
	ds_read_b128 v[40:43], v171 offset:15392
	ds_read_b128 v[44:47], v171 offset:15408
	v_pk_add_f32 v[160:161], v[162:163], v[160:161]
	v_pk_add_f32 v[164:165], v[166:167], v[164:165]
	v_add_f32_e32 v168, v160, v161
	v_add_f32_e32 v169, v164, v165
	s_nop 0
	v_add_f32_dpp v168, v168, v168 quad_perm:[1,0,3,2] row_mask:0xf bank_mask:0xf bound_ctrl:1
	v_add_f32_dpp v169, v169, v169 quad_perm:[1,0,3,2] row_mask:0xf bank_mask:0xf bound_ctrl:1
	s_nop 0
	v_add_f32_dpp v190, v168, v168 quad_perm:[2,3,0,1] row_mask:0xf bank_mask:0xf bound_ctrl:1
	v_add_f32_dpp v192, v169, v169 quad_perm:[2,3,0,1] row_mask:0xf bank_mask:0xf bound_ctrl:1
	s_waitcnt lgkmcnt(9)
; #define LAS __attribute__((address_space(3)))
; __device__ __forceinline__ float red4(float x) { x = DPP_ADD(x, 0xB1); x = DPP_ADD(x, 0x4E); return x; }
; __device__ __forceinline__ void phase_scan(const ScanArgs A, LAS unsigned char* lds) {
;     ...
;                     for (int i = 0; i < 2; ++i) { f32x2 y0 = {0.f, 0.f}, y1 = {0.f, 0.f}; const f32x2 sai = {sa[i], sa[i]}, vi = {v2[i], v2[i]};
; #pragma unroll
;                         for (int p = 0; p < 8; p += 2) {
;                             const f32x2 n0 = S2[i][p] * PAIR(Wv, p) + sai * PAIR(Bv, p) + vi * PAIR(KDv, p);
;                             const f32x2 n1 = S2[i][p + 1] * PAIR(Wv, p + 1) + sai * PAIR(Bv, p + 1) + vi * PAIR(KDv, p + 1);
;                             S2[i][p] = n0; S2[i][p + 1] = n1; y0 += n0 * PAIR(Rv, p); y1 += n1 * PAIR(Rv, p + 1); }
;                         y0 += y1; y[i] = red4(y0[0] + y0[1]); }
;     ...
;                     if (kq == 0) *(LAS f32x2*)(yb + t * 64 + half * 32 + rb * 2) = (f32x2){y[0], y[1]};
	v_pk_mul_f32 v[216:217], v[142:143], v[190:191] op_sel_hi:[1,0]
	v_pk_mul_f32 v[218:219], v[144:145], v[190:191] op_sel_hi:[1,0]
	v_pk_mul_f32 v[232:233], v[142:143], v[192:193] op_sel_hi:[1,0]
	v_pk_mul_f32 v[234:235], v[144:145], v[192:193] op_sel_hi:[1,0]
	v_pk_fma_f32 v[216:217], v[84:85], v[48:49], v[216:217]
	v_pk_fma_f32 v[218:219], v[88:89], v[50:51], v[218:219]
	v_pk_fma_f32 v[232:233], v[100:101], v[48:49], v[232:233]
	v_pk_fma_f32 v[234:235], v[104:105], v[50:51], v[234:235]
	v_pk_fma_f32 v[84:85], v[172:173], v[188:189], v[216:217] op_sel_hi:[1,0,1]
	v_pk_fma_f32 v[88:89], v[174:175], v[188:189], v[218:219] op_sel_hi:[1,0,1]
	v_pk_fma_f32 v[100:101], v[172:173], v[188:189], v[232:233] op_sel:[0,1,0]
	v_pk_fma_f32 v[104:105], v[174:175], v[188:189], v[234:235] op_sel:[0,1,0]
	ds_read_b128 v[142:145], v171 offset:11264
	ds_read_b128 v[48:51], v171 offset:3072
	ds_read_b128 v[172:175], v171 offset:7168
	v_pk_mul_f32 v[220:221], v[146:147], v[190:191] op_sel_hi:[1,0]
	v_pk_mul_f32 v[222:223], v[148:149], v[190:191] op_sel_hi:[1,0]
	v_pk_mul_f32 v[236:237], v[146:147], v[192:193] op_sel_hi:[1,0]
	v_pk_mul_f32 v[238:239], v[148:149], v[192:193] op_sel_hi:[1,0]
	v_pk_fma_f32 v[220:221], v[86:87], v[52:53], v[220:221]
	v_pk_fma_f32 v[222:223], v[92:93], v[54:55], v[222:223]
	v_pk_fma_f32 v[236:237], v[106:107], v[52:53], v[236:237]
	v_pk_fma_f32 v[238:239], v[108:109], v[54:55], v[238:239]
	v_pk_fma_f32 v[86:87], v[176:177], v[188:189], v[220:221] op_sel_hi:[1,0,1]
	v_pk_fma_f32 v[92:93], v[178:179], v[188:189], v[222:223] op_sel_hi:[1,0,1]
	v_pk_fma_f32 v[106:107], v[176:177], v[188:189], v[236:237] op_sel:[0,1,0]
	v_pk_fma_f32 v[108:109], v[178:179], v[188:189], v[238:239] op_sel:[0,1,0]
	ds_read_b128 v[146:149], v171 offset:11280
	ds_read_b128 v[52:55], v171 offset:3088
	ds_read_b128 v[176:179], v171 offset:7184
	v_pk_mul_f32 v[224:225], v[150:151], v[190:191] op_sel_hi:[1,0]
	v_pk_mul_f32 v[226:227], v[152:153], v[190:191] op_sel_hi:[1,0]
	v_pk_mul_f32 v[240:241], v[150:151], v[192:193] op_sel_hi:[1,0]
	v_pk_mul_f32 v[242:243], v[152:153], v[192:193] op_sel_hi:[1,0]
	v_pk_fma_f32 v[224:225], v[90:91], v[56:57], v[224:225]
	v_pk_fma_f32 v[226:227], v[98:99], v[58:59], v[226:227]
	v_pk_fma_f32 v[240:241], v[110:111], v[56:57], v[240:241]
	v_pk_fma_f32 v[242:243], v[112:113], v[58:59], v[242:243]
	v_pk_fma_f32 v[90:91], v[180:181], v[188:189], v[224:225] op_sel_hi:[1,0,1]
	v_pk_fma_f32 v[98:99], v[182:183], v[188:189], v[226:227] op_sel_hi:[1,0,1]
	v_pk_fma_f32 v[110:111], v[180:181], v[188:189], v[240:241] op_sel:[0,1,0]
	v_pk_fma_f32 v[112:113], v[182:183], v[188:189], v[242:243] op_sel:[0,1,0]
	ds_read_b128 v[150:153], v171 offset:11296
	ds_read_b128 v[56:59], v171 offset:3104
	ds_read_b128 v[180:183], v171 offset:7200
	v_pk_mul_f32 v[228:229], v[154:155], v[190:191] op_sel_hi:[1,0]
	v_pk_mul_f32 v[230:231], v[156:157], v[190:191] op_sel_hi:[1,0]
	v_pk_mul_f32 v[244:245], v[154:155], v[192:193] op_sel_hi:[1,0]
	v_pk_mul_f32 v[246:247], v[156:157], v[192:193] op_sel_hi:[1,0]
	v_pk_fma_f32 v[228:229], v[94:95], v[60:61], v[228:229]
	v_pk_fma_f32 v[230:231], v[102:103], v[62:63], v[230:231]
	v_pk_fma_f32 v[244:245], v[114:115], v[60:61], v[244:245]
	v_pk_fma_f32 v[246:247], v[116:117], v[62:63], v[246:247]
	v_pk_fma_f32 v[94:95], v[184:185], v[188:189], v[228:229] op_sel_hi:[1,0,1]
	v_pk_fma_f32 v[102:103], v[186:187], v[188:189], v[230:231] op_sel_hi:[1,0,1]
	v_pk_fma_f32 v[114:115], v[184:185], v[188:189], v[244:245] op_sel:[0,1,0]
	v_pk_fma_f32 v[116:117], v[186:187], v[188:189], v[246:247] op_sel:[0,1,0]
	ds_read_b128 v[154:157], v171 offset:11312
	ds_read_b128 v[60:63], v171 offset:3120
	ds_read_b128 v[184:187], v171 offset:7216
	ds_read_b64 v[188:189], v96 offset:3072
	s_waitcnt lgkmcnt(15)
	v_pk_fma_f32 v[248:249], v[200:201], v[84:85], 0 op_sel_hi:[1,1,0]
	v_pk_fma_f32 v[250:251], v[202:203], v[88:89], 0 op_sel_hi:[1,1,0]
	v_pk_fma_f32 v[194:195], v[200:201], v[100:101], 0 op_sel_hi:[1,1,0]
	v_pk_fma_f32 v[158:159], v[202:203], v[104:105], 0 op_sel_hi:[1,1,0]
	v_pk_fma_f32 v[248:249], v[204:205], v[86:87], v[248:249]
	v_pk_fma_f32 v[250:251], v[206:207], v[92:93], v[250:251]
	v_pk_fma_f32 v[194:195], v[204:205], v[106:107], v[194:195]
	v_pk_fma_f32 v[158:159], v[206:207], v[108:109], v[158:159]
	v_pk_fma_f32 v[248:249], v[208:209], v[90:91], v[248:249]
	v_pk_fma_f32 v[250:251], v[210:211], v[98:99], v[250:251]
	v_pk_fma_f32 v[194:195], v[208:209], v[110:111], v[194:195]
	v_pk_fma_f32 v[158:159], v[210:211], v[112:113], v[158:159]
	v_pk_fma_f32 v[248:249], v[212:213], v[94:95], v[248:249]
	v_pk_fma_f32 v[250:251], v[214:215], v[102:103], v[250:251]
	v_pk_fma_f32 v[194:195], v[212:213], v[114:115], v[194:195]
	v_pk_fma_f32 v[158:159], v[214:215], v[116:117], v[158:159]
	ds_read_b128 v[200:203], v171 offset:19456
	ds_read_b128 v[204:207], v171 offset:19472
	ds_read_b128 v[208:211], v171 offset:19488
	ds_read_b128 v[212:215], v171 offset:19504
	v_pk_add_f32 v[248:249], v[250:251], v[248:249]
	v_pk_add_f32 v[194:195], v[158:159], v[194:195]
	v_add_f32_e32 v168, v248, v249
	v_add_f32_e32 v169, v194, v195
	s_nop 0
	v_add_f32_dpp v168, v168, v168 quad_perm:[1,0,3,2] row_mask:0xf bank_mask:0xf bound_ctrl:1
	v_add_f32_dpp v169, v169, v169 quad_perm:[1,0,3,2] row_mask:0xf bank_mask:0xf bound_ctrl:1
	s_nop 0
	v_add_f32_dpp v168, v168, v168 quad_perm:[2,3,0,1] row_mask:0xf bank_mask:0xf bound_ctrl:1
	v_add_f32_dpp v169, v169, v169 quad_perm:[2,3,0,1] row_mask:0xf bank_mask:0xf bound_ctrl:1
	s_and_saveexec_b64 s[34:35], s[8:9]
	ds_write_b64 v75, v[168:169] offset:2816
	s_or_b64 exec, exec, s[34:35]
	s_waitcnt lgkmcnt(15)
; #define LAS __attribute__((address_space(3)))
; __device__ __forceinline__ float red4(float x) { x = DPP_ADD(x, 0xB1); x = DPP_ADD(x, 0x4E); return x; }
; __device__ __forceinline__ void phase_scan(const ScanArgs A, LAS unsigned char* lds) {
;     ...
;                 for (int t = 0; t < 16; ++t) {
;                     const LAS float* q = in + t * 64 + kq * 16;
;                     f32x4 Wv[4], KDv[4], Bv[4], ANv[4], Rv[4];
; #pragma unroll
;                     for (int j = 0; j < 4; ++j) { Wv[j] = *(const LAS f32x4*)(q + 4 * j); KDv[j] = *(const LAS f32x4*)(q + 1024 + 4 * j); Bv[j] = *(const LAS f32x4*)(q + 2048 + 4 * j);
;                                                   ANv[j] = *(const LAS f32x4*)(q + 3072 + 4 * j); Rv[j] = *(const LAS f32x4*)(q + 4096 + 4 * j); }
;                     const f32x2 v2 = *(const LAS f32x2*)(in + 5120 + t * 64 + half * 32 + rb * 2);
;     ...
;                     float sa[2], y[2];
; #pragma unroll
;                     for (int i = 0; i < 2; ++i) { f32x2 a0 = {0.f, 0.f}, a1 = {0.f, 0.f};
; #pragma unroll
;                         for (int p = 0; p < 8; p += 2) { a0 += S2[i][p] * PAIR(ANv, p); a1 += S2[i][p + 1] * PAIR(ANv, p + 1); }
;                         a0 += a1; sa[i] = red4(a0[0] + a0[1]); }
; #pragma unroll
;                     for (int i = 0; i < 2; ++i) { f32x2 y0 = {0.f, 0.f}, y1 = {0.f, 0.f}; const f32x2 sai = {sa[i], sa[i]}, vi = {v2[i], v2[i]};
; #pragma unroll
;                         for (int p = 0; p < 8; p += 2) {
;                             const f32x2 n0 = S2[i][p] * PAIR(Wv, p) + sai * PAIR(Bv, p) + vi * PAIR(KDv, p);
;                             const f32x2 n1 = S2[i][p + 1] * PAIR(Wv, p + 1) + sai * PAIR(Bv, p + 1) + vi * PAIR(KDv, p + 1);
;                             S2[i][p] = n0; S2[i][p + 1] = n1; y0 += n0 * PAIR(Rv, p); y1 += n1 * PAIR(Rv, p + 1); }
;                         y0 += y1; y[i] = red4(y0[0] + y0[1]); }
	v_pk_fma_f32 v[160:161], v[84:85], v[32:33], 0 op_sel_hi:[1,1,0]
	v_pk_fma_f32 v[162:163], v[88:89], v[34:35], 0 op_sel_hi:[1,1,0]
	v_pk_fma_f32 v[164:165], v[100:101], v[32:33], 0 op_sel_hi:[1,1,0]
	v_pk_fma_f32 v[166:167], v[104:105], v[34:35], 0 op_sel_hi:[1,1,0]
	v_pk_fma_f32 v[160:161], v[86:87], v[36:37], v[160:161]
	v_pk_fma_f32 v[162:163], v[92:93], v[38:39], v[162:163]
	v_pk_fma_f32 v[164:165], v[106:107], v[36:37], v[164:165]
	v_pk_fma_f32 v[166:167], v[108:109], v[38:39], v[166:167]
	v_pk_fma_f32 v[160:161], v[90:91], v[40:41], v[160:161]
	v_pk_fma_f32 v[162:163], v[98:99], v[42:43], v[162:163]
	v_pk_fma_f32 v[164:165], v[110:111], v[40:41], v[164:165]
	v_pk_fma_f32 v[166:167], v[112:113], v[42:43], v[166:167]
	v_pk_fma_f32 v[160:161], v[94:95], v[44:45], v[160:161]
	v_pk_fma_f32 v[162:163], v[102:103], v[46:47], v[162:163]
	v_pk_fma_f32 v[164:165], v[114:115], v[44:45], v[164:165]
	v_pk_fma_f32 v[166:167], v[116:117], v[46:47], v[166:167]
	ds_read_b128 v[32:35], v171 offset:15616
	ds_read_b128 v[36:39], v171 offset:15632
	ds_read_b128 v[40:43], v171 offset:15648
	ds_read_b128 v[44:47], v171 offset:15664
	v_pk_add_f32 v[160:161], v[162:163], v[160:161]
	v_pk_add_f32 v[164:165], v[166:167], v[164:165]
	v_add_f32_e32 v168, v160, v161
	v_add_f32_e32 v169, v164, v165
	s_nop 0
	v_add_f32_dpp v168, v168, v168 quad_perm:[1,0,3,2] row_mask:0xf bank_mask:0xf bound_ctrl:1
	v_add_f32_dpp v169, v169, v169 quad_perm:[1,0,3,2] row_mask:0xf bank_mask:0xf bound_ctrl:1
	s_nop 0
	v_add_f32_dpp v190, v168, v168 quad_perm:[2,3,0,1] row_mask:0xf bank_mask:0xf bound_ctrl:1
	v_add_f32_dpp v192, v169, v169 quad_perm:[2,3,0,1] row_mask:0xf bank_mask:0xf bound_ctrl:1
	s_waitcnt lgkmcnt(9)
	v_pk_mul_f32 v[216:217], v[142:143], v[190:191] op_sel_hi:[1,0]
	v_pk_mul_f32 v[218:219], v[144:145], v[190:191] op_sel_hi:[1,0]
	v_pk_mul_f32 v[232:233], v[142:143], v[192:193] op_sel_hi:[1,0]
	v_pk_mul_f32 v[234:235], v[144:145], v[192:193] op_sel_hi:[1,0]
	v_pk_fma_f32 v[216:217], v[84:85], v[48:49], v[216:217]
	v_pk_fma_f32 v[218:219], v[88:89], v[50:51], v[218:219]
	v_pk_fma_f32 v[232:233], v[100:101], v[48:49], v[232:233]
	v_pk_fma_f32 v[234:235], v[104:105], v[50:51], v[234:235]
	v_pk_fma_f32 v[84:85], v[172:173], v[188:189], v[216:217] op_sel_hi:[1,0,1]
	v_pk_fma_f32 v[88:89], v[174:175], v[188:189], v[218:219] op_sel_hi:[1,0,1]
	v_pk_fma_f32 v[100:101], v[172:173], v[188:189], v[232:233] op_sel:[0,1,0]
	v_pk_fma_f32 v[104:105], v[174:175], v[188:189], v[234:235] op_sel:[0,1,0]
	ds_read_b128 v[142:145], v171 offset:11520
	ds_read_b128 v[48:51], v171 offset:3328
	ds_read_b128 v[172:175], v171 offset:7424
	v_pk_mul_f32 v[220:221], v[146:147], v[190:191] op_sel_hi:[1,0]
	v_pk_mul_f32 v[222:223], v[148:149], v[190:191] op_sel_hi:[1,0]
	v_pk_mul_f32 v[236:237], v[146:147], v[192:193] op_sel_hi:[1,0]
	v_pk_mul_f32 v[238:239], v[148:149], v[192:193] op_sel_hi:[1,0]
	v_pk_fma_f32 v[220:221], v[86:87], v[52:53], v[220:221]
	v_pk_fma_f32 v[222:223], v[92:93], v[54:55], v[222:223]
	v_pk_fma_f32 v[236:237], v[106:107], v[52:53], v[236:237]
	v_pk_fma_f32 v[238:239], v[108:109], v[54:55], v[238:239]
	v_pk_fma_f32 v[86:87], v[176:177], v[188:189], v[220:221] op_sel_hi:[1,0,1]
	v_pk_fma_f32 v[92:93], v[178:179], v[188:189], v[222:223] op_sel_hi:[1,0,1]
	v_pk_fma_f32 v[106:107], v[176:177], v[188:189], v[236:237] op_sel:[0,1,0]
	v_pk_fma_f32 v[108:109], v[178:179], v[188:189], v[238:239] op_sel:[0,1,0]
	ds_read_b128 v[146:149], v171 offset:11536
	ds_read_b128 v[52:55], v171 offset:3344
	ds_read_b128 v[176:179], v171 offset:7440
	v_pk_mul_f32 v[224:225], v[150:151], v[190:191] op_sel_hi:[1,0]
	v_pk_mul_f32 v[226:227], v[152:153], v[190:191] op_sel_hi:[1,0]
	v_pk_mul_f32 v[240:241], v[150:151], v[192:193] op_sel_hi:[1,0]
	v_pk_mul_f32 v[242:243], v[152:153], v[192:193] op_sel_hi:[1,0]
	v_pk_fma_f32 v[224:225], v[90:91], v[56:57], v[224:225]
	v_pk_fma_f32 v[226:227], v[98:99], v[58:59], v[226:227]
	v_pk_fma_f32 v[240:241], v[110:111], v[56:57], v[240:241]
	v_pk_fma_f32 v[242:243], v[112:113], v[58:59], v[242:243]
	v_pk_fma_f32 v[90:91], v[180:181], v[188:189], v[224:225] op_sel_hi:[1,0,1]
	v_pk_fma_f32 v[98:99], v[182:183], v[188:189], v[226:227] op_sel_hi:[1,0,1]
	v_pk_fma_f32 v[110:111], v[180:181], v[188:189], v[240:241] op_sel:[0,1,0]
	v_pk_fma_f32 v[112:113], v[182:183], v[188:189], v[242:243] op_sel:[0,1,0]
	ds_read_b128 v[150:153], v171 offset:11552
	ds_read_b128 v[56:59], v171 offset:3360
	ds_read_b128 v[180:183], v171 offset:7456
	v_pk_mul_f32 v[228:229], v[154:155], v[190:191] op_sel_hi:[1,0]
	v_pk_mul_f32 v[230:231], v[156:157], v[190:191] op_sel_hi:[1,0]
	v_pk_mul_f32 v[244:245], v[154:155], v[192:193] op_sel_hi:[1,0]
	v_pk_mul_f32 v[246:247], v[156:157], v[192:193] op_sel_hi:[1,0]
	v_pk_fma_f32 v[228:229], v[94:95], v[60:61], v[228:229]
	v_pk_fma_f32 v[230:231], v[102:103], v[62:63], v[230:231]
	v_pk_fma_f32 v[244:245], v[114:115], v[60:61], v[244:245]
	v_pk_fma_f32 v[246:247], v[116:117], v[62:63], v[246:247]
	v_pk_fma_f32 v[94:95], v[184:185], v[188:189], v[228:229] op_sel_hi:[1,0,1]
	v_pk_fma_f32 v[102:103], v[186:187], v[188:189], v[230:231] op_sel_hi:[1,0,1]
	v_pk_fma_f32 v[114:115], v[184:185], v[188:189], v[244:245] op_sel:[0,1,0]
	v_pk_fma_f32 v[116:117], v[186:187], v[188:189], v[246:247] op_sel:[0,1,0]
	ds_read_b128 v[154:157], v171 offset:11568
	ds_read_b128 v[60:63], v171 offset:3376
	ds_read_b128 v[184:187], v171 offset:7472
	ds_read_b64 v[188:189], v96 offset:3328
	s_waitcnt lgkmcnt(15)
; #define LAS __attribute__((address_space(3)))
; __device__ __forceinline__ float red4(float x) { x = DPP_ADD(x, 0xB1); x = DPP_ADD(x, 0x4E); return x; }
; __device__ __forceinline__ void phase_scan(const ScanArgs A, LAS unsigned char* lds) {
;     ...
;                 for (int t = 0; t < 16; ++t) {
;                     const LAS float* q = in + t * 64 + kq * 16;
;                     f32x4 Wv[4], KDv[4], Bv[4], ANv[4], Rv[4];
; #pragma unroll
;                     for (int j = 0; j < 4; ++j) { Wv[j] = *(const LAS f32x4*)(q + 4 * j); KDv[j] = *(const LAS f32x4*)(q + 1024 + 4 * j); Bv[j] = *(const LAS f32x4*)(q + 2048 + 4 * j);
;                                                   ANv[j] = *(const LAS f32x4*)(q + 3072 + 4 * j); Rv[j] = *(const LAS f32x4*)(q + 4096 + 4 * j); }
;                     const f32x2 v2 = *(const LAS f32x2*)(in + 5120 + t * 64 + half * 32 + rb * 2);
;     ...
;                     float sa[2], y[2];
; #pragma unroll
;                     for (int i = 0; i < 2; ++i) { f32x2 a0 = {0.f, 0.f}, a1 = {0.f, 0.f};
; #pragma unroll
;                         for (int p = 0; p < 8; p += 2) { a0 += S2[i][p] * PAIR(ANv, p); a1 += S2[i][p + 1] * PAIR(ANv, p + 1); }
;                         a0 += a1; sa[i] = red4(a0[0] + a0[1]); }
;     ...
;                     for (int i = 0; i < 2; ++i) { f32x2 y0 = {0.f, 0.f}, y1 = {0.f, 0.f}; const f32x2 sai = {sa[i], sa[i]}, vi = {v2[i], v2[i]};
; #pragma unroll
;                         for (int p = 0; p < 8; p += 2) {
;                             const f32x2 n0 = S2[i][p] * PAIR(Wv, p) + sai * PAIR(Bv, p) + vi * PAIR(KDv, p);
;                             const f32x2 n1 = S2[i][p + 1] * PAIR(Wv, p + 1) + sai * PAIR(Bv, p + 1) + vi * PAIR(KDv, p + 1);
;                             S2[i][p] = n0; S2[i][p + 1] = n1; y0 += n0 * PAIR(Rv, p); y1 += n1 * PAIR(Rv, p + 1); }
;                         y0 += y1; y[i] = red4(y0[0] + y0[1]); }
;     ...
;                     if (kq == 0) *(LAS f32x2*)(yb + t * 64 + half * 32 + rb * 2) = (f32x2){y[0], y[1]};
	v_pk_fma_f32 v[248:249], v[200:201], v[84:85], 0 op_sel_hi:[1,1,0]
	v_pk_fma_f32 v[250:251], v[202:203], v[88:89], 0 op_sel_hi:[1,1,0]
	v_pk_fma_f32 v[194:195], v[200:201], v[100:101], 0 op_sel_hi:[1,1,0]
	v_pk_fma_f32 v[158:159], v[202:203], v[104:105], 0 op_sel_hi:[1,1,0]
	v_pk_fma_f32 v[248:249], v[204:205], v[86:87], v[248:249]
	v_pk_fma_f32 v[250:251], v[206:207], v[92:93], v[250:251]
	v_pk_fma_f32 v[194:195], v[204:205], v[106:107], v[194:195]
	v_pk_fma_f32 v[158:159], v[206:207], v[108:109], v[158:159]
	v_pk_fma_f32 v[248:249], v[208:209], v[90:91], v[248:249]
	v_pk_fma_f32 v[250:251], v[210:211], v[98:99], v[250:251]
	v_pk_fma_f32 v[194:195], v[208:209], v[110:111], v[194:195]
	v_pk_fma_f32 v[158:159], v[210:211], v[112:113], v[158:159]
	v_pk_fma_f32 v[248:249], v[212:213], v[94:95], v[248:249]
	v_pk_fma_f32 v[250:251], v[214:215], v[102:103], v[250:251]
	v_pk_fma_f32 v[194:195], v[212:213], v[114:115], v[194:195]
	v_pk_fma_f32 v[158:159], v[214:215], v[116:117], v[158:159]
	ds_read_b128 v[200:203], v171 offset:19712
	ds_read_b128 v[204:207], v171 offset:19728
	ds_read_b128 v[208:211], v171 offset:19744
	ds_read_b128 v[212:215], v171 offset:19760
	v_pk_add_f32 v[248:249], v[250:251], v[248:249]
	v_pk_add_f32 v[194:195], v[158:159], v[194:195]
	v_add_f32_e32 v168, v248, v249
	v_add_f32_e32 v169, v194, v195
	s_nop 0
	v_add_f32_dpp v168, v168, v168 quad_perm:[1,0,3,2] row_mask:0xf bank_mask:0xf bound_ctrl:1
	v_add_f32_dpp v169, v169, v169 quad_perm:[1,0,3,2] row_mask:0xf bank_mask:0xf bound_ctrl:1
	s_nop 0
	v_add_f32_dpp v168, v168, v168 quad_perm:[2,3,0,1] row_mask:0xf bank_mask:0xf bound_ctrl:1
	v_add_f32_dpp v169, v169, v169 quad_perm:[2,3,0,1] row_mask:0xf bank_mask:0xf bound_ctrl:1
	s_and_saveexec_b64 s[34:35], s[8:9]
	ds_write_b64 v75, v[168:169] offset:3072
	s_or_b64 exec, exec, s[34:35]
	s_waitcnt lgkmcnt(15)
	v_pk_fma_f32 v[160:161], v[84:85], v[32:33], 0 op_sel_hi:[1,1,0]
	v_pk_fma_f32 v[162:163], v[88:89], v[34:35], 0 op_sel_hi:[1,1,0]
	v_pk_fma_f32 v[164:165], v[100:101], v[32:33], 0 op_sel_hi:[1,1,0]
	v_pk_fma_f32 v[166:167], v[104:105], v[34:35], 0 op_sel_hi:[1,1,0]
	v_pk_fma_f32 v[160:161], v[86:87], v[36:37], v[160:161]
	v_pk_fma_f32 v[162:163], v[92:93], v[38:39], v[162:163]
	v_pk_fma_f32 v[164:165], v[106:107], v[36:37], v[164:165]
	v_pk_fma_f32 v[166:167], v[108:109], v[38:39], v[166:167]
	v_pk_fma_f32 v[160:161], v[90:91], v[40:41], v[160:161]
	v_pk_fma_f32 v[162:163], v[98:99], v[42:43], v[162:163]
	v_pk_fma_f32 v[164:165], v[110:111], v[40:41], v[164:165]
	v_pk_fma_f32 v[166:167], v[112:113], v[42:43], v[166:167]
	v_pk_fma_f32 v[160:161], v[94:95], v[44:45], v[160:161]
	v_pk_fma_f32 v[162:163], v[102:103], v[46:47], v[162:163]
	v_pk_fma_f32 v[164:165], v[114:115], v[44:45], v[164:165]
	v_pk_fma_f32 v[166:167], v[116:117], v[46:47], v[166:167]
	ds_read_b128 v[32:35], v171 offset:15872
	ds_read_b128 v[36:39], v171 offset:15888
	ds_read_b128 v[40:43], v171 offset:15904
	ds_read_b128 v[44:47], v171 offset:15920
	v_pk_add_f32 v[160:161], v[162:163], v[160:161]
	v_pk_add_f32 v[164:165], v[166:167], v[164:165]
	v_add_f32_e32 v168, v160, v161
	v_add_f32_e32 v169, v164, v165
	s_nop 0
	v_add_f32_dpp v168, v168, v168 quad_perm:[1,0,3,2] row_mask:0xf bank_mask:0xf bound_ctrl:1
	v_add_f32_dpp v169, v169, v169 quad_perm:[1,0,3,2] row_mask:0xf bank_mask:0xf bound_ctrl:1
	s_nop 0
	v_add_f32_dpp v190, v168, v168 quad_perm:[2,3,0,1] row_mask:0xf bank_mask:0xf bound_ctrl:1
	v_add_f32_dpp v192, v169, v169 quad_perm:[2,3,0,1] row_mask:0xf bank_mask:0xf bound_ctrl:1
	s_waitcnt lgkmcnt(9)
	v_pk_mul_f32 v[216:217], v[142:143], v[190:191] op_sel_hi:[1,0]
	v_pk_mul_f32 v[218:219], v[144:145], v[190:191] op_sel_hi:[1,0]
	v_pk_mul_f32 v[232:233], v[142:143], v[192:193] op_sel_hi:[1,0]
	v_pk_mul_f32 v[234:235], v[144:145], v[192:193] op_sel_hi:[1,0]
	v_pk_fma_f32 v[216:217], v[84:85], v[48:49], v[216:217]
	v_pk_fma_f32 v[218:219], v[88:89], v[50:51], v[218:219]
	v_pk_fma_f32 v[232:233], v[100:101], v[48:49], v[232:233]
	v_pk_fma_f32 v[234:235], v[104:105], v[50:51], v[234:235]
	v_pk_fma_f32 v[84:85], v[172:173], v[188:189], v[216:217] op_sel_hi:[1,0,1]
	v_pk_fma_f32 v[88:89], v[174:175], v[188:189], v[218:219] op_sel_hi:[1,0,1]
	v_pk_fma_f32 v[100:101], v[172:173], v[188:189], v[232:233] op_sel:[0,1,0]
	v_pk_fma_f32 v[104:105], v[174:175], v[188:189], v[234:235] op_sel:[0,1,0]
	ds_read_b128 v[142:145], v171 offset:11776
	ds_read_b128 v[48:51], v171 offset:3584
	ds_read_b128 v[172:175], v171 offset:7680
	v_pk_mul_f32 v[220:221], v[146:147], v[190:191] op_sel_hi:[1,0]
	v_pk_mul_f32 v[222:223], v[148:149], v[190:191] op_sel_hi:[1,0]
	v_pk_mul_f32 v[236:237], v[146:147], v[192:193] op_sel_hi:[1,0]
	v_pk_mul_f32 v[238:239], v[148:149], v[192:193] op_sel_hi:[1,0]
	v_pk_fma_f32 v[220:221], v[86:87], v[52:53], v[220:221]
	v_pk_fma_f32 v[222:223], v[92:93], v[54:55], v[222:223]
	v_pk_fma_f32 v[236:237], v[106:107], v[52:53], v[236:237]
	v_pk_fma_f32 v[238:239], v[108:109], v[54:55], v[238:239]
	v_pk_fma_f32 v[86:87], v[176:177], v[188:189], v[220:221] op_sel_hi:[1,0,1]
	v_pk_fma_f32 v[92:93], v[178:179], v[188:189], v[222:223] op_sel_hi:[1,0,1]
	v_pk_fma_f32 v[106:107], v[176:177], v[188:189], v[236:237] op_sel:[0,1,0]
	v_pk_fma_f32 v[108:109], v[178:179], v[188:189], v[238:239] op_sel:[0,1,0]
	ds_read_b128 v[146:149], v171 offset:11792
	ds_read_b128 v[52:55], v171 offset:3600
	ds_read_b128 v[176:179], v171 offset:7696
	v_pk_mul_f32 v[224:225], v[150:151], v[190:191] op_sel_hi:[1,0]
	v_pk_mul_f32 v[226:227], v[152:153], v[190:191] op_sel_hi:[1,0]
	v_pk_mul_f32 v[240:241], v[150:151], v[192:193] op_sel_hi:[1,0]
	v_pk_mul_f32 v[242:243], v[152:153], v[192:193] op_sel_hi:[1,0]
; #define LAS __attribute__((address_space(3)))
; __device__ __forceinline__ float red4(float x) { x = DPP_ADD(x, 0xB1); x = DPP_ADD(x, 0x4E); return x; }
; __device__ __forceinline__ void phase_scan(const ScanArgs A, LAS unsigned char* lds) {
;     ...
;                 for (int t = 0; t < 16; ++t) {
;                     const LAS float* q = in + t * 64 + kq * 16;
;                     f32x4 Wv[4], KDv[4], Bv[4], ANv[4], Rv[4];
; #pragma unroll
;                     for (int j = 0; j < 4; ++j) { Wv[j] = *(const LAS f32x4*)(q + 4 * j); KDv[j] = *(const LAS f32x4*)(q + 1024 + 4 * j); Bv[j] = *(const LAS f32x4*)(q + 2048 + 4 * j);
;                                                   ANv[j] = *(const LAS f32x4*)(q + 3072 + 4 * j); Rv[j] = *(const LAS f32x4*)(q + 4096 + 4 * j); }
;                     const f32x2 v2 = *(const LAS f32x2*)(in + 5120 + t * 64 + half * 32 + rb * 2);
;     ...
;                     float sa[2], y[2];
; #pragma unroll
;                     for (int i = 0; i < 2; ++i) { f32x2 a0 = {0.f, 0.f}, a1 = {0.f, 0.f};
; #pragma unroll
;                         for (int p = 0; p < 8; p += 2) { a0 += S2[i][p] * PAIR(ANv, p); a1 += S2[i][p + 1] * PAIR(ANv, p + 1); }
;                         a0 += a1; sa[i] = red4(a0[0] + a0[1]); }
;     ...
;                     for (int i = 0; i < 2; ++i) { f32x2 y0 = {0.f, 0.f}, y1 = {0.f, 0.f}; const f32x2 sai = {sa[i], sa[i]}, vi = {v2[i], v2[i]};
; #pragma unroll
;                         for (int p = 0; p < 8; p += 2) {
;                             const f32x2 n0 = S2[i][p] * PAIR(Wv, p) + sai * PAIR(Bv, p) + vi * PAIR(KDv, p);
;                             const f32x2 n1 = S2[i][p + 1] * PAIR(Wv, p + 1) + sai * PAIR(Bv, p + 1) + vi * PAIR(KDv, p + 1);
;                             S2[i][p] = n0; S2[i][p + 1] = n1; y0 += n0 * PAIR(Rv, p); y1 += n1 * PAIR(Rv, p + 1); }
;                         y0 += y1; y[i] = red4(y0[0] + y0[1]); }
;     ...
;                     if (kq == 0) *(LAS f32x2*)(yb + t * 64 + half * 32 + rb * 2) = (f32x2){y[0], y[1]};
	v_pk_fma_f32 v[224:225], v[90:91], v[56:57], v[224:225]
	v_pk_fma_f32 v[226:227], v[98:99], v[58:59], v[226:227]
	v_pk_fma_f32 v[240:241], v[110:111], v[56:57], v[240:241]
	v_pk_fma_f32 v[242:243], v[112:113], v[58:59], v[242:243]
	v_pk_fma_f32 v[90:91], v[180:181], v[188:189], v[224:225] op_sel_hi:[1,0,1]
	v_pk_fma_f32 v[98:99], v[182:183], v[188:189], v[226:227] op_sel_hi:[1,0,1]
	v_pk_fma_f32 v[110:111], v[180:181], v[188:189], v[240:241] op_sel:[0,1,0]
	v_pk_fma_f32 v[112:113], v[182:183], v[188:189], v[242:243] op_sel:[0,1,0]
	ds_read_b128 v[150:153], v171 offset:11808
	ds_read_b128 v[56:59], v171 offset:3616
	ds_read_b128 v[180:183], v171 offset:7712
	v_pk_mul_f32 v[228:229], v[154:155], v[190:191] op_sel_hi:[1,0]
	v_pk_mul_f32 v[230:231], v[156:157], v[190:191] op_sel_hi:[1,0]
	v_pk_mul_f32 v[244:245], v[154:155], v[192:193] op_sel_hi:[1,0]
	v_pk_mul_f32 v[246:247], v[156:157], v[192:193] op_sel_hi:[1,0]
	v_pk_fma_f32 v[228:229], v[94:95], v[60:61], v[228:229]
	v_pk_fma_f32 v[230:231], v[102:103], v[62:63], v[230:231]
	v_pk_fma_f32 v[244:245], v[114:115], v[60:61], v[244:245]
	v_pk_fma_f32 v[246:247], v[116:117], v[62:63], v[246:247]
	v_pk_fma_f32 v[94:95], v[184:185], v[188:189], v[228:229] op_sel_hi:[1,0,1]
	v_pk_fma_f32 v[102:103], v[186:187], v[188:189], v[230:231] op_sel_hi:[1,0,1]
	v_pk_fma_f32 v[114:115], v[184:185], v[188:189], v[244:245] op_sel:[0,1,0]
	v_pk_fma_f32 v[116:117], v[186:187], v[188:189], v[246:247] op_sel:[0,1,0]
	ds_read_b128 v[154:157], v171 offset:11824
	ds_read_b128 v[60:63], v171 offset:3632
	ds_read_b128 v[184:187], v171 offset:7728
	ds_read_b64 v[188:189], v96 offset:3584
	s_waitcnt lgkmcnt(15)
	v_pk_fma_f32 v[248:249], v[200:201], v[84:85], 0 op_sel_hi:[1,1,0]
	v_pk_fma_f32 v[250:251], v[202:203], v[88:89], 0 op_sel_hi:[1,1,0]
	v_pk_fma_f32 v[194:195], v[200:201], v[100:101], 0 op_sel_hi:[1,1,0]
	v_pk_fma_f32 v[158:159], v[202:203], v[104:105], 0 op_sel_hi:[1,1,0]
	v_pk_fma_f32 v[248:249], v[204:205], v[86:87], v[248:249]
	v_pk_fma_f32 v[250:251], v[206:207], v[92:93], v[250:251]
	v_pk_fma_f32 v[194:195], v[204:205], v[106:107], v[194:195]
	v_pk_fma_f32 v[158:159], v[206:207], v[108:109], v[158:159]
	v_pk_fma_f32 v[248:249], v[208:209], v[90:91], v[248:249]
	v_pk_fma_f32 v[250:251], v[210:211], v[98:99], v[250:251]
	v_pk_fma_f32 v[194:195], v[208:209], v[110:111], v[194:195]
	v_pk_fma_f32 v[158:159], v[210:211], v[112:113], v[158:159]
	v_pk_fma_f32 v[248:249], v[212:213], v[94:95], v[248:249]
	v_pk_fma_f32 v[250:251], v[214:215], v[102:103], v[250:251]
	v_pk_fma_f32 v[194:195], v[212:213], v[114:115], v[194:195]
	v_pk_fma_f32 v[158:159], v[214:215], v[116:117], v[158:159]
	ds_read_b128 v[200:203], v171 offset:19968
	ds_read_b128 v[204:207], v171 offset:19984
	ds_read_b128 v[208:211], v171 offset:20000
	ds_read_b128 v[212:215], v171 offset:20016
	v_pk_add_f32 v[248:249], v[250:251], v[248:249]
	v_pk_add_f32 v[194:195], v[158:159], v[194:195]
	v_add_f32_e32 v168, v248, v249
	v_add_f32_e32 v169, v194, v195
	s_nop 0
	v_add_f32_dpp v168, v168, v168 quad_perm:[1,0,3,2] row_mask:0xf bank_mask:0xf bound_ctrl:1
	v_add_f32_dpp v169, v169, v169 quad_perm:[1,0,3,2] row_mask:0xf bank_mask:0xf bound_ctrl:1
	s_nop 0
	v_add_f32_dpp v168, v168, v168 quad_perm:[2,3,0,1] row_mask:0xf bank_mask:0xf bound_ctrl:1
	v_add_f32_dpp v169, v169, v169 quad_perm:[2,3,0,1] row_mask:0xf bank_mask:0xf bound_ctrl:1
	s_and_saveexec_b64 s[34:35], s[8:9]
	ds_write_b64 v75, v[168:169] offset:3328
	s_or_b64 exec, exec, s[34:35]
	s_waitcnt lgkmcnt(15)
	v_pk_fma_f32 v[160:161], v[84:85], v[32:33], 0 op_sel_hi:[1,1,0]
	v_pk_fma_f32 v[162:163], v[88:89], v[34:35], 0 op_sel_hi:[1,1,0]
	v_pk_fma_f32 v[164:165], v[100:101], v[32:33], 0 op_sel_hi:[1,1,0]
	v_pk_fma_f32 v[166:167], v[104:105], v[34:35], 0 op_sel_hi:[1,1,0]
	v_pk_fma_f32 v[160:161], v[86:87], v[36:37], v[160:161]
	v_pk_fma_f32 v[162:163], v[92:93], v[38:39], v[162:163]
	v_pk_fma_f32 v[164:165], v[106:107], v[36:37], v[164:165]
	v_pk_fma_f32 v[166:167], v[108:109], v[38:39], v[166:167]
	v_pk_fma_f32 v[160:161], v[90:91], v[40:41], v[160:161]
	v_pk_fma_f32 v[162:163], v[98:99], v[42:43], v[162:163]
	v_pk_fma_f32 v[164:165], v[110:111], v[40:41], v[164:165]
	v_pk_fma_f32 v[166:167], v[112:113], v[42:43], v[166:167]
	v_pk_fma_f32 v[160:161], v[94:95], v[44:45], v[160:161]
	v_pk_fma_f32 v[162:163], v[102:103], v[46:47], v[162:163]
	v_pk_fma_f32 v[164:165], v[114:115], v[44:45], v[164:165]
	v_pk_fma_f32 v[166:167], v[116:117], v[46:47], v[166:167]
	ds_read_b128 v[32:35], v171 offset:16128
	ds_read_b128 v[36:39], v171 offset:16144
	ds_read_b128 v[40:43], v171 offset:16160
	ds_read_b128 v[44:47], v171 offset:16176
	v_pk_add_f32 v[160:161], v[162:163], v[160:161]
	v_pk_add_f32 v[164:165], v[166:167], v[164:165]
	v_add_f32_e32 v168, v160, v161
	v_add_f32_e32 v169, v164, v165
	s_nop 0
	v_add_f32_dpp v168, v168, v168 quad_perm:[1,0,3,2] row_mask:0xf bank_mask:0xf bound_ctrl:1
	v_add_f32_dpp v169, v169, v169 quad_perm:[1,0,3,2] row_mask:0xf bank_mask:0xf bound_ctrl:1
	s_nop 0
	v_add_f32_dpp v190, v168, v168 quad_perm:[2,3,0,1] row_mask:0xf bank_mask:0xf bound_ctrl:1
	v_add_f32_dpp v192, v169, v169 quad_perm:[2,3,0,1] row_mask:0xf bank_mask:0xf bound_ctrl:1
	s_waitcnt lgkmcnt(9)
; #define LAS __attribute__((address_space(3)))
; __device__ __forceinline__ float red4(float x) { x = DPP_ADD(x, 0xB1); x = DPP_ADD(x, 0x4E); return x; }
; __device__ __forceinline__ void phase_scan(const ScanArgs A, LAS unsigned char* lds) {
;     ...
;                 for (int t = 0; t < 16; ++t) {
;                     const LAS float* q = in + t * 64 + kq * 16;
;                     f32x4 Wv[4], KDv[4], Bv[4], ANv[4], Rv[4];
; #pragma unroll
;                     for (int j = 0; j < 4; ++j) { Wv[j] = *(const LAS f32x4*)(q + 4 * j); KDv[j] = *(const LAS f32x4*)(q + 1024 + 4 * j); Bv[j] = *(const LAS f32x4*)(q + 2048 + 4 * j);
;                                                   ANv[j] = *(const LAS f32x4*)(q + 3072 + 4 * j); Rv[j] = *(const LAS f32x4*)(q + 4096 + 4 * j); }
;                     const f32x2 v2 = *(const LAS f32x2*)(in + 5120 + t * 64 + half * 32 + rb * 2);
;     ...
;                     float sa[2], y[2];
; #pragma unroll
;                     for (int i = 0; i < 2; ++i) { f32x2 a0 = {0.f, 0.f}, a1 = {0.f, 0.f};
; #pragma unroll
;                         for (int p = 0; p < 8; p += 2) { a0 += S2[i][p] * PAIR(ANv, p); a1 += S2[i][p + 1] * PAIR(ANv, p + 1); }
;                         a0 += a1; sa[i] = red4(a0[0] + a0[1]); }
; #pragma unroll
;                     for (int i = 0; i < 2; ++i) { f32x2 y0 = {0.f, 0.f}, y1 = {0.f, 0.f}; const f32x2 sai = {sa[i], sa[i]}, vi = {v2[i], v2[i]};
; #pragma unroll
;                         for (int p = 0; p < 8; p += 2) {
;                             const f32x2 n0 = S2[i][p] * PAIR(Wv, p) + sai * PAIR(Bv, p) + vi * PAIR(KDv, p);
;                             const f32x2 n1 = S2[i][p + 1] * PAIR(Wv, p + 1) + sai * PAIR(Bv, p + 1) + vi * PAIR(KDv, p + 1);
;                             S2[i][p] = n0; S2[i][p + 1] = n1; y0 += n0 * PAIR(Rv, p); y1 += n1 * PAIR(Rv, p + 1); }
;                         y0 += y1; y[i] = red4(y0[0] + y0[1]); }
;     ...
;                     if (kq == 0) *(LAS f32x2*)(yb + t * 64 + half * 32 + rb * 2) = (f32x2){y[0], y[1]};
	v_pk_mul_f32 v[216:217], v[142:143], v[190:191] op_sel_hi:[1,0]
	v_pk_mul_f32 v[218:219], v[144:145], v[190:191] op_sel_hi:[1,0]
	v_pk_mul_f32 v[232:233], v[142:143], v[192:193] op_sel_hi:[1,0]
	v_pk_mul_f32 v[234:235], v[144:145], v[192:193] op_sel_hi:[1,0]
	v_pk_fma_f32 v[216:217], v[84:85], v[48:49], v[216:217]
	v_pk_fma_f32 v[218:219], v[88:89], v[50:51], v[218:219]
	v_pk_fma_f32 v[232:233], v[100:101], v[48:49], v[232:233]
	v_pk_fma_f32 v[234:235], v[104:105], v[50:51], v[234:235]
	v_pk_fma_f32 v[84:85], v[172:173], v[188:189], v[216:217] op_sel_hi:[1,0,1]
	v_pk_fma_f32 v[88:89], v[174:175], v[188:189], v[218:219] op_sel_hi:[1,0,1]
	v_pk_fma_f32 v[100:101], v[172:173], v[188:189], v[232:233] op_sel:[0,1,0]
	v_pk_fma_f32 v[104:105], v[174:175], v[188:189], v[234:235] op_sel:[0,1,0]
	ds_read_b128 v[142:145], v171 offset:12032
	ds_read_b128 v[48:51], v171 offset:3840
	ds_read_b128 v[172:175], v171 offset:7936
	v_pk_mul_f32 v[220:221], v[146:147], v[190:191] op_sel_hi:[1,0]
	v_pk_mul_f32 v[222:223], v[148:149], v[190:191] op_sel_hi:[1,0]
	v_pk_mul_f32 v[236:237], v[146:147], v[192:193] op_sel_hi:[1,0]
	v_pk_mul_f32 v[238:239], v[148:149], v[192:193] op_sel_hi:[1,0]
	v_pk_fma_f32 v[220:221], v[86:87], v[52:53], v[220:221]
	v_pk_fma_f32 v[222:223], v[92:93], v[54:55], v[222:223]
	v_pk_fma_f32 v[236:237], v[106:107], v[52:53], v[236:237]
	v_pk_fma_f32 v[238:239], v[108:109], v[54:55], v[238:239]
	v_pk_fma_f32 v[86:87], v[176:177], v[188:189], v[220:221] op_sel_hi:[1,0,1]
	v_pk_fma_f32 v[92:93], v[178:179], v[188:189], v[222:223] op_sel_hi:[1,0,1]
	v_pk_fma_f32 v[106:107], v[176:177], v[188:189], v[236:237] op_sel:[0,1,0]
	v_pk_fma_f32 v[108:109], v[178:179], v[188:189], v[238:239] op_sel:[0,1,0]
	ds_read_b128 v[146:149], v171 offset:12048
	ds_read_b128 v[52:55], v171 offset:3856
	ds_read_b128 v[176:179], v171 offset:7952
	v_pk_mul_f32 v[224:225], v[150:151], v[190:191] op_sel_hi:[1,0]
	v_pk_mul_f32 v[226:227], v[152:153], v[190:191] op_sel_hi:[1,0]
	v_pk_mul_f32 v[240:241], v[150:151], v[192:193] op_sel_hi:[1,0]
	v_pk_mul_f32 v[242:243], v[152:153], v[192:193] op_sel_hi:[1,0]
	v_pk_fma_f32 v[224:225], v[90:91], v[56:57], v[224:225]
	v_pk_fma_f32 v[226:227], v[98:99], v[58:59], v[226:227]
	v_pk_fma_f32 v[240:241], v[110:111], v[56:57], v[240:241]
	v_pk_fma_f32 v[242:243], v[112:113], v[58:59], v[242:243]
	v_pk_fma_f32 v[90:91], v[180:181], v[188:189], v[224:225] op_sel_hi:[1,0,1]
	v_pk_fma_f32 v[98:99], v[182:183], v[188:189], v[226:227] op_sel_hi:[1,0,1]
	v_pk_fma_f32 v[110:111], v[180:181], v[188:189], v[240:241] op_sel:[0,1,0]
	v_pk_fma_f32 v[112:113], v[182:183], v[188:189], v[242:243] op_sel:[0,1,0]
	ds_read_b128 v[150:153], v171 offset:12064
	ds_read_b128 v[56:59], v171 offset:3872
	ds_read_b128 v[180:183], v171 offset:7968
	v_pk_mul_f32 v[228:229], v[154:155], v[190:191] op_sel_hi:[1,0]
	v_pk_mul_f32 v[230:231], v[156:157], v[190:191] op_sel_hi:[1,0]
	v_pk_mul_f32 v[244:245], v[154:155], v[192:193] op_sel_hi:[1,0]
	v_pk_mul_f32 v[246:247], v[156:157], v[192:193] op_sel_hi:[1,0]
	v_pk_fma_f32 v[228:229], v[94:95], v[60:61], v[228:229]
	v_pk_fma_f32 v[230:231], v[102:103], v[62:63], v[230:231]
	v_pk_fma_f32 v[244:245], v[114:115], v[60:61], v[244:245]
	v_pk_fma_f32 v[246:247], v[116:117], v[62:63], v[246:247]
	v_pk_fma_f32 v[94:95], v[184:185], v[188:189], v[228:229] op_sel_hi:[1,0,1]
	v_pk_fma_f32 v[102:103], v[186:187], v[188:189], v[230:231] op_sel_hi:[1,0,1]
	v_pk_fma_f32 v[114:115], v[184:185], v[188:189], v[244:245] op_sel:[0,1,0]
	v_pk_fma_f32 v[116:117], v[186:187], v[188:189], v[246:247] op_sel:[0,1,0]
	ds_read_b128 v[154:157], v171 offset:12080
	ds_read_b128 v[60:63], v171 offset:3888
	ds_read_b128 v[184:187], v171 offset:7984
	ds_read_b64 v[188:189], v96 offset:3840
	s_waitcnt lgkmcnt(15)
	v_pk_fma_f32 v[248:249], v[200:201], v[84:85], 0 op_sel_hi:[1,1,0]
	v_pk_fma_f32 v[250:251], v[202:203], v[88:89], 0 op_sel_hi:[1,1,0]
	v_pk_fma_f32 v[194:195], v[200:201], v[100:101], 0 op_sel_hi:[1,1,0]
	v_pk_fma_f32 v[158:159], v[202:203], v[104:105], 0 op_sel_hi:[1,1,0]
	v_pk_fma_f32 v[248:249], v[204:205], v[86:87], v[248:249]
	v_pk_fma_f32 v[250:251], v[206:207], v[92:93], v[250:251]
	v_pk_fma_f32 v[194:195], v[204:205], v[106:107], v[194:195]
	v_pk_fma_f32 v[158:159], v[206:207], v[108:109], v[158:159]
	v_pk_fma_f32 v[248:249], v[208:209], v[90:91], v[248:249]
	v_pk_fma_f32 v[250:251], v[210:211], v[98:99], v[250:251]
	v_pk_fma_f32 v[194:195], v[208:209], v[110:111], v[194:195]
	v_pk_fma_f32 v[158:159], v[210:211], v[112:113], v[158:159]
	v_pk_fma_f32 v[248:249], v[212:213], v[94:95], v[248:249]
	v_pk_fma_f32 v[250:251], v[214:215], v[102:103], v[250:251]
	v_pk_fma_f32 v[194:195], v[212:213], v[114:115], v[194:195]
	v_pk_fma_f32 v[158:159], v[214:215], v[116:117], v[158:159]
	ds_read_b128 v[200:203], v171 offset:20224
	ds_read_b128 v[204:207], v171 offset:20240
	ds_read_b128 v[208:211], v171 offset:20256
	ds_read_b128 v[212:215], v171 offset:20272
	v_pk_add_f32 v[248:249], v[250:251], v[248:249]
	v_pk_add_f32 v[194:195], v[158:159], v[194:195]
	v_add_f32_e32 v168, v248, v249
	v_add_f32_e32 v169, v194, v195
	s_nop 0
	v_add_f32_dpp v168, v168, v168 quad_perm:[1,0,3,2] row_mask:0xf bank_mask:0xf bound_ctrl:1
	v_add_f32_dpp v169, v169, v169 quad_perm:[1,0,3,2] row_mask:0xf bank_mask:0xf bound_ctrl:1
	s_nop 0
	v_add_f32_dpp v168, v168, v168 quad_perm:[2,3,0,1] row_mask:0xf bank_mask:0xf bound_ctrl:1
	v_add_f32_dpp v169, v169, v169 quad_perm:[2,3,0,1] row_mask:0xf bank_mask:0xf bound_ctrl:1
	s_and_saveexec_b64 s[34:35], s[8:9]
	ds_write_b64 v75, v[168:169] offset:3584
	s_or_b64 exec, exec, s[34:35]
	s_waitcnt lgkmcnt(15)
; #define LAS __attribute__((address_space(3)))
; __device__ __forceinline__ float red4(float x) { x = DPP_ADD(x, 0xB1); x = DPP_ADD(x, 0x4E); return x; }
; __device__ __forceinline__ void phase_scan(const ScanArgs A, LAS unsigned char* lds) {
;     ...
;                 for (int t = 0; t < 16; ++t) {
;                     const LAS float* q = in + t * 64 + kq * 16;
;                     f32x4 Wv[4], KDv[4], Bv[4], ANv[4], Rv[4];
; #pragma unroll
;                     for (int j = 0; j < 4; ++j) { Wv[j] = *(const LAS f32x4*)(q + 4 * j); KDv[j] = *(const LAS f32x4*)(q + 1024 + 4 * j); Bv[j] = *(const LAS f32x4*)(q + 2048 + 4 * j);
;                                                   ANv[j] = *(const LAS f32x4*)(q + 3072 + 4 * j); Rv[j] = *(const LAS f32x4*)(q + 4096 + 4 * j); }
;                     const f32x2 v2 = *(const LAS f32x2*)(in + 5120 + t * 64 + half * 32 + rb * 2);
;     ...
;                     float sa[2], y[2];
; #pragma unroll
;                     for (int i = 0; i < 2; ++i) { f32x2 a0 = {0.f, 0.f}, a1 = {0.f, 0.f};
; #pragma unroll
;                         for (int p = 0; p < 8; p += 2) { a0 += S2[i][p] * PAIR(ANv, p); a1 += S2[i][p + 1] * PAIR(ANv, p + 1); }
;                         a0 += a1; sa[i] = red4(a0[0] + a0[1]); }
; #pragma unroll
;                     for (int i = 0; i < 2; ++i) { f32x2 y0 = {0.f, 0.f}, y1 = {0.f, 0.f}; const f32x2 sai = {sa[i], sa[i]}, vi = {v2[i], v2[i]};
; #pragma unroll
;                         for (int p = 0; p < 8; p += 2) {
;                             const f32x2 n0 = S2[i][p] * PAIR(Wv, p) + sai * PAIR(Bv, p) + vi * PAIR(KDv, p);
;                             const f32x2 n1 = S2[i][p + 1] * PAIR(Wv, p + 1) + sai * PAIR(Bv, p + 1) + vi * PAIR(KDv, p + 1);
;                             S2[i][p] = n0; S2[i][p + 1] = n1; y0 += n0 * PAIR(Rv, p); y1 += n1 * PAIR(Rv, p + 1); }
;                         y0 += y1; y[i] = red4(y0[0] + y0[1]); }
;     ...
;                     if (kq == 0) *(LAS f32x2*)(yb + t * 64 + half * 32 + rb * 2) = (f32x2){y[0], y[1]};
;                 }
	v_pk_fma_f32 v[160:161], v[84:85], v[32:33], 0 op_sel_hi:[1,1,0]
	v_pk_fma_f32 v[162:163], v[88:89], v[34:35], 0 op_sel_hi:[1,1,0]
	v_pk_fma_f32 v[164:165], v[100:101], v[32:33], 0 op_sel_hi:[1,1,0]
	v_pk_fma_f32 v[166:167], v[104:105], v[34:35], 0 op_sel_hi:[1,1,0]
	v_pk_fma_f32 v[160:161], v[86:87], v[36:37], v[160:161]
	v_pk_fma_f32 v[162:163], v[92:93], v[38:39], v[162:163]
	v_pk_fma_f32 v[164:165], v[106:107], v[36:37], v[164:165]
	v_pk_fma_f32 v[166:167], v[108:109], v[38:39], v[166:167]
	v_pk_fma_f32 v[160:161], v[90:91], v[40:41], v[160:161]
	v_pk_fma_f32 v[162:163], v[98:99], v[42:43], v[162:163]
	v_pk_fma_f32 v[164:165], v[110:111], v[40:41], v[164:165]
	v_pk_fma_f32 v[166:167], v[112:113], v[42:43], v[166:167]
	v_pk_fma_f32 v[160:161], v[94:95], v[44:45], v[160:161]
	v_pk_fma_f32 v[162:163], v[102:103], v[46:47], v[162:163]
	v_pk_fma_f32 v[164:165], v[114:115], v[44:45], v[164:165]
	v_pk_fma_f32 v[166:167], v[116:117], v[46:47], v[166:167]
	v_pk_add_f32 v[160:161], v[162:163], v[160:161]
	v_pk_add_f32 v[164:165], v[166:167], v[164:165]
	v_add_f32_e32 v168, v160, v161
	v_add_f32_e32 v169, v164, v165
	s_nop 0
	v_add_f32_dpp v168, v168, v168 quad_perm:[1,0,3,2] row_mask:0xf bank_mask:0xf bound_ctrl:1
	v_add_f32_dpp v169, v169, v169 quad_perm:[1,0,3,2] row_mask:0xf bank_mask:0xf bound_ctrl:1
	s_nop 0
	v_add_f32_dpp v190, v168, v168 quad_perm:[2,3,0,1] row_mask:0xf bank_mask:0xf bound_ctrl:1
	v_add_f32_dpp v192, v169, v169 quad_perm:[2,3,0,1] row_mask:0xf bank_mask:0xf bound_ctrl:1
	s_waitcnt lgkmcnt(5)
	v_pk_mul_f32 v[216:217], v[142:143], v[190:191] op_sel_hi:[1,0]
	v_pk_mul_f32 v[218:219], v[144:145], v[190:191] op_sel_hi:[1,0]
	v_pk_mul_f32 v[232:233], v[142:143], v[192:193] op_sel_hi:[1,0]
	v_pk_mul_f32 v[234:235], v[144:145], v[192:193] op_sel_hi:[1,0]
	v_pk_fma_f32 v[216:217], v[84:85], v[48:49], v[216:217]
	v_pk_fma_f32 v[218:219], v[88:89], v[50:51], v[218:219]
	v_pk_fma_f32 v[232:233], v[100:101], v[48:49], v[232:233]
	v_pk_fma_f32 v[234:235], v[104:105], v[50:51], v[234:235]
	v_pk_fma_f32 v[84:85], v[172:173], v[188:189], v[216:217] op_sel_hi:[1,0,1]
	v_pk_fma_f32 v[88:89], v[174:175], v[188:189], v[218:219] op_sel_hi:[1,0,1]
	v_pk_fma_f32 v[100:101], v[172:173], v[188:189], v[232:233] op_sel:[0,1,0]
	v_pk_fma_f32 v[104:105], v[174:175], v[188:189], v[234:235] op_sel:[0,1,0]
	v_pk_mul_f32 v[220:221], v[146:147], v[190:191] op_sel_hi:[1,0]
	v_pk_mul_f32 v[222:223], v[148:149], v[190:191] op_sel_hi:[1,0]
	v_pk_mul_f32 v[236:237], v[146:147], v[192:193] op_sel_hi:[1,0]
	v_pk_mul_f32 v[238:239], v[148:149], v[192:193] op_sel_hi:[1,0]
	v_pk_fma_f32 v[220:221], v[86:87], v[52:53], v[220:221]
	v_pk_fma_f32 v[222:223], v[92:93], v[54:55], v[222:223]
	v_pk_fma_f32 v[236:237], v[106:107], v[52:53], v[236:237]
	v_pk_fma_f32 v[238:239], v[108:109], v[54:55], v[238:239]
	v_pk_fma_f32 v[86:87], v[176:177], v[188:189], v[220:221] op_sel_hi:[1,0,1]
	v_pk_fma_f32 v[92:93], v[178:179], v[188:189], v[222:223] op_sel_hi:[1,0,1]
	v_pk_fma_f32 v[106:107], v[176:177], v[188:189], v[236:237] op_sel:[0,1,0]
	v_pk_fma_f32 v[108:109], v[178:179], v[188:189], v[238:239] op_sel:[0,1,0]
	v_pk_mul_f32 v[224:225], v[150:151], v[190:191] op_sel_hi:[1,0]
	v_pk_mul_f32 v[226:227], v[152:153], v[190:191] op_sel_hi:[1,0]
	v_pk_mul_f32 v[240:241], v[150:151], v[192:193] op_sel_hi:[1,0]
	v_pk_mul_f32 v[242:243], v[152:153], v[192:193] op_sel_hi:[1,0]
	v_pk_fma_f32 v[224:225], v[90:91], v[56:57], v[224:225]
	v_pk_fma_f32 v[226:227], v[98:99], v[58:59], v[226:227]
	v_pk_fma_f32 v[240:241], v[110:111], v[56:57], v[240:241]
	v_pk_fma_f32 v[242:243], v[112:113], v[58:59], v[242:243]
	v_pk_fma_f32 v[90:91], v[180:181], v[188:189], v[224:225] op_sel_hi:[1,0,1]
	v_pk_fma_f32 v[98:99], v[182:183], v[188:189], v[226:227] op_sel_hi:[1,0,1]
	v_pk_fma_f32 v[110:111], v[180:181], v[188:189], v[240:241] op_sel:[0,1,0]
	v_pk_fma_f32 v[112:113], v[182:183], v[188:189], v[242:243] op_sel:[0,1,0]
	v_pk_mul_f32 v[228:229], v[154:155], v[190:191] op_sel_hi:[1,0]
	v_pk_mul_f32 v[230:231], v[156:157], v[190:191] op_sel_hi:[1,0]
	v_pk_mul_f32 v[244:245], v[154:155], v[192:193] op_sel_hi:[1,0]
	v_pk_mul_f32 v[246:247], v[156:157], v[192:193] op_sel_hi:[1,0]
	v_pk_fma_f32 v[228:229], v[94:95], v[60:61], v[228:229]
	v_pk_fma_f32 v[230:231], v[102:103], v[62:63], v[230:231]
	v_pk_fma_f32 v[244:245], v[114:115], v[60:61], v[244:245]
	v_pk_fma_f32 v[246:247], v[116:117], v[62:63], v[246:247]
	v_pk_fma_f32 v[94:95], v[184:185], v[188:189], v[228:229] op_sel_hi:[1,0,1]
	v_pk_fma_f32 v[102:103], v[186:187], v[188:189], v[230:231] op_sel_hi:[1,0,1]
	v_pk_fma_f32 v[114:115], v[184:185], v[188:189], v[244:245] op_sel:[0,1,0]
	v_pk_fma_f32 v[116:117], v[186:187], v[188:189], v[246:247] op_sel:[0,1,0]
	s_waitcnt lgkmcnt(1)
	v_pk_fma_f32 v[248:249], v[200:201], v[84:85], 0 op_sel_hi:[1,1,0]
	v_pk_fma_f32 v[250:251], v[202:203], v[88:89], 0 op_sel_hi:[1,1,0]
	v_pk_fma_f32 v[194:195], v[200:201], v[100:101], 0 op_sel_hi:[1,1,0]
	v_pk_fma_f32 v[158:159], v[202:203], v[104:105], 0 op_sel_hi:[1,1,0]
	v_pk_fma_f32 v[248:249], v[204:205], v[86:87], v[248:249]
	v_pk_fma_f32 v[250:251], v[206:207], v[92:93], v[250:251]
	v_pk_fma_f32 v[194:195], v[204:205], v[106:107], v[194:195]
	v_pk_fma_f32 v[158:159], v[206:207], v[108:109], v[158:159]
	v_pk_fma_f32 v[248:249], v[208:209], v[90:91], v[248:249]
	v_pk_fma_f32 v[250:251], v[210:211], v[98:99], v[250:251]
	v_pk_fma_f32 v[194:195], v[208:209], v[110:111], v[194:195]
	v_pk_fma_f32 v[158:159], v[210:211], v[112:113], v[158:159]
	v_pk_fma_f32 v[248:249], v[212:213], v[94:95], v[248:249]
	v_pk_fma_f32 v[250:251], v[214:215], v[102:103], v[250:251]
	v_pk_fma_f32 v[194:195], v[212:213], v[114:115], v[194:195]
	v_pk_fma_f32 v[158:159], v[214:215], v[116:117], v[158:159]
	v_pk_add_f32 v[248:249], v[250:251], v[248:249]
	v_pk_add_f32 v[194:195], v[158:159], v[194:195]
	v_add_f32_e32 v168, v248, v249
	v_add_f32_e32 v169, v194, v195
	s_nop 0
	v_add_f32_dpp v168, v168, v168 quad_perm:[1,0,3,2] row_mask:0xf bank_mask:0xf bound_ctrl:1
	v_add_f32_dpp v169, v169, v169 quad_perm:[1,0,3,2] row_mask:0xf bank_mask:0xf bound_ctrl:1
	s_nop 0
	v_add_f32_dpp v168, v168, v168 quad_perm:[2,3,0,1] row_mask:0xf bank_mask:0xf bound_ctrl:1
	v_add_f32_dpp v169, v169, v169 quad_perm:[2,3,0,1] row_mask:0xf bank_mask:0xf bound_ctrl:1
	s_and_saveexec_b64 s[34:35], s[8:9]
	ds_write_b64 v75, v[168:169] offset:3840
	s_or_b64 exec, exec, s[34:35]
	s_branch .LBB0_162
